# v23 + GEMM unit transition: accumulators cleared with 64 v_mov_b64 instead of 127 v_mov_b32 (all GEMM copies)
# baseline (speedup 1.0000x reference)
; template <class Epi, bool DYN = false>
; __device__ __forceinline__ void gemm_phase(LAS unsigned char* lds, const Gemm g, const Epi& E, int wave, unsigned* ctr = nullptr) {
;     ...
;     Unit cur, nxt; int ui = 0;
;     LAS int* slot = (LAS int*)(lds + 131072 + 64);
;     const int xcd = (int)(hw_xcc_id() & 7u); int ticket = 0;
;     auto rng_cnt = [&](int x) { const int q = S.nwg / NXCD, r = S.nwg % NXCD; return q + (x < r ? 1 : 0); };
;     auto rng_start = [&](int x) { const int q = S.nwg / NXCD, r = S.nwg % NXCD; return x < r ? x * (q + 1) : r * (q + 1) + (x - r) * q; };
;     auto decode = [&](int wgid, Unit& u) { const int nig = WGM * S.nN, gid = wgid / nig, fm = gid * WGM, gsz = (S.nM - fm) < WGM ? (S.nM - fm) : WGM; u.pm = fm + ((wgid % nig) % gsz); u.pn = (wgid % nig) / gsz; u.b = 0; };
;     auto issue = [&]() { if (tid == 0) ticket = (int)__hip_atomic_fetch_add(ctr + xcd * 16, 1u, __ATOMIC_RELAXED, __HIP_MEMORY_SCOPE_AGENT); };
;     auto publish = [&](int si) { if (tid == 0) { int wg = -1;
;             if (ticket < rng_cnt(xcd)) wg = rng_start(xcd) + ticket;
;             else { for (int k = 1; k < 8; ++k) { const int x2 = (xcd + k) & 7; const int t2 = (int)__hip_atomic_fetch_add(ctr + x2 * 16, 1u, __ATOMIC_RELAXED, __HIP_MEMORY_SCOPE_AGENT); if (t2 < rng_cnt(x2)) { wg = rng_start(x2) + t2; break; } } }
;             slot[si] = wg; } };
;     if (DYN) { issue(); publish(0); __syncthreads(); const int w0 = __builtin_amdgcn_readfirstlane(slot[0]); if (w0 < 0) return; decode(w0, cur); issue(); }
;     else if (!S.next(0, cur)) return;
;     f32x4 acc[2][2][4][2];
; #pragma unroll
;     for (int a = 0; a < 2; ++a)
; #pragma unroll
;         for (int b = 0; b < 2; ++b)
; #pragma unroll
;             for (int m = 0; m < 4; ++m)
; #pragma unroll
;                 for (int n = 0; n < 2; ++n) acc[a][b][m][n] = (f32x4){0.f, 0.f, 0.f, 0.f};
;     bf16x8 At[4][2], B0[2][2], B1[2][2];
;     const char* cA = (const char*)(g.A + (size_t)cur.b * g.sA) + (size_t)cur.pm * tstepA; const char* cB = (const char*)(g.Bt + (size_t)cur.b * g.sB) + (size_t)cur.pn * tstepB;
;     float pre[8];
;     E.prefetch(pre, cur, wr, fr);
;     PG8_STAGE(PG8_SB(0, 0), cB, voffB); PG8_STAGE(PG8_SA(0, 0), cA, voffA); PG8_STAGE(PG8_SB(0, 1), cB + hstepB, voffB); PG8_STAGE(PG8_SA(0, 1), cA + hstepA, voffA);
;     if (wr == 1) PG8_BAR;
;     PG8_WAIT_V(4); PG8_BAR;
.LBB0_70:
	v_lshrrev_b32_e32 v13, 1, v192
	v_and_b32_e32 v14, 24, v13
	v_and_b32_e32 v12, 15, v192
	v_lshlrev_b32_e32 v13, 1, v14
	s_lshl_b32 s0, s0, 5
	v_lshl_or_b32 v194, s1, 6, v12
	v_lshl_or_b32 v12, v12, 6, v13
	v_lshlrev_b32_e32 v13, 2, v192
	s_and_b32 s6, s0, 0x60
	s_lshl_b32 s1, s1, 13
	v_and_b32_e32 v13, 32, v13
	s_lshl_b32 s0, s6, 7
	v_bitop3_b32 v200, v12, s0, v13 bitop3:0xde
	s_add_u32 s0, s46, 0x8000
	v_mov_b32_e32 v179, v1
	v_bitop3_b32 v15, v12, s1, v13 bitop3:0xde
	s_addc_u32 s1, s47, 0
	v_mov_b32_e32 v183, v1
	s_add_i32 m0, s18, 0x18000
	v_lshl_add_u64 v[12:13], s[0:1], 0, v[178:179]
	s_waitcnt vmcnt(4)
	s_barrier
	global_load_lds_dwordx4 v[12:13], off
	v_lshl_add_u64 v[12:13], s[0:1], 0, v[182:183]
	s_add_i32 m0, s18, 0x1a000
	s_add_i32 s41, s18, 0x8000
	s_add_i32 s43, s18, 0xa000
	global_load_lds_dwordx4 v[12:13], off
	v_lshl_add_u64 v[4:5], v[4:5], 0, s[52:53]
	s_mov_b32 m0, s41
	s_add_u32 s0, s46, 0xc000
	global_load_lds_dwordx4 v[4:5], off
	v_lshl_add_u64 v[2:3], v[2:3], 0, s[52:53]
	s_mov_b32 m0, s43
	s_addc_u32 s1, s47, 0
	s_add_i32 s90, s18, 0x1c000
	global_load_lds_dwordx4 v[2:3], off
	v_lshl_add_u64 v[2:3], s[0:1], 0, v[178:179]
	s_mov_b32 m0, s90
	s_add_i32 s95, s18, 0x1e000
	global_load_lds_dwordx4 v[2:3], off
	v_lshl_add_u64 v[2:3], s[0:1], 0, v[182:183]
	s_mov_b32 m0, s95
	s_add_i32 s0, s5, 1
	global_load_lds_dwordx4 v[2:3], off
	s_and_b32 s2, s0, 7
	s_lshl_b32 s0, s2, 6
	v_readlane_b32 s10, v254, 47
	s_add_u32 s7, s10, s0
	v_readlane_b32 s36, v254, 48
	s_addc_u32 s8, s36, 0
	s_lshl_b64 s[0:1], s[44:45], 2
	s_add_u32 s44, s7, s0
	s_addc_u32 s45, s8, s1
	s_add_i32 s7, s5, 2
	s_and_b32 s66, s7, 7
	s_lshl_b32 s7, s66, 6
	s_add_u32 s7, s10, s7
	s_addc_u32 s8, s36, 0
	s_add_u32 s58, s7, s0
	s_addc_u32 s59, s8, s1
	s_add_i32 s7, s5, 3
	s_and_b32 s67, s7, 7
	s_lshl_b32 s7, s67, 6
	s_add_u32 s7, s10, s7
	s_addc_u32 s8, s36, 0
	s_add_u32 s60, s7, s0
	s_addc_u32 s61, s8, s1
	s_xor_b32 s22, s4, 4
	s_lshl_b32 s7, s22, 6
	s_add_u32 s7, s10, s7
	s_addc_u32 s8, s36, 0
	s_add_u32 s62, s7, s0
	s_addc_u32 s63, s8, s1
	s_add_i32 s7, s5, 5
	s_and_b32 s7, s7, 7
	s_lshl_b32 s8, s7, 6
	s_add_u32 s8, s10, s8
	s_addc_u32 s9, s36, 0
	s_add_u32 s92, s8, s0
	s_mulk_i32 s7, 0x60
	s_addc_u32 s93, s9, s1
	v_writelane_b32 v255, s7, 2
	s_add_i32 s7, s5, 6
	s_and_b32 s7, s7, 7
	s_lshl_b32 s8, s7, 6
	s_add_u32 s8, s10, s8
	s_addc_u32 s9, s36, 0
	s_add_u32 s8, s8, s0
	s_addc_u32 s9, s9, s1
	v_writelane_b32 v255, s8, 4
	s_add_i32 s5, s5, -1
	s_mulk_i32 s7, 0x60
	v_writelane_b32 v255, s9, 5
	s_and_b32 s5, s5, 7
	v_writelane_b32 v255, s7, 6
	s_lshl_b32 s7, s5, 6
	s_add_u32 s7, s10, s7
	s_addc_u32 s8, s36, 0
	s_add_u32 s38, s7, s0
	s_addc_u32 s39, s8, s1
	v_writelane_b32 v255, s38, 8
	s_mul_i32 s23, s4, 0x60
	s_lshl_b32 s4, s4, 6
	v_writelane_b32 v255, s39, 9
	s_mulk_i32 s5, 0x60
	s_add_u32 s4, s10, s4
	v_writelane_b32 v255, s5, 10
	s_addc_u32 s5, s36, 0
	v_lshlrev_b32_e32 v2, 15, v9
	s_add_u32 s0, s4, s0
	v_and_b32_e32 v2, 0xffff0000, v2
	s_addc_u32 s1, s5, s1
	v_lshl_add_u32 v2, v10, 12, v2
	v_and_b32_e32 v3, 1, v9
	v_writelane_b32 v255, s0, 12
	v_lshl_or_b32 v2, v3, 6, v2
	v_lshl_add_u32 v2, v11, 1, v2
	v_writelane_b32 v255, s1, 13
	v_mov_b32_e32 v3, v1
	s_mov_b64 s[0:1], 0x80080
	v_lshl_add_u64 v[184:185], v[2:3], 0, s[0:1]
	v_lshlrev_b32_e32 v2, 15, v6
	v_and_b32_e32 v2, 0xffff0000, v2
	v_lshl_add_u32 v2, v7, 12, v2
	v_and_b32_e32 v3, 1, v6
	s_waitcnt vmcnt(6)
	v_lshl_or_b32 v2, v3, 6, v2
	v_lshl_add_u32 v2, v8, 1, v2
	v_mov_b32_e32 v3, v1
	v_mov_b32_e32 v30, 0
	s_mulk_i32 s2, 0x60
	s_mulk_i32 s66, 0x60
	s_mulk_i32 s67, 0x60
	s_mulk_i32 s22, 0x60
	v_or_b32_e32 v201, s6, v14
	v_lshl_add_u64 v[186:187], v[2:3], 0, s[0:1]
	s_mov_b32 s4, 0
	v_add_u32_e32 v202, 0, v15
	v_mov_b32_e32 v31, v30
	v_mov_b64_e32 v[32:33], 0
	v_mov_b64_e32 v[50:51], 0
	v_mov_b64_e32 v[52:53], 0
	v_mov_b64_e32 v[58:59], 0
	v_mov_b64_e32 v[60:61], 0
	v_mov_b64_e32 v[66:67], 0
	v_mov_b64_e32 v[68:69], 0
	v_mov_b64_e32 v[74:75], 0
	v_mov_b64_e32 v[76:77], 0
	v_mov_b64_e32 v[82:83], 0
	v_mov_b64_e32 v[84:85], 0
	v_mov_b64_e32 v[90:91], 0
	v_mov_b64_e32 v[92:93], 0
	v_mov_b64_e32 v[98:99], 0
	v_mov_b64_e32 v[100:101], 0
	v_mov_b64_e32 v[2:3], 0
	v_mov_b64_e32 v[4:5], 0
	v_mov_b64_e32 v[6:7], 0
	v_mov_b64_e32 v[8:9], 0
	v_mov_b64_e32 v[10:11], 0
	v_mov_b64_e32 v[12:13], 0
	v_mov_b64_e32 v[14:15], 0
	v_mov_b64_e32 v[16:17], 0
	v_mov_b64_e32 v[18:19], 0
	v_mov_b64_e32 v[20:21], 0
	v_mov_b64_e32 v[22:23], 0
	v_mov_b64_e32 v[24:25], 0
	v_mov_b64_e32 v[26:27], 0
	v_mov_b64_e32 v[28:29], 0
	v_mov_b64_e32 v[34:35], 0
	v_mov_b64_e32 v[36:37], 0
	v_mov_b64_e32 v[38:39], 0
	v_mov_b64_e32 v[40:41], 0
	v_mov_b64_e32 v[42:43], 0
	v_mov_b64_e32 v[44:45], 0
	v_mov_b64_e32 v[46:47], 0
	v_mov_b64_e32 v[48:49], 0
	v_mov_b64_e32 v[54:55], 0
	v_mov_b64_e32 v[56:57], 0
	v_mov_b64_e32 v[62:63], 0
	v_mov_b64_e32 v[64:65], 0
	v_mov_b64_e32 v[70:71], 0
	v_mov_b64_e32 v[72:73], 0
	v_mov_b64_e32 v[78:79], 0
	v_mov_b64_e32 v[80:81], 0
	v_mov_b64_e32 v[86:87], 0
	v_mov_b64_e32 v[88:89], 0
	v_mov_b64_e32 v[94:95], 0
	v_mov_b64_e32 v[96:97], 0
	v_mov_b64_e32 v[102:103], 0
	v_mov_b64_e32 v[104:105], 0
	v_mov_b64_e32 v[106:107], 0
	v_mov_b64_e32 v[108:109], 0
	v_mov_b64_e32 v[110:111], 0
	v_mov_b64_e32 v[112:113], 0
	v_mov_b64_e32 v[114:115], 0
	v_mov_b64_e32 v[116:117], 0
	v_mov_b64_e32 v[118:119], 0
	v_mov_b64_e32 v[120:121], 0
	v_mov_b64_e32 v[122:123], 0
	v_mov_b64_e32 v[124:125], 0
	v_mov_b64_e32 v[126:127], 0
	v_mov_b64_e32 v[128:129], 0
	s_barrier
	s_branch .LBB0_73
; template <class Epi, bool DYN = false>
; __device__ __forceinline__ void gemm_phase(LAS unsigned char* lds, const Gemm g, const Epi& E, int wave, unsigned* ctr = nullptr) {
;     ...
;         if (!has_next) break;
; #pragma unroll
;         for (int a = 0; a < 2; ++a)
; #pragma unroll
;             for (int b = 0; b < 2; ++b)
; #pragma unroll
;                 for (int m = 0; m < 4; ++m)
; #pragma unroll
;                     for (int n = 0; n < 2; ++n) acc[a][b][m][n] = (f32x4){0.f, 0.f, 0.f, 0.f};
;         cur = nxt; cA = nA; cB = nB; ++ui;
;         if (DYN) issue();
;         E.prefetch(pre, cur, wr, fr);
.LBB0_71:
	s_or_b64 exec, exec, s[0:1]
	v_mov_b32_e32 v30, 0
	s_add_i32 s4, s4, 1
	s_mov_b32 s42, s48
	s_mov_b32 s40, s76
	v_mov_b32_e32 v31, v30
	v_mov_b64_e32 v[32:33], 0
	v_mov_b64_e32 v[50:51], 0
	v_mov_b64_e32 v[52:53], 0
	v_mov_b64_e32 v[58:59], 0
	v_mov_b64_e32 v[60:61], 0
	v_mov_b64_e32 v[66:67], 0
	v_mov_b64_e32 v[68:69], 0
	v_mov_b64_e32 v[74:75], 0
	v_mov_b64_e32 v[76:77], 0
	v_mov_b64_e32 v[82:83], 0
	v_mov_b64_e32 v[84:85], 0
	v_mov_b64_e32 v[90:91], 0
	v_mov_b64_e32 v[92:93], 0
	v_mov_b64_e32 v[98:99], 0
	v_mov_b64_e32 v[100:101], 0
	v_mov_b64_e32 v[2:3], 0
	v_mov_b64_e32 v[4:5], 0
	v_mov_b64_e32 v[6:7], 0
	v_mov_b64_e32 v[8:9], 0
	v_mov_b64_e32 v[10:11], 0
	v_mov_b64_e32 v[12:13], 0
	v_mov_b64_e32 v[14:15], 0
	v_mov_b64_e32 v[16:17], 0
	v_mov_b64_e32 v[18:19], 0
	v_mov_b64_e32 v[20:21], 0
	v_mov_b64_e32 v[22:23], 0
	v_mov_b64_e32 v[24:25], 0
	v_mov_b64_e32 v[26:27], 0
	v_mov_b64_e32 v[28:29], 0
	v_mov_b64_e32 v[34:35], 0
	v_mov_b64_e32 v[36:37], 0
	v_mov_b64_e32 v[38:39], 0
	v_mov_b64_e32 v[40:41], 0
	v_mov_b64_e32 v[42:43], 0
	v_mov_b64_e32 v[44:45], 0
	v_mov_b64_e32 v[46:47], 0
	v_mov_b64_e32 v[48:49], 0
	v_mov_b64_e32 v[54:55], 0
	v_mov_b64_e32 v[56:57], 0
	v_mov_b64_e32 v[62:63], 0
	v_mov_b64_e32 v[64:65], 0
	v_mov_b64_e32 v[70:71], 0
	v_mov_b64_e32 v[72:73], 0
	v_mov_b64_e32 v[78:79], 0
	v_mov_b64_e32 v[80:81], 0
	v_mov_b64_e32 v[86:87], 0
	v_mov_b64_e32 v[88:89], 0
	v_mov_b64_e32 v[94:95], 0
	v_mov_b64_e32 v[96:97], 0
	v_mov_b64_e32 v[102:103], 0
	v_mov_b64_e32 v[104:105], 0
	v_mov_b64_e32 v[106:107], 0
	v_mov_b64_e32 v[108:109], 0
	v_mov_b64_e32 v[110:111], 0
	v_mov_b64_e32 v[112:113], 0
	v_mov_b64_e32 v[114:115], 0
	v_mov_b64_e32 v[116:117], 0
	v_mov_b64_e32 v[118:119], 0
	v_mov_b64_e32 v[120:121], 0
	v_mov_b64_e32 v[122:123], 0
	v_mov_b64_e32 v[124:125], 0
	v_mov_b64_e32 v[126:127], 0
	v_mov_b64_e32 v[128:129], 0
	s_mov_b64 s[46:47], s[64:65]
	s_mov_b64 s[68:69], s[78:79]

; #define PG8_STAGE(bufoff, gbase, voff) do { _Pragma("unroll") for (int _i = 0; _i < 2; ++_i) \
;         __builtin_amdgcn_global_load_lds((const unsigned*)((const char*)(gbase) + (voff)[_i]), (LAS unsigned*)(lds + (bufoff) + ldsw + _i * 8192), 16, 0, 0); } while (0)
; #define PG8_WAIT_V(n) asm volatile("s_waitcnt vmcnt(" #n ")" ::: "memory")
; #define PG8_BAR __builtin_amdgcn_s_barrier()
; template <class Epi, bool DYN = false>
; __device__ __forceinline__ void gemm_phase(LAS unsigned char* lds, const Gemm g, const Epi& E, int wave, unsigned* ctr = nullptr) {
;     ...
;     f32x4 acc[2][2][4][2];
; #pragma unroll
;     for (int a = 0; a < 2; ++a)
; #pragma unroll
;         for (int b = 0; b < 2; ++b)
; #pragma unroll
;             for (int m = 0; m < 4; ++m)
; #pragma unroll
;                 for (int n = 0; n < 2; ++n) acc[a][b][m][n] = (f32x4){0.f, 0.f, 0.f, 0.f};
;     bf16x8 At[4][2], B0[2][2], B1[2][2];
;     const char* cA = (const char*)(g.A + (size_t)cur.b * g.sA) + (size_t)cur.pm * tstepA; const char* cB = (const char*)(g.Bt + (size_t)cur.b * g.sB) + (size_t)cur.pn * tstepB;
;     float pre[8];
;     E.prefetch(pre, cur, wr, fr);
;     PG8_STAGE(PG8_SB(0, 0), cB, voffB); PG8_STAGE(PG8_SA(0, 0), cA, voffA); PG8_STAGE(PG8_SB(0, 1), cB + hstepB, voffB); PG8_STAGE(PG8_SA(0, 1), cA + hstepA, voffA);
;     if (wr == 1) PG8_BAR;
;     PG8_WAIT_V(4); PG8_BAR;
;     PG8_STAGE(PG8_SB(1, 0), cB + kstepB, voffB); PG8_STAGE(PG8_SA(1, 0), cA + kstepA, voffA); PG8_STAGE(PG8_SB(1, 1), cB + hstepB + kstepB, voffB);
;     PG8_WAIT_V(6); PG8_BAR;
; __global__ __launch_bounds__(512, 2) void mega(Params p0) {
;     ...
;             for (int pass = 0; pass < 3; ++pass) {
;                 EpiMerge e; e.Mo = Mb; e.first = pass == 0; e.Gt = (const bf16_t*)(ws + (pass == 0 ? B_GA : (pass == 1 ? B_GB : B_GC)));
;                 const bf16_t* Ap = pass == 0 ? (const bf16_t*)(ws + B_GL) : (pass == 1 ? (const bf16_t*)YS5 : (const bf16_t*)(ws + B_YATT));
;                 const bf16_t* Bp = W + (pass == 0 ? W_BRL : (pass == 1 ? W_BRS : W_BRA)); const int Kp = pass == 2 ? 512 : 1024;
;                 Gemm gm = mk_gemm(Ap, Kp, Bp, Kp, Kp, MT / 256, 8); gm.tB = 1; gemm_phase(lds, gm, e, p.wave);
.LBB0_113:
	s_and_b64 s[6:7], s[36:37], exec
	s_mov_b32 s5, 0x32600000
	s_cselect_b32 s5, s5, 0x38600000
	s_and_b64 s[6:7], s[38:39], exec
	s_cselect_b32 s5, 0x2c600000, s5
	s_add_u32 s70, s26, s5
	v_lshrrev_b32_e32 v8, 1, v6
	s_addc_u32 s71, s27, 0
	v_and_b32_e32 v8, 24, v8
	s_lshl_b32 s0, s0, 5
	v_and_b32_e32 v7, 15, v6
	s_lshr_b32 s86, s4, 6
	v_lshlrev_b32_e32 v9, 1, v8
	v_lshlrev_b32_e32 v6, 2, v6
	s_and_b32 s4, s0, 0x60
	v_lshl_or_b32 v194, s1, 6, v7
	v_lshl_or_b32 v7, v7, 6, v9
	s_lshl_b32 s1, s1, 13
	v_and_b32_e32 v6, 32, v6
	s_lshl_b32 s0, s4, 7
	v_bitop3_b32 v244, v7, s0, v6 bitop3:0xde
	s_add_u32 s0, s66, 0x8000
	v_mov_b32_e32 v201, v1
	v_bitop3_b32 v9, v7, s1, v6 bitop3:0xde
	s_addc_u32 s1, s67, 0
	v_mov_b32_e32 v205, v1
	s_add_i32 m0, s59, 0x18000
	v_lshl_add_u64 v[6:7], s[0:1], 0, v[200:201]
	s_waitcnt vmcnt(4)
	s_barrier
	global_load_lds_dwordx4 v[6:7], off
	v_lshl_add_u64 v[6:7], s[0:1], 0, v[204:205]
	s_add_i32 m0, s59, 0x1a000
	s_add_i32 s88, s59, 0x8000
	s_add_i32 s89, s59, 0xa000
	global_load_lds_dwordx4 v[6:7], off
	v_lshl_add_u64 v[4:5], v[4:5], 0, s[52:53]
	s_mov_b32 m0, s88
	s_add_u32 s0, s66, 0xc000
	global_load_lds_dwordx4 v[4:5], off
	v_lshl_add_u64 v[2:3], v[2:3], 0, s[52:53]
	s_mov_b32 m0, s89
	s_addc_u32 s1, s67, 0
	global_load_lds_dwordx4 v[2:3], off
	s_add_i32 m0, s59, 0x1c000
	v_lshl_add_u64 v[2:3], s[0:1], 0, v[200:201]
	global_load_lds_dwordx4 v[2:3], off
	v_lshl_add_u64 v[2:3], s[0:1], 0, v[204:205]
	s_add_i32 m0, s59, 0x1e000
	s_add_i32 s90, s86, -2
	global_load_lds_dwordx4 v[2:3], off
	s_waitcnt vmcnt(6)
	s_add_u32 s0, s82, 0x80
	s_addc_u32 s1, 0, 0
	v_mov_b32_e32 v2, 0
	s_mov_b32 s87, 0
	v_or_b32_e32 v245, s4, v8
	v_lshl_add_u64 v[206:207], s[0:1], 0, v[202:203]
	v_lshl_add_u64 v[208:209], s[0:1], 0, v[0:1]
	v_add_u32_e32 v246, 0, v9
	v_mov_b32_e32 v3, v2
	v_mov_b64_e32 v[4:5], 0
	v_mov_b64_e32 v[6:7], 0
	v_mov_b64_e32 v[8:9], 0
	v_mov_b64_e32 v[10:11], 0
	v_mov_b64_e32 v[12:13], 0
	v_mov_b64_e32 v[14:15], 0
	v_mov_b64_e32 v[16:17], 0
	v_mov_b64_e32 v[18:19], 0
	v_mov_b64_e32 v[20:21], 0
	v_mov_b64_e32 v[22:23], 0
	v_mov_b64_e32 v[24:25], 0
	v_mov_b64_e32 v[26:27], 0
	v_mov_b64_e32 v[28:29], 0
	v_mov_b64_e32 v[30:31], 0
	v_mov_b64_e32 v[32:33], 0
	v_mov_b64_e32 v[34:35], 0
	v_mov_b64_e32 v[36:37], 0
	v_mov_b64_e32 v[38:39], 0
	v_mov_b64_e32 v[40:41], 0
	v_mov_b64_e32 v[42:43], 0
	v_mov_b64_e32 v[44:45], 0
	v_mov_b64_e32 v[46:47], 0
	v_mov_b64_e32 v[48:49], 0
	v_mov_b64_e32 v[50:51], 0
	v_mov_b64_e32 v[52:53], 0
	v_mov_b64_e32 v[54:55], 0
	v_mov_b64_e32 v[56:57], 0
	v_mov_b64_e32 v[58:59], 0
	v_mov_b64_e32 v[60:61], 0
	v_mov_b64_e32 v[62:63], 0
	v_mov_b64_e32 v[64:65], 0
	v_mov_b64_e32 v[66:67], 0
	v_mov_b64_e32 v[68:69], 0
	v_mov_b64_e32 v[70:71], 0
	v_mov_b64_e32 v[72:73], 0
	v_mov_b64_e32 v[74:75], 0
	v_mov_b64_e32 v[76:77], 0
	v_mov_b64_e32 v[78:79], 0
	v_mov_b64_e32 v[80:81], 0
	v_mov_b64_e32 v[82:83], 0
	v_mov_b64_e32 v[84:85], 0
	v_mov_b64_e32 v[86:87], 0
	v_mov_b64_e32 v[88:89], 0
	v_mov_b64_e32 v[90:91], 0
	v_mov_b64_e32 v[92:93], 0
	v_mov_b64_e32 v[94:95], 0
	v_mov_b64_e32 v[96:97], 0
	v_mov_b64_e32 v[98:99], 0
	v_mov_b64_e32 v[100:101], 0
	v_mov_b64_e32 v[102:103], 0
	v_mov_b64_e32 v[104:105], 0
	v_mov_b64_e32 v[106:107], 0
	v_mov_b64_e32 v[108:109], 0
	v_mov_b64_e32 v[110:111], 0
	v_mov_b64_e32 v[112:113], 0
	v_mov_b64_e32 v[114:115], 0
	v_mov_b64_e32 v[116:117], 0
	v_mov_b64_e32 v[118:119], 0
	v_mov_b64_e32 v[120:121], 0
	v_mov_b64_e32 v[122:123], 0
	v_mov_b64_e32 v[124:125], 0
	v_mov_b64_e32 v[126:127], 0
	v_mov_b64_e32 v[128:129], 0
	s_movk_i32 s91, 0x61
	s_barrier
	s_branch .LBB0_115

; __device__ __forceinline__ u32x4 pack8(f32x4 v0, f32x4 v1) { u32x4 w; w.x = cvt_pk_bf16(v0[0], v0[1]); w.y = cvt_pk_bf16(v0[2], v0[3]); w.z = cvt_pk_bf16(v1[0], v1[1]); w.w = cvt_pk_bf16(v1[2], v1[3]); return w; }
; __device__ __forceinline__ void unpack8(u32x4 w, f32x4& v0, f32x4& v1) { v0 = (f32x4){bflo(w.x), bfhi(w.x), bflo(w.y), bfhi(w.y)}; v1 = (f32x4){bflo(w.z), bfhi(w.z), bflo(w.w), bfhi(w.w)}; }
;     __device__ __forceinline__ void operator()(AccRef acc, const Unit& u, int wr, int wc, int fr, int fq, const float (&pre)[8]) const {
;     ...
;         for (int ai = 0; ai < 2; ++ai) {
;             u32x4 gv[4][2], mv[4][2];
; #pragma unroll
;             for (int m = 0; m < 4; ++m)
; #pragma unroll
;                 for (int bj = 0; bj < 2; ++bj) { const size_t off = (size_t)(row0 + ai * HALF + m * 16) * 2048 + col0 + bj * HALF;
;                     gv[m][bj] = gld16(Gt + off); mv[m][bj] = (u32x4){0u, 0u, 0u, 0u}; if (!first) mv[m][bj] = gld16(Mo + off); }
; #pragma unroll
;             for (int m = 0; m < 4; ++m)
; #pragma unroll
;                 for (int bj = 0; bj < 2; ++bj) { const size_t off = (size_t)(row0 + ai * HALF + m * 16) * 2048 + col0 + bj * HALF;
;                     f32x4 g0, g1; unpack8(gv[m][bj], g0, g1);
;                     f32x4 v0 = g0 * acc[ai][bj][m][0], v1 = g1 * acc[ai][bj][m][1];
;                     { f32x4 p0, p1; unpack8(mv[m][bj], p0, p1); v0 += p0; v1 += p1; }
;                     gst16(Mo + off, pack8(v0, v1)); }
.LBB0_151:
	v_lshlrev_b64 v[196:197], 12, v[220:221]
	s_waitcnt vmcnt(0)
	v_lshlrev_b32_e32 v198, 16, v190
	v_and_b32_e32 v199, 0xffff0000, v190
	v_lshlrev_b32_e32 v190, 16, v191
	v_and_b32_e32 v191, 0xffff0000, v191
	v_lshlrev_b32_e32 v212, 16, v192
	v_and_b32_e32 v213, 0xffff0000, v192
	v_lshlrev_b32_e32 v192, 16, v193
	v_and_b32_e32 v193, 0xffff0000, v193
	v_lshlrev_b32_e32 v220, 16, v186
	v_and_b32_e32 v221, 0xffff0000, v186
	v_lshlrev_b32_e32 v186, 16, v187
	v_and_b32_e32 v187, 0xffff0000, v187
	v_lshlrev_b32_e32 v232, 16, v188
	v_and_b32_e32 v233, 0xffff0000, v188
	v_lshlrev_b32_e32 v188, 16, v189
	v_and_b32_e32 v189, 0xffff0000, v189
	v_pk_fma_f32 v[190:191], v[64:65], v[190:191], v[186:187]
	v_pk_fma_f32 v[186:187], v[62:63], v[198:199], v[220:221]
	v_pk_fma_f32 v[192:193], v[60:61], v[192:193], v[188:189]
	v_pk_fma_f32 v[188:189], v[58:59], v[212:213], v[232:233]
	v_lshl_add_u64 v[196:197], s[50:51], 0, v[196:197]
	v_lshl_add_u64 v[196:197], v[196:197], 0, v[210:211]
	v_cvt_pk_bf16_f32 v186, v186, v187
	v_cvt_pk_bf16_f32 v187, v190, v191
	v_cvt_pk_bf16_f32 v188, v188, v189
	v_cvt_pk_bf16_f32 v189, v192, v193
	global_store_dwordx4 v[196:197], v[186:189], off
	v_lshlrev_b32_e32 v190, 16, v170
	v_and_b32_e32 v191, 0xffff0000, v170
	v_lshlrev_b32_e32 v186, 16, v182
	v_and_b32_e32 v187, 0xffff0000, v182
	v_lshlrev_b32_e32 v182, 16, v183
	v_and_b32_e32 v183, 0xffff0000, v183
	v_lshlrev_b32_e32 v188, 16, v184
	v_and_b32_e32 v189, 0xffff0000, v184
	v_lshlrev_b32_e32 v184, 16, v185
	v_and_b32_e32 v185, 0xffff0000, v185
	v_lshlrev_b32_e32 v170, 16, v171
	v_and_b32_e32 v171, 0xffff0000, v171
	v_lshlrev_b32_e32 v192, 16, v172
	v_and_b32_e32 v193, 0xffff0000, v172
	v_lshlrev_b32_e32 v172, 16, v173
	v_and_b32_e32 v173, 0xffff0000, v173
	v_pk_fma_f32 v[182:183], v[32:33], v[182:183], v[170:171]
	v_pk_fma_f32 v[170:171], v[30:31], v[186:187], v[190:191]
	v_pk_fma_f32 v[184:185], v[28:29], v[184:185], v[172:173]
	v_pk_fma_f32 v[172:173], v[26:27], v[188:189], v[192:193]
	v_cvt_pk_bf16_f32 v170, v170, v171
	v_cvt_pk_bf16_f32 v171, v182, v183
	v_lshlrev_b32_e32 v182, 16, v180
	v_cvt_pk_bf16_f32 v172, v172, v173
	v_cvt_pk_bf16_f32 v173, v184, v185
	global_store_dwordx4 v[196:197], v[170:173], off offset:256
	v_lshlrev_b32_e32 v184, 16, v174
	v_and_b32_e32 v185, 0xffff0000, v174
	v_lshlrev_b64 v[170:171], 12, v[218:219]
	v_lshlrev_b32_e32 v172, 16, v178
	v_and_b32_e32 v173, 0xffff0000, v178
	v_lshlrev_b32_e32 v178, 16, v179
	v_and_b32_e32 v179, 0xffff0000, v179
	v_and_b32_e32 v183, 0xffff0000, v180
	v_lshlrev_b32_e32 v180, 16, v181
	v_and_b32_e32 v181, 0xffff0000, v181
	v_lshlrev_b32_e32 v174, 16, v175
	v_and_b32_e32 v175, 0xffff0000, v175
	v_lshlrev_b32_e32 v186, 16, v176
	v_and_b32_e32 v187, 0xffff0000, v176
	v_lshlrev_b32_e32 v176, 16, v177
	v_and_b32_e32 v177, 0xffff0000, v177
	v_pk_fma_f32 v[172:173], v[54:55], v[172:173], v[184:185]
	v_lshl_add_u64 v[170:171], s[50:51], 0, v[170:171]
	v_pk_fma_f32 v[174:175], v[56:57], v[178:179], v[174:175]
	v_pk_fma_f32 v[176:177], v[52:53], v[180:181], v[176:177]
	v_pk_fma_f32 v[178:179], v[50:51], v[182:183], v[186:187]
	v_lshl_add_u64 v[180:181], v[170:171], 0, v[210:211]
	v_cvt_pk_bf16_f32 v170, v172, v173
	v_cvt_pk_bf16_f32 v171, v174, v175
	v_cvt_pk_bf16_f32 v172, v178, v179
	v_cvt_pk_bf16_f32 v173, v176, v177
	global_store_dwordx4 v[180:181], v[170:173], off
	v_lshlrev_b32_e32 v174, 16, v154
	v_and_b32_e32 v175, 0xffff0000, v154
	v_lshlrev_b32_e32 v170, 16, v166
	v_and_b32_e32 v171, 0xffff0000, v166
	v_lshlrev_b32_e32 v166, 16, v167
	v_and_b32_e32 v167, 0xffff0000, v167
	v_lshlrev_b32_e32 v172, 16, v168
	v_and_b32_e32 v173, 0xffff0000, v168
	v_lshlrev_b32_e32 v168, 16, v169
	v_and_b32_e32 v169, 0xffff0000, v169
	v_lshlrev_b32_e32 v154, 16, v155
	v_and_b32_e32 v155, 0xffff0000, v155
	v_lshlrev_b32_e32 v176, 16, v156
	v_and_b32_e32 v177, 0xffff0000, v156
	v_lshlrev_b32_e32 v156, 16, v157
	v_and_b32_e32 v157, 0xffff0000, v157
	v_pk_fma_f32 v[166:167], v[24:25], v[166:167], v[154:155]
	v_pk_fma_f32 v[154:155], v[22:23], v[170:171], v[174:175]
	v_pk_fma_f32 v[168:169], v[20:21], v[168:169], v[156:157]
	v_pk_fma_f32 v[156:157], v[18:19], v[172:173], v[176:177]
	v_cvt_pk_bf16_f32 v154, v154, v155
	v_cvt_pk_bf16_f32 v155, v166, v167
	v_lshlrev_b32_e32 v166, 16, v164
	v_cvt_pk_bf16_f32 v156, v156, v157
	v_cvt_pk_bf16_f32 v157, v168, v169
	global_store_dwordx4 v[180:181], v[154:157], off offset:256
	v_lshlrev_b32_e32 v168, 16, v158
	v_and_b32_e32 v169, 0xffff0000, v158
	v_lshlrev_b64 v[154:155], 12, v[216:217]
	v_lshlrev_b32_e32 v156, 16, v162
	v_and_b32_e32 v157, 0xffff0000, v162
	v_lshlrev_b32_e32 v162, 16, v163
	v_and_b32_e32 v163, 0xffff0000, v163
	v_and_b32_e32 v167, 0xffff0000, v164
	v_lshlrev_b32_e32 v164, 16, v165
	v_and_b32_e32 v165, 0xffff0000, v165
	v_lshlrev_b32_e32 v158, 16, v159
	v_and_b32_e32 v159, 0xffff0000, v159
	v_lshlrev_b32_e32 v170, 16, v160
	v_and_b32_e32 v171, 0xffff0000, v160
	v_lshlrev_b32_e32 v160, 16, v161
	v_and_b32_e32 v161, 0xffff0000, v161
	v_pk_fma_f32 v[156:157], v[46:47], v[156:157], v[168:169]
	v_lshl_add_u64 v[154:155], s[50:51], 0, v[154:155]
	v_pk_fma_f32 v[158:159], v[48:49], v[162:163], v[158:159]
	v_pk_fma_f32 v[160:161], v[44:45], v[164:165], v[160:161]
	v_pk_fma_f32 v[162:163], v[42:43], v[166:167], v[170:171]
	v_lshl_add_u64 v[164:165], v[154:155], 0, v[210:211]
; __device__ __forceinline__ u32x4 pack8(f32x4 v0, f32x4 v1) { u32x4 w; w.x = cvt_pk_bf16(v0[0], v0[1]); w.y = cvt_pk_bf16(v0[2], v0[3]); w.z = cvt_pk_bf16(v1[0], v1[1]); w.w = cvt_pk_bf16(v1[2], v1[3]); return w; }
; __device__ __forceinline__ void unpack8(u32x4 w, f32x4& v0, f32x4& v1) { v0 = (f32x4){bflo(w.x), bfhi(w.x), bflo(w.y), bfhi(w.y)}; v1 = (f32x4){bflo(w.z), bfhi(w.z), bflo(w.w), bfhi(w.w)}; }
; template <class Epi, bool DYN = false>
; __device__ __forceinline__ void gemm_phase(LAS unsigned char* lds, const Gemm g, const Epi& E, int wave, unsigned* ctr = nullptr) {
;     ...
;         if (!has_next) break;
; #pragma unroll
;         for (int a = 0; a < 2; ++a)
; #pragma unroll
;             for (int b = 0; b < 2; ++b)
; #pragma unroll
;                 for (int m = 0; m < 4; ++m)
; #pragma unroll
;                     for (int n = 0; n < 2; ++n) acc[a][b][m][n] = (f32x4){0.f, 0.f, 0.f, 0.f};
;         cur = nxt; cA = nA; cB = nB; ++ui;
;     __device__ __forceinline__ void operator()(AccRef acc, const Unit& u, int wr, int wc, int fr, int fq, const float (&pre)[8]) const {
;     ...
;             for (int m = 0; m < 4; ++m)
; #pragma unroll
;                 for (int bj = 0; bj < 2; ++bj) { const size_t off = (size_t)(row0 + ai * HALF + m * 16) * 2048 + col0 + bj * HALF;
;                     f32x4 g0, g1; unpack8(gv[m][bj], g0, g1);
;                     f32x4 v0 = g0 * acc[ai][bj][m][0], v1 = g1 * acc[ai][bj][m][1];
;                     { f32x4 p0, p1; unpack8(mv[m][bj], p0, p1); v0 += p0; v1 += p1; }
;                     gst16(Mo + off, pack8(v0, v1)); }
	v_cvt_pk_bf16_f32 v154, v156, v157
	v_cvt_pk_bf16_f32 v155, v158, v159
	v_cvt_pk_bf16_f32 v156, v162, v163
	v_cvt_pk_bf16_f32 v157, v160, v161
	global_store_dwordx4 v[164:165], v[154:157], off
	v_lshlrev_b32_e32 v158, 16, v138
	v_and_b32_e32 v159, 0xffff0000, v138
	v_lshlrev_b32_e32 v154, 16, v150
	v_and_b32_e32 v155, 0xffff0000, v150
	v_lshlrev_b32_e32 v150, 16, v151
	v_and_b32_e32 v151, 0xffff0000, v151
	v_lshlrev_b32_e32 v156, 16, v152
	v_and_b32_e32 v157, 0xffff0000, v152
	v_lshlrev_b32_e32 v152, 16, v153
	v_and_b32_e32 v153, 0xffff0000, v153
	v_lshlrev_b32_e32 v138, 16, v139
	v_and_b32_e32 v139, 0xffff0000, v139
	v_lshlrev_b32_e32 v160, 16, v140
	v_and_b32_e32 v161, 0xffff0000, v140
	v_lshlrev_b32_e32 v140, 16, v141
	v_and_b32_e32 v141, 0xffff0000, v141
	v_pk_fma_f32 v[150:151], v[16:17], v[150:151], v[138:139]
	v_pk_fma_f32 v[138:139], v[14:15], v[154:155], v[158:159]
	v_pk_fma_f32 v[152:153], v[12:13], v[152:153], v[140:141]
	v_pk_fma_f32 v[140:141], v[10:11], v[156:157], v[160:161]
	v_cvt_pk_bf16_f32 v138, v138, v139
	v_cvt_pk_bf16_f32 v139, v150, v151
	v_lshlrev_b32_e32 v150, 16, v148
	v_cvt_pk_bf16_f32 v140, v140, v141
	v_cvt_pk_bf16_f32 v141, v152, v153
	global_store_dwordx4 v[164:165], v[138:141], off offset:256
	v_lshlrev_b32_e32 v152, 16, v142
	v_and_b32_e32 v153, 0xffff0000, v142
	v_lshlrev_b64 v[138:139], 12, v[214:215]
	v_lshlrev_b32_e32 v140, 16, v146
	v_and_b32_e32 v141, 0xffff0000, v146
	v_lshlrev_b32_e32 v146, 16, v147
	v_and_b32_e32 v147, 0xffff0000, v147
	v_and_b32_e32 v151, 0xffff0000, v148
	v_lshlrev_b32_e32 v148, 16, v149
	v_and_b32_e32 v149, 0xffff0000, v149
	v_lshlrev_b32_e32 v142, 16, v143
	v_and_b32_e32 v143, 0xffff0000, v143
	v_lshlrev_b32_e32 v154, 16, v144
	v_and_b32_e32 v155, 0xffff0000, v144
	v_lshlrev_b32_e32 v144, 16, v145
	v_and_b32_e32 v145, 0xffff0000, v145
	v_pk_fma_f32 v[140:141], v[38:39], v[140:141], v[152:153]
	v_lshl_add_u64 v[138:139], s[50:51], 0, v[138:139]
	v_pk_fma_f32 v[142:143], v[40:41], v[146:147], v[142:143]
	v_pk_fma_f32 v[144:145], v[36:37], v[148:149], v[144:145]
	v_pk_fma_f32 v[146:147], v[34:35], v[150:151], v[154:155]
	v_lshl_add_u64 v[148:149], v[138:139], 0, v[210:211]
	v_cvt_pk_bf16_f32 v138, v140, v141
	v_cvt_pk_bf16_f32 v139, v142, v143
	v_cvt_pk_bf16_f32 v140, v146, v147
	v_cvt_pk_bf16_f32 v141, v144, v145
	global_store_dwordx4 v[148:149], v[138:141], off
	v_lshlrev_b32_e32 v142, 16, v130
	v_and_b32_e32 v143, 0xffff0000, v130
	v_lshlrev_b32_e32 v138, 16, v134
	v_and_b32_e32 v139, 0xffff0000, v134
	v_lshlrev_b32_e32 v134, 16, v135
	v_and_b32_e32 v135, 0xffff0000, v135
	v_lshlrev_b32_e32 v140, 16, v136
	v_and_b32_e32 v141, 0xffff0000, v136
	v_lshlrev_b32_e32 v136, 16, v137
	v_and_b32_e32 v137, 0xffff0000, v137
	v_lshlrev_b32_e32 v130, 16, v131
	v_and_b32_e32 v131, 0xffff0000, v131
	v_lshlrev_b32_e32 v144, 16, v132
	v_and_b32_e32 v145, 0xffff0000, v132
	v_lshlrev_b32_e32 v132, 16, v133
	v_and_b32_e32 v133, 0xffff0000, v133
	v_pk_fma_f32 v[134:135], v[8:9], v[134:135], v[130:131]
	v_pk_fma_f32 v[130:131], v[6:7], v[138:139], v[142:143]
	v_pk_fma_f32 v[136:137], v[4:5], v[136:137], v[132:133]
	v_pk_fma_f32 v[132:133], v[2:3], v[140:141], v[144:145]
	s_andn2_b64 vcc, exec, s[38:39]
	v_cvt_pk_bf16_f32 v130, v130, v131
	v_cvt_pk_bf16_f32 v131, v134, v135
	v_cvt_pk_bf16_f32 v132, v132, v133
	v_cvt_pk_bf16_f32 v133, v136, v137
	global_store_dwordx4 v[148:149], v[130:133], off offset:256
	s_cbranch_vccnz .LBB0_114
	v_mov_b32_e32 v2, 0
	s_mov_b32 s60, s62
	s_mov_b32 s58, s72
	s_mov_b64 s[66:67], s[76:77]
	s_mov_b64 s[68:69], s[74:75]
	s_mov_b32 s87, s95
	v_mov_b32_e32 v3, v2
	v_mov_b64_e32 v[4:5], 0
	v_mov_b64_e32 v[6:7], 0
	v_mov_b64_e32 v[8:9], 0
	v_mov_b64_e32 v[10:11], 0
	v_mov_b64_e32 v[12:13], 0
	v_mov_b64_e32 v[14:15], 0
	v_mov_b64_e32 v[16:17], 0
	v_mov_b64_e32 v[18:19], 0
	v_mov_b64_e32 v[20:21], 0
	v_mov_b64_e32 v[22:23], 0
	v_mov_b64_e32 v[24:25], 0
	v_mov_b64_e32 v[26:27], 0
	v_mov_b64_e32 v[28:29], 0
	v_mov_b64_e32 v[30:31], 0
	v_mov_b64_e32 v[32:33], 0
	v_mov_b64_e32 v[34:35], 0
	v_mov_b64_e32 v[36:37], 0
	v_mov_b64_e32 v[38:39], 0
	v_mov_b64_e32 v[40:41], 0
	v_mov_b64_e32 v[42:43], 0
	v_mov_b64_e32 v[44:45], 0
	v_mov_b64_e32 v[46:47], 0
	v_mov_b64_e32 v[48:49], 0
	v_mov_b64_e32 v[50:51], 0
	v_mov_b64_e32 v[52:53], 0
	v_mov_b64_e32 v[54:55], 0
	v_mov_b64_e32 v[56:57], 0
	v_mov_b64_e32 v[58:59], 0
	v_mov_b64_e32 v[60:61], 0
	v_mov_b64_e32 v[62:63], 0
	v_mov_b64_e32 v[64:65], 0
	v_mov_b64_e32 v[66:67], 0
	v_mov_b64_e32 v[68:69], 0
	v_mov_b64_e32 v[70:71], 0
	v_mov_b64_e32 v[72:73], 0
	v_mov_b64_e32 v[74:75], 0
	v_mov_b64_e32 v[76:77], 0
	v_mov_b64_e32 v[78:79], 0
	v_mov_b64_e32 v[80:81], 0
	v_mov_b64_e32 v[82:83], 0
	v_mov_b64_e32 v[84:85], 0
	v_mov_b64_e32 v[86:87], 0
	v_mov_b64_e32 v[88:89], 0
	v_mov_b64_e32 v[90:91], 0
	v_mov_b64_e32 v[92:93], 0
	v_mov_b64_e32 v[94:95], 0
	v_mov_b64_e32 v[96:97], 0
	v_mov_b64_e32 v[98:99], 0
	v_mov_b64_e32 v[100:101], 0
	v_mov_b64_e32 v[102:103], 0
	v_mov_b64_e32 v[104:105], 0
	v_mov_b64_e32 v[106:107], 0
	v_mov_b64_e32 v[108:109], 0
	v_mov_b64_e32 v[110:111], 0
	v_mov_b64_e32 v[112:113], 0
	v_mov_b64_e32 v[114:115], 0
	v_mov_b64_e32 v[116:117], 0
	v_mov_b64_e32 v[118:119], 0
	v_mov_b64_e32 v[120:121], 0
	v_mov_b64_e32 v[122:123], 0
	v_mov_b64_e32 v[124:125], 0
	v_mov_b64_e32 v[126:127], 0
	v_mov_b64_e32 v[128:129], 0
	s_branch .LBB0_114

; #define PG8_STAGE(bufoff, gbase, voff) do { _Pragma("unroll") for (int _i = 0; _i < 2; ++_i) \
;         __builtin_amdgcn_global_load_lds((const unsigned*)((const char*)(gbase) + (voff)[_i]), (LAS unsigned*)(lds + (bufoff) + ldsw + _i * 8192), 16, 0, 0); } while (0)
; #define PG8_WAIT_V(n) asm volatile("s_waitcnt vmcnt(" #n ")" ::: "memory")
; #define PG8_BAR __builtin_amdgcn_s_barrier()
; template <class Epi, bool DYN = false>
; __device__ __forceinline__ void gemm_phase(LAS unsigned char* lds, const Gemm g, const Epi& E, int wave, unsigned* ctr = nullptr) {
;     ...
;     f32x4 acc[2][2][4][2];
; #pragma unroll
;     for (int a = 0; a < 2; ++a)
; #pragma unroll
;         for (int b = 0; b < 2; ++b)
; #pragma unroll
;             for (int m = 0; m < 4; ++m)
; #pragma unroll
;                 for (int n = 0; n < 2; ++n) acc[a][b][m][n] = (f32x4){0.f, 0.f, 0.f, 0.f};
;     bf16x8 At[4][2], B0[2][2], B1[2][2];
;     const char* cA = (const char*)(g.A + (size_t)cur.b * g.sA) + (size_t)cur.pm * tstepA; const char* cB = (const char*)(g.Bt + (size_t)cur.b * g.sB) + (size_t)cur.pn * tstepB;
;     float pre[8];
;     E.prefetch(pre, cur, wr, fr);
;     PG8_STAGE(PG8_SB(0, 0), cB, voffB); PG8_STAGE(PG8_SA(0, 0), cA, voffA); PG8_STAGE(PG8_SB(0, 1), cB + hstepB, voffB); PG8_STAGE(PG8_SA(0, 1), cA + hstepA, voffA);
;     if (wr == 1) PG8_BAR;
;     PG8_WAIT_V(4); PG8_BAR;
;     PG8_STAGE(PG8_SB(1, 0), cB + kstepB, voffB); PG8_STAGE(PG8_SA(1, 0), cA + kstepA, voffA); PG8_STAGE(PG8_SB(1, 1), cB + hstepB + kstepB, voffB);
;     PG8_WAIT_V(6); PG8_BAR;
; __global__ __launch_bounds__(512, 2) void mega(Params p0) {
;     ...
;             lru_items<1>(p, shm, l);
;         } break;
;         case 8: {
;             EpiGlu e; e.Y1 = Y1; e.O = YS5; e.bias = p.in[20] + l * 1024; Gemm gg = mk_gemm(Y1, 1024, W + W_GLU, 1024, 1024, MT / 256, 4); gg.tB = 1; gemm_phase(lds, gg, e, p.wave);
.LBB0_160:
	v_readlane_b32 s4, v254, 43
	v_readlane_b32 s5, v254, 44
	s_lshl_b32 s4, s4, 10
	s_ashr_i32 s5, s4, 31
	v_readlane_b32 s80, v251, 52
	v_lshrrev_b32_e32 v14, 1, v8
	s_lshl_b64 s[4:5], s[4:5], 2
	v_readlane_b32 s88, v251, 60
	v_and_b32_e32 v16, 24, v14
	v_readlane_b32 s89, v251, 61
	s_add_u32 s64, s88, s4
	v_and_b32_e32 v13, 15, v8
	v_lshlrev_b32_e32 v14, 1, v16
	v_lshlrev_b32_e32 v8, 2, v8
	s_sext_i32_i8 s78, s0
	s_addc_u32 s65, s89, s5
	v_lshl_or_b32 v194, s2, 6, v13
	v_lshl_or_b32 v13, v13, 6, v14
	s_lshl_b32 s0, s2, 13
	v_and_b32_e32 v8, 32, v8
	v_bitop3_b32 v17, v13, s0, v8 bitop3:0xde
	s_lshl_b32 s0, s1, 5
	s_and_b32 s2, s0, 0x60
	s_lshl_b32 s0, s2, 7
	v_bitop3_b32 v204, v13, s0, v8 bitop3:0xde
	s_add_u32 s0, s60, 0x8000
	v_mov_b32_e32 v179, v1
	s_addc_u32 s1, s61, 0
	v_mov_b32_e32 v175, v1
	s_add_i32 m0, s59, 0x18000
	v_lshl_add_u64 v[14:15], s[0:1], 0, v[178:179]
	s_waitcnt vmcnt(4)
	s_barrier
	global_load_lds_dwordx4 v[14:15], off
	v_lshl_add_u64 v[14:15], s[0:1], 0, v[174:175]
	s_add_i32 m0, s59, 0x1a000
	s_add_i32 s79, s59, 0x8000
	s_add_i32 s80, s59, 0xa000
	global_load_lds_dwordx4 v[14:15], off
	v_lshl_add_u64 v[4:5], v[4:5], 0, s[52:53]
	s_mov_b32 m0, s79
	s_add_u32 s0, s60, 0xc000
	global_load_lds_dwordx4 v[4:5], off
	v_lshl_add_u64 v[2:3], v[2:3], 0, s[52:53]
	s_mov_b32 m0, s80
	s_addc_u32 s1, s61, 0
	global_load_lds_dwordx4 v[2:3], off
	s_add_i32 m0, s59, 0x1c000
	v_lshl_add_u64 v[2:3], s[0:1], 0, v[178:179]
	global_load_lds_dwordx4 v[2:3], off
	v_lshl_add_u64 v[2:3], s[0:1], 0, v[174:175]
	s_add_i32 m0, s59, 0x1e000
	s_mov_b64 s[0:1], 0x40080
	global_load_lds_dwordx4 v[2:3], off
	v_lshlrev_b32_e32 v2, 14, v6
	v_and_b32_e32 v2, 0xffff8000, v2
	v_lshl_add_u32 v2, v7, 11, v2
	v_and_b32_e32 v3, 1, v6
	v_lshl_or_b32 v2, v3, 6, v2
	v_lshl_add_u32 v2, v9, 1, v2
	v_mov_b32_e32 v3, v1
	v_lshl_add_u64 v[180:181], v[2:3], 0, s[0:1]
	v_lshlrev_b32_e32 v2, 14, v11
	v_and_b32_e32 v2, 0xffff8000, v2
	v_lshl_add_u32 v2, v10, 11, v2
	v_and_b32_e32 v3, 1, v11
	v_lshl_or_b32 v2, v3, 6, v2
	v_readlane_b32 s90, v251, 62
	v_readlane_b32 s91, v251, 63
	s_waitcnt vmcnt(6)
	v_lshl_add_u32 v2, v12, 1, v2
	v_mov_b32_e32 v3, v1
	v_readlane_b32 s81, v251, 53
	v_readlane_b32 s84, v251, 56
	v_readlane_b32 s92, v252, 0
	v_readlane_b32 s93, v252, 1
	v_readlane_b32 s94, v252, 2
	v_readlane_b32 s95, v252, 3
	v_lshl_add_u64 v[182:183], v[2:3], 0, s[0:1]
	v_mov_b32_e32 v2, 0
	v_readlane_b32 s0, v254, 61
	v_readlane_b32 s90, v254, 25
	v_readlane_b32 s88, v254, 27
	v_or_b32_e32 v205, s2, v16
	s_mov_b32 s81, 0
	v_add_u32_e32 v206, 0, v17
	s_mov_b32 s40, s0
	v_mov_b32_e32 v3, v2
	v_mov_b64_e32 v[4:5], 0
	v_mov_b64_e32 v[6:7], 0
	v_mov_b64_e32 v[8:9], 0
	v_mov_b64_e32 v[10:11], 0
	v_mov_b64_e32 v[12:13], 0
	v_mov_b64_e32 v[14:15], 0
	v_mov_b64_e32 v[16:17], 0
	v_mov_b64_e32 v[18:19], 0
	v_mov_b64_e32 v[20:21], 0
	v_mov_b64_e32 v[22:23], 0
	v_mov_b64_e32 v[24:25], 0
	v_mov_b64_e32 v[26:27], 0
	v_mov_b64_e32 v[28:29], 0
	v_mov_b64_e32 v[30:31], 0
	v_mov_b64_e32 v[32:33], 0
	v_mov_b64_e32 v[34:35], 0
	v_mov_b64_e32 v[36:37], 0
	v_mov_b64_e32 v[38:39], 0
	v_mov_b64_e32 v[40:41], 0
	v_mov_b64_e32 v[42:43], 0
	v_mov_b64_e32 v[44:45], 0
	v_mov_b64_e32 v[46:47], 0
	v_mov_b64_e32 v[48:49], 0
	v_mov_b64_e32 v[50:51], 0
	v_mov_b64_e32 v[52:53], 0
	v_mov_b64_e32 v[54:55], 0
	v_mov_b64_e32 v[56:57], 0
	v_mov_b64_e32 v[58:59], 0
	v_mov_b64_e32 v[60:61], 0
	v_mov_b64_e32 v[62:63], 0
	v_mov_b64_e32 v[64:65], 0
	v_mov_b64_e32 v[66:67], 0
	v_mov_b64_e32 v[68:69], 0
	v_mov_b64_e32 v[70:71], 0
	v_mov_b64_e32 v[72:73], 0
	v_mov_b64_e32 v[74:75], 0
	v_mov_b64_e32 v[76:77], 0
	v_mov_b64_e32 v[78:79], 0
	v_mov_b64_e32 v[80:81], 0
	v_mov_b64_e32 v[82:83], 0
	v_mov_b64_e32 v[84:85], 0
	v_mov_b64_e32 v[86:87], 0
	v_mov_b64_e32 v[88:89], 0
	v_mov_b64_e32 v[90:91], 0
	v_mov_b64_e32 v[92:93], 0
	v_mov_b64_e32 v[94:95], 0
	v_mov_b64_e32 v[96:97], 0
	v_mov_b64_e32 v[98:99], 0
	v_mov_b64_e32 v[100:101], 0
	v_mov_b64_e32 v[102:103], 0
	v_mov_b64_e32 v[104:105], 0
	v_mov_b64_e32 v[106:107], 0
	v_mov_b64_e32 v[108:109], 0
	v_mov_b64_e32 v[110:111], 0
	v_mov_b64_e32 v[112:113], 0
	v_mov_b64_e32 v[114:115], 0
	v_mov_b64_e32 v[116:117], 0
	v_mov_b64_e32 v[118:119], 0
	v_mov_b64_e32 v[120:121], 0
	v_mov_b64_e32 v[122:123], 0
	v_mov_b64_e32 v[124:125], 0
	v_mov_b64_e32 v[126:127], 0
	v_mov_b64_e32 v[128:129], 0
	v_readlane_b32 s93, v254, 24
	v_readlane_b32 s91, v254, 26
	v_readlane_b32 s89, v254, 28
	s_movk_i32 s95, 0x600
	s_movk_i32 s94, 0x1000
	v_readlane_b32 s84, v254, 58
	s_mov_b32 s92, s8
	v_readlane_b32 s82, v251, 54
	v_readlane_b32 s83, v251, 55
	v_readlane_b32 s85, v251, 57
	v_readlane_b32 s86, v251, 58
	v_readlane_b32 s87, v251, 59
	s_barrier
	s_branch .LBB0_162

; #define PG8_STAGE(bufoff, gbase, voff) do { _Pragma("unroll") for (int _i = 0; _i < 2; ++_i) \
;         __builtin_amdgcn_global_load_lds((const unsigned*)((const char*)(gbase) + (voff)[_i]), (LAS unsigned*)(lds + (bufoff) + ldsw + _i * 8192), 16, 0, 0); } while (0)
; #define PG8_LDA(dst, b, h) do { _Pragma("unroll") for (int m = 0; m < 4; ++m) _Pragma("unroll") for (int k = 0; k < 2; ++k) dst[m][k] = *(const LAS bf16x8*)(lds + PG8_SA(b, h) + aoff + m * 2048 + k * 1024); } while (0)
; #define PG8_LDB(dst, b, h) do { _Pragma("unroll") for (int n = 0; n < 2; ++n) _Pragma("unroll") for (int k = 0; k < 2; ++k) dst[n][k] = *(const LAS bf16x8*)(lds + PG8_SB(b, h) + boff + n * 2048 + k * 1024); } while (0)
; #define PG8_MMA(ai, bj, At, Bt) do { __builtin_amdgcn_s_setprio(1); _Pragma("unroll") for (int m = 0; m < 4; ++m) _Pragma("unroll") for (int n = 0; n < 2; ++n) _Pragma("unroll") for (int k = 0; k < 2; ++k) \
;         acc[ai][bj][m][n] = __builtin_amdgcn_mfma_f32_16x16x32_bf16(Bt[n][k], At[m][k], acc[ai][bj][m][n], 0, 0, 0); __builtin_amdgcn_s_setprio(0); } while (0)
; #define PG8_WAIT_V(n) asm volatile("s_waitcnt vmcnt(" #n ")" ::: "memory")
; #define PG8_WAIT_L(n) asm volatile("s_waitcnt lgkmcnt(" #n ")" ::: "memory")
; #define PG8_BAR __builtin_amdgcn_s_barrier()
; #define PG8_SCHED __builtin_amdgcn_sched_barrier(0)
; template <class Epi, bool DYN = false>
; __device__ __forceinline__ void gemm_phase(LAS unsigned char* lds, const Gemm g, const Epi& E, int wave, unsigned* ctr = nullptr) {
;     ...
;             PG8_LDB(B0, 0, 0); PG8_SCHED; PG8_LDA(At, 0, 0); PG8_STAGE(PG8_SA(1, 1), a1 + hstepA, voffA);
;             PG8_WAIT_L(8); PG8_BAR; PG8_WAIT_L(0); PG8_MMA(0, 0, At, B0); PG8_BAR; PG8_SCHED;
;             PG8_LDB(B1, 0, 1); PG8_STAGE(PG8_SB(0, 0), b2, voffB);
;             PG8_BAR; PG8_WAIT_L(0); PG8_MMA(0, 1, At, B1); PG8_BAR;
;             PG8_LDA(At, 0, 1); PG8_STAGE(PG8_SA(0, 0), a2, voffA);
;             PG8_BAR; PG8_WAIT_L(0); PG8_MMA(1, 0, At, B0); PG8_BAR; PG8_SCHED;
;             PG8_STAGE(PG8_SB(0, 1), b2 + hstepB, voffB);
;             PG8_WAIT_V(6); PG8_BAR; PG8_MMA(1, 1, At, B1); PG8_BAR;
.LBB0_165:
	s_add_u32 s7, s62, s46
	s_addc_u32 s8, s63, s47
	s_add_i32 s9, 0, 0x10000
	v_add_u32_e32 v146, s9, v204
	ds_read_b128 v[134:137], v146
	ds_read_b128 v[138:141], v146 offset:1024
	ds_read_b128 v[142:145], v146 offset:2048
	ds_read_b128 v[146:149], v146 offset:3072
	s_cmp_eq_u32 s6, 12
	s_cselect_b32 s73, s0, s8
	s_cselect_b32 s72, s1, s7
	s_cselect_b32 s55, s2, s5
	s_cselect_b32 s54, s3, s4
	v_lshl_add_u64 v[192:193], s[62:63], 0, v[130:131]
	s_add_i32 m0, s59, 0xc000
	ds_read_b128 v[150:153], v206
	ds_read_b128 v[154:157], v206 offset:1024
	ds_read_b128 v[158:161], v206 offset:2048
	ds_read_b128 v[162:165], v206 offset:3072
	ds_read_b128 v[166:169], v206 offset:4096
	ds_read_b128 v[170:173], v206 offset:5120
	ds_read_b128 v[184:187], v206 offset:6144
	ds_read_b128 v[188:191], v206 offset:7168
	global_load_lds_dwordx4 v[192:193], off
	v_lshl_add_u64 v[192:193], s[62:63], 0, v[132:133]
	s_add_i32 m0, s59, 0xe000
	s_nop 0
	global_load_lds_dwordx4 v[192:193], off
	s_waitcnt lgkmcnt(8)
	s_barrier
	s_waitcnt lgkmcnt(0)
	s_setprio 1
	s_waitcnt lgkmcnt(0)
	v_mfma_f32_16x16x32_bf16 v[126:129], v[134:137], v[150:153], v[126:129]
	v_mfma_f32_16x16x32_bf16 v[122:125], v[142:145], v[150:153], v[122:125]
	v_mfma_f32_16x16x32_bf16 v[118:121], v[134:137], v[158:161], v[118:121]
	v_mfma_f32_16x16x32_bf16 v[114:117], v[142:145], v[158:161], v[114:117]
	v_mfma_f32_16x16x32_bf16 v[110:113], v[134:137], v[166:169], v[110:113]
	v_mfma_f32_16x16x32_bf16 v[106:109], v[142:145], v[166:169], v[106:109]
	v_mfma_f32_16x16x32_bf16 v[102:105], v[134:137], v[184:187], v[102:105]
	v_mfma_f32_16x16x32_bf16 v[98:101], v[142:145], v[184:187], v[98:101]
	v_mfma_f32_16x16x32_bf16 v[126:129], v[138:141], v[154:157], v[126:129]
	v_mfma_f32_16x16x32_bf16 v[122:125], v[146:149], v[154:157], v[122:125]
	v_mfma_f32_16x16x32_bf16 v[118:121], v[138:141], v[162:165], v[118:121]
	v_mfma_f32_16x16x32_bf16 v[114:117], v[146:149], v[162:165], v[114:117]
	v_mfma_f32_16x16x32_bf16 v[110:113], v[138:141], v[170:173], v[110:113]
	v_mfma_f32_16x16x32_bf16 v[106:109], v[146:149], v[170:173], v[106:109]
	v_mfma_f32_16x16x32_bf16 v[102:105], v[138:141], v[188:191], v[102:105]
	v_mfma_f32_16x16x32_bf16 v[98:101], v[146:149], v[188:191], v[98:101]
	s_setprio 0
	s_barrier
	s_add_i32 s7, 0, 0x14000
	v_add_u32_e32 v192, s7, v204
	s_add_i32 s8, s9, s48
	ds_read_b128 v[196:199], v192
	ds_read_b128 v[200:203], v192 offset:1024
	ds_read_b128 v[208:211], v192 offset:2048
	ds_read_b128 v[212:215], v192 offset:3072
	v_lshl_add_u64 v[192:193], s[54:55], 0, v[178:179]
	s_mov_b32 m0, s8
	s_nop 0
	global_load_lds_dwordx4 v[192:193], off
	v_lshl_add_u64 v[192:193], s[54:55], 0, v[174:175]
	s_add_i32 m0, s8, 0x2000
	s_nop 0
	global_load_lds_dwordx4 v[192:193], off
	s_barrier
	s_waitcnt lgkmcnt(0)
	s_setprio 1
	s_waitcnt lgkmcnt(0)
	v_mfma_f32_16x16x32_bf16 v[94:97], v[196:199], v[150:153], v[94:97]
	v_mfma_f32_16x16x32_bf16 v[90:93], v[208:211], v[150:153], v[90:93]
	v_mfma_f32_16x16x32_bf16 v[86:89], v[196:199], v[158:161], v[86:89]
	v_mfma_f32_16x16x32_bf16 v[82:85], v[208:211], v[158:161], v[82:85]
	v_mfma_f32_16x16x32_bf16 v[78:81], v[196:199], v[166:169], v[78:81]
	v_mfma_f32_16x16x32_bf16 v[74:77], v[208:211], v[166:169], v[74:77]
	v_mfma_f32_16x16x32_bf16 v[70:73], v[196:199], v[184:187], v[70:73]
	v_mfma_f32_16x16x32_bf16 v[66:69], v[208:211], v[184:187], v[66:69]
	v_mfma_f32_16x16x32_bf16 v[94:97], v[200:203], v[154:157], v[94:97]
	v_mfma_f32_16x16x32_bf16 v[90:93], v[212:215], v[154:157], v[90:93]
	v_mfma_f32_16x16x32_bf16 v[86:89], v[200:203], v[162:165], v[86:89]
	v_mfma_f32_16x16x32_bf16 v[82:85], v[212:215], v[162:165], v[82:85]
	v_mfma_f32_16x16x32_bf16 v[78:81], v[200:203], v[170:173], v[78:81]
	v_mfma_f32_16x16x32_bf16 v[74:77], v[212:215], v[170:173], v[74:77]
	v_mfma_f32_16x16x32_bf16 v[70:73], v[200:203], v[188:191], v[70:73]
	v_mfma_f32_16x16x32_bf16 v[66:69], v[212:215], v[188:191], v[66:69]
	s_setprio 0
	s_mov_b32 m0, s59
	v_lshl_add_u64 v[192:193], s[72:73], 0, v[0:1]
	s_barrier
	ds_read_b128 v[150:153], v206 offset:16384
	ds_read_b128 v[154:157], v206 offset:17408
	ds_read_b128 v[158:161], v206 offset:18432
	ds_read_b128 v[162:165], v206 offset:19456
	ds_read_b128 v[166:169], v206 offset:20480
	ds_read_b128 v[170:173], v206 offset:21504
	ds_read_b128 v[184:187], v206 offset:22528
	ds_read_b128 v[188:191], v206 offset:23552
	global_load_lds_dwordx4 v[192:193], off
	v_lshl_add_u64 v[216:217], s[72:73], 0, v[176:177]
	s_mov_b32 m0, s75
	s_nop 0
	global_load_lds_dwordx4 v[216:217], off
	s_barrier
	s_waitcnt lgkmcnt(0)
	s_setprio 1
	s_waitcnt lgkmcnt(0)
	v_mfma_f32_16x16x32_bf16 v[62:65], v[134:137], v[150:153], v[62:65]
	v_mfma_f32_16x16x32_bf16 v[58:61], v[142:145], v[150:153], v[58:61]
	v_mfma_f32_16x16x32_bf16 v[54:57], v[134:137], v[158:161], v[54:57]
	v_mfma_f32_16x16x32_bf16 v[50:53], v[142:145], v[158:161], v[50:53]
	v_mfma_f32_16x16x32_bf16 v[46:49], v[134:137], v[166:169], v[46:49]
	v_mfma_f32_16x16x32_bf16 v[42:45], v[142:145], v[166:169], v[42:45]
	v_mfma_f32_16x16x32_bf16 v[38:41], v[134:137], v[184:187], v[38:41]
	v_mfma_f32_16x16x32_bf16 v[34:37], v[142:145], v[184:187], v[34:37]
	v_mfma_f32_16x16x32_bf16 v[62:65], v[138:141], v[154:157], v[62:65]
	v_mfma_f32_16x16x32_bf16 v[58:61], v[146:149], v[154:157], v[58:61]
	v_mfma_f32_16x16x32_bf16 v[54:57], v[138:141], v[162:165], v[54:57]
	v_mfma_f32_16x16x32_bf16 v[50:53], v[146:149], v[162:165], v[50:53]
	v_mfma_f32_16x16x32_bf16 v[46:49], v[138:141], v[170:173], v[46:49]
	v_mfma_f32_16x16x32_bf16 v[42:45], v[146:149], v[170:173], v[42:45]
	v_mfma_f32_16x16x32_bf16 v[38:41], v[138:141], v[188:191], v[38:41]
	v_mfma_f32_16x16x32_bf16 v[34:37], v[146:149], v[188:191], v[34:37]
	s_setprio 0
	s_barrier
; #define PG8_STAGE(bufoff, gbase, voff) do { _Pragma("unroll") for (int _i = 0; _i < 2; ++_i) \
;         __builtin_amdgcn_global_load_lds((const unsigned*)((const char*)(gbase) + (voff)[_i]), (LAS unsigned*)(lds + (bufoff) + ldsw + _i * 8192), 16, 0, 0); } while (0)
; #define PG8_LDA(dst, b, h) do { _Pragma("unroll") for (int m = 0; m < 4; ++m) _Pragma("unroll") for (int k = 0; k < 2; ++k) dst[m][k] = *(const LAS bf16x8*)(lds + PG8_SA(b, h) + aoff + m * 2048 + k * 1024); } while (0)
; #define PG8_LDB(dst, b, h) do { _Pragma("unroll") for (int n = 0; n < 2; ++n) _Pragma("unroll") for (int k = 0; k < 2; ++k) dst[n][k] = *(const LAS bf16x8*)(lds + PG8_SB(b, h) + boff + n * 2048 + k * 1024); } while (0)
; #define PG8_MMA(ai, bj, At, Bt) do { __builtin_amdgcn_s_setprio(1); _Pragma("unroll") for (int m = 0; m < 4; ++m) _Pragma("unroll") for (int n = 0; n < 2; ++n) _Pragma("unroll") for (int k = 0; k < 2; ++k) \
;         acc[ai][bj][m][n] = __builtin_amdgcn_mfma_f32_16x16x32_bf16(Bt[n][k], At[m][k], acc[ai][bj][m][n], 0, 0, 0); __builtin_amdgcn_s_setprio(0); } while (0)
; #define PG8_WAIT_V(n) asm volatile("s_waitcnt vmcnt(" #n ")" ::: "memory")
; #define PG8_WAIT_L(n) asm volatile("s_waitcnt lgkmcnt(" #n ")" ::: "memory")
; #define PG8_BAR __builtin_amdgcn_s_barrier()
; #define PG8_SCHED __builtin_amdgcn_sched_barrier(0)
; template <class Epi, bool DYN = false>
; __device__ __forceinline__ void gemm_phase(LAS unsigned char* lds, const Gemm g, const Epi& E, int wave, unsigned* ctr = nullptr) {
;     ...
;             PG8_WAIT_V(6); PG8_BAR; PG8_MMA(1, 1, At, B1); PG8_BAR;
;             PG8_LDB(B0, 1, 0); PG8_SCHED; PG8_LDA(At, 1, 0); PG8_STAGE(PG8_SA(0, 1), a2 + hstepA, voffA);
;             PG8_WAIT_L(8); PG8_BAR; PG8_WAIT_L(0); PG8_MMA(0, 0, At, B0); PG8_BAR; PG8_SCHED;
;             PG8_LDB(B1, 1, 1); PG8_STAGE(PG8_SB(1, 0), b3, voffB);
;             PG8_BAR; PG8_WAIT_L(0); PG8_MMA(0, 1, At, B1); PG8_BAR;
	s_add_u32 s8, s54, 0x4000
	s_addc_u32 s9, s55, 0
	s_add_i32 s7, s7, s48
	v_lshl_add_u64 v[134:135], s[8:9], 0, v[178:179]
	s_mov_b32 m0, s7
	s_nop 0
	global_load_lds_dwordx4 v[134:135], off
	v_lshl_add_u64 v[134:135], s[8:9], 0, v[174:175]
	s_add_i32 m0, s7, 0x2000
	s_nop 0
	global_load_lds_dwordx4 v[134:135], off
	s_waitcnt vmcnt(6)
	s_barrier
	s_setprio 1
	v_mfma_f32_16x16x32_bf16 v[30:33], v[196:199], v[150:153], v[30:33]
	v_mfma_f32_16x16x32_bf16 v[26:29], v[208:211], v[150:153], v[26:29]
	v_mfma_f32_16x16x32_bf16 v[22:25], v[196:199], v[158:161], v[22:25]
	v_mfma_f32_16x16x32_bf16 v[18:21], v[208:211], v[158:161], v[18:21]
	v_mfma_f32_16x16x32_bf16 v[14:17], v[196:199], v[166:169], v[14:17]
	v_mfma_f32_16x16x32_bf16 v[10:13], v[208:211], v[166:169], v[10:13]
	v_mfma_f32_16x16x32_bf16 v[6:9], v[196:199], v[184:187], v[6:9]
	v_mfma_f32_16x16x32_bf16 v[2:5], v[208:211], v[184:187], v[2:5]
	v_mfma_f32_16x16x32_bf16 v[30:33], v[200:203], v[154:157], v[30:33]
	v_mfma_f32_16x16x32_bf16 v[26:29], v[212:215], v[154:157], v[26:29]
	v_mfma_f32_16x16x32_bf16 v[22:25], v[200:203], v[162:165], v[22:25]
	v_mfma_f32_16x16x32_bf16 v[18:21], v[212:215], v[162:165], v[18:21]
	v_mfma_f32_16x16x32_bf16 v[14:17], v[200:203], v[170:173], v[14:17]
	v_mfma_f32_16x16x32_bf16 v[10:13], v[212:215], v[170:173], v[10:13]
	v_mfma_f32_16x16x32_bf16 v[6:9], v[200:203], v[188:191], v[6:9]
	v_mfma_f32_16x16x32_bf16 v[2:5], v[212:215], v[188:191], v[2:5]
	s_setprio 0
	s_add_i32 s7, 0, 0x18000
	v_add_u32_e32 v146, s7, v204
	s_barrier
	ds_read_b128 v[134:137], v146
	ds_read_b128 v[138:141], v146 offset:1024
	ds_read_b128 v[142:145], v146 offset:2048
	ds_read_b128 v[146:149], v146 offset:3072
	s_add_u32 s8, s72, 0x40000
	s_addc_u32 s9, s73, 0
	s_mov_b32 m0, s76
	v_lshl_add_u64 v[196:197], s[8:9], 0, v[0:1]
	ds_read_b128 v[150:153], v206 offset:32768
	ds_read_b128 v[154:157], v206 offset:33792
	ds_read_b128 v[158:161], v206 offset:34816
	ds_read_b128 v[162:165], v206 offset:35840
	ds_read_b128 v[166:169], v206 offset:36864
	ds_read_b128 v[170:173], v206 offset:37888
	ds_read_b128 v[184:187], v206 offset:38912
	ds_read_b128 v[188:191], v206 offset:39936
	global_load_lds_dwordx4 v[196:197], off
	v_lshl_add_u64 v[196:197], s[8:9], 0, v[176:177]
	s_mov_b32 m0, s77
	s_nop 0
	global_load_lds_dwordx4 v[196:197], off
	s_waitcnt lgkmcnt(8)
	s_barrier
	s_waitcnt lgkmcnt(0)
	s_setprio 1
	s_waitcnt lgkmcnt(0)
	v_mfma_f32_16x16x32_bf16 v[126:129], v[134:137], v[150:153], v[126:129]
	v_mfma_f32_16x16x32_bf16 v[122:125], v[142:145], v[150:153], v[122:125]
	v_mfma_f32_16x16x32_bf16 v[118:121], v[134:137], v[158:161], v[118:121]
	v_mfma_f32_16x16x32_bf16 v[114:117], v[142:145], v[158:161], v[114:117]
	v_mfma_f32_16x16x32_bf16 v[110:113], v[134:137], v[166:169], v[110:113]
	v_mfma_f32_16x16x32_bf16 v[106:109], v[142:145], v[166:169], v[106:109]
	v_mfma_f32_16x16x32_bf16 v[102:105], v[134:137], v[184:187], v[102:105]
	v_mfma_f32_16x16x32_bf16 v[98:101], v[142:145], v[184:187], v[98:101]
	v_mfma_f32_16x16x32_bf16 v[126:129], v[138:141], v[154:157], v[126:129]
	v_mfma_f32_16x16x32_bf16 v[122:125], v[146:149], v[154:157], v[122:125]
	v_mfma_f32_16x16x32_bf16 v[118:121], v[138:141], v[162:165], v[118:121]
	v_mfma_f32_16x16x32_bf16 v[114:117], v[146:149], v[162:165], v[114:117]
	v_mfma_f32_16x16x32_bf16 v[110:113], v[138:141], v[170:173], v[110:113]
	v_mfma_f32_16x16x32_bf16 v[106:109], v[146:149], v[170:173], v[106:109]
	v_mfma_f32_16x16x32_bf16 v[102:105], v[138:141], v[188:191], v[102:105]
	v_mfma_f32_16x16x32_bf16 v[98:101], v[146:149], v[188:191], v[98:101]
	s_setprio 0
	s_barrier
	s_add_i32 s10, 0, 0x1c000
	s_add_u32 s8, s54, 0x8000
	s_addc_u32 s9, s55, 0
	s_add_i32 s7, s7, s48
	v_add_u32_e32 v207, s10, v204
	v_lshl_add_u64 v[218:219], s[8:9], 0, v[178:179]
	s_mov_b32 m0, s7
	ds_read_b128 v[196:199], v207
	ds_read_b128 v[200:203], v207 offset:1024
	ds_read_b128 v[208:211], v207 offset:2048
	ds_read_b128 v[212:215], v207 offset:3072
	global_load_lds_dwordx4 v[218:219], off
	v_lshl_add_u64 v[218:219], s[8:9], 0, v[174:175]
	s_add_i32 m0, s7, 0x2000
	s_nop 0
	global_load_lds_dwordx4 v[218:219], off
	s_barrier
	s_waitcnt lgkmcnt(0)
	s_setprio 1
	s_waitcnt lgkmcnt(0)
	v_mfma_f32_16x16x32_bf16 v[94:97], v[196:199], v[150:153], v[94:97]
	v_mfma_f32_16x16x32_bf16 v[90:93], v[208:211], v[150:153], v[90:93]
	v_mfma_f32_16x16x32_bf16 v[86:89], v[196:199], v[158:161], v[86:89]
	v_mfma_f32_16x16x32_bf16 v[82:85], v[208:211], v[158:161], v[82:85]
	v_mfma_f32_16x16x32_bf16 v[78:81], v[196:199], v[166:169], v[78:81]
	v_mfma_f32_16x16x32_bf16 v[74:77], v[208:211], v[166:169], v[74:77]
	v_mfma_f32_16x16x32_bf16 v[70:73], v[196:199], v[184:187], v[70:73]
	v_mfma_f32_16x16x32_bf16 v[66:69], v[208:211], v[184:187], v[66:69]
	v_mfma_f32_16x16x32_bf16 v[94:97], v[200:203], v[154:157], v[94:97]
	v_mfma_f32_16x16x32_bf16 v[90:93], v[212:215], v[154:157], v[90:93]
	v_mfma_f32_16x16x32_bf16 v[86:89], v[200:203], v[162:165], v[86:89]
	v_mfma_f32_16x16x32_bf16 v[82:85], v[212:215], v[162:165], v[82:85]
	v_mfma_f32_16x16x32_bf16 v[78:81], v[200:203], v[170:173], v[78:81]
	v_mfma_f32_16x16x32_bf16 v[74:77], v[212:215], v[170:173], v[74:77]
	v_mfma_f32_16x16x32_bf16 v[70:73], v[200:203], v[188:191], v[70:73]
	v_mfma_f32_16x16x32_bf16 v[66:69], v[212:215], v[188:191], v[66:69]
	s_setprio 0
	s_mov_b32 m0, s79
	v_lshl_add_u64 v[192:193], v[192:193], 0, s[52:53]
	s_barrier
; #define PG8_STAGE(bufoff, gbase, voff) do { _Pragma("unroll") for (int _i = 0; _i < 2; ++_i) \
;         __builtin_amdgcn_global_load_lds((const unsigned*)((const char*)(gbase) + (voff)[_i]), (LAS unsigned*)(lds + (bufoff) + ldsw + _i * 8192), 16, 0, 0); } while (0)
; #define PG8_LDA(dst, b, h) do { _Pragma("unroll") for (int m = 0; m < 4; ++m) _Pragma("unroll") for (int k = 0; k < 2; ++k) dst[m][k] = *(const LAS bf16x8*)(lds + PG8_SA(b, h) + aoff + m * 2048 + k * 1024); } while (0)
; #define PG8_MMA(ai, bj, At, Bt) do { __builtin_amdgcn_s_setprio(1); _Pragma("unroll") for (int m = 0; m < 4; ++m) _Pragma("unroll") for (int n = 0; n < 2; ++n) _Pragma("unroll") for (int k = 0; k < 2; ++k) \
;         acc[ai][bj][m][n] = __builtin_amdgcn_mfma_f32_16x16x32_bf16(Bt[n][k], At[m][k], acc[ai][bj][m][n], 0, 0, 0); __builtin_amdgcn_s_setprio(0); } while (0)
; #define PG8_WAIT_V(n) asm volatile("s_waitcnt vmcnt(" #n ")" ::: "memory")
; #define PG8_WAIT_L(n) asm volatile("s_waitcnt lgkmcnt(" #n ")" ::: "memory")
; #define PG8_BAR __builtin_amdgcn_s_barrier()
; #define PG8_SCHED __builtin_amdgcn_sched_barrier(0)
; template <class Epi, bool DYN = false>
; __device__ __forceinline__ void gemm_phase(LAS unsigned char* lds, const Gemm g, const Epi& E, int wave, unsigned* ctr = nullptr) {
;     ...
;             PG8_BAR; PG8_WAIT_L(0); PG8_MMA(0, 1, At, B1); PG8_BAR;
;             PG8_LDA(At, 1, 1); PG8_STAGE(PG8_SA(1, 0), a3, voffA);
;             PG8_BAR; PG8_WAIT_L(0); PG8_MMA(1, 0, At, B0); PG8_BAR; PG8_SCHED;
;             if (DYN && t == 0) publish((ui + 1) & 1);
;             PG8_STAGE(PG8_SB(1, 1), b3 + hstepB, voffB);
;             PG8_WAIT_V(6); PG8_BAR; PG8_MMA(1, 1, At, B1); PG8_BAR;
;     __device__ __forceinline__ void operator()(AccRef acc, const Unit& u, int wr, int wc, int fr, int fq, const float (&pre)[8]) const {
;     ...
;         f32x4 bv[2][2];
; #pragma unroll
;         for (int bj = 0; bj < 2; ++bj) { bv[bj][0] = *(const GAS f32x4*)(unsigned long long)(bias + col0 + bj * HALF); bv[bj][1] = *(const GAS f32x4*)(unsigned long long)(bias + col0 + bj * HALF + 4); }
; #pragma unroll
;         for (int ai = 0; ai < 2; ++ai) {
;             u32x4 yv[4][2];
; #pragma unroll
;             for (int m = 0; m < 4; ++m)
; #pragma unroll
;                 for (int bj = 0; bj < 2; ++bj) yv[m][bj] = gld16(Y1 + (size_t)(row0 + ai * HALF + m * 16) * 1024 + col0 + bj * HALF);
	ds_read_b128 v[150:153], v206 offset:49152
	ds_read_b128 v[154:157], v206 offset:50176
	ds_read_b128 v[158:161], v206 offset:51200
	ds_read_b128 v[162:165], v206 offset:52224
	ds_read_b128 v[166:169], v206 offset:53248
	ds_read_b128 v[170:173], v206 offset:54272
	ds_read_b128 v[184:187], v206 offset:55296
	ds_read_b128 v[188:191], v206 offset:56320
	global_load_lds_dwordx4 v[192:193], off
	v_lshl_add_u64 v[192:193], v[216:217], 0, s[52:53]
	s_mov_b32 m0, s80
	s_nop 0
	global_load_lds_dwordx4 v[192:193], off
	s_barrier
	s_waitcnt lgkmcnt(0)
	s_setprio 1
	s_waitcnt lgkmcnt(0)
	v_mfma_f32_16x16x32_bf16 v[62:65], v[134:137], v[150:153], v[62:65]
	v_mfma_f32_16x16x32_bf16 v[58:61], v[142:145], v[150:153], v[58:61]
	v_mfma_f32_16x16x32_bf16 v[54:57], v[134:137], v[158:161], v[54:57]
	v_mfma_f32_16x16x32_bf16 v[50:53], v[142:145], v[158:161], v[50:53]
	v_mfma_f32_16x16x32_bf16 v[46:49], v[134:137], v[166:169], v[46:49]
	v_mfma_f32_16x16x32_bf16 v[42:45], v[142:145], v[166:169], v[42:45]
	v_mfma_f32_16x16x32_bf16 v[38:41], v[134:137], v[184:187], v[38:41]
	v_mfma_f32_16x16x32_bf16 v[34:37], v[142:145], v[184:187], v[34:37]
	v_mfma_f32_16x16x32_bf16 v[62:65], v[138:141], v[154:157], v[62:65]
	v_mfma_f32_16x16x32_bf16 v[58:61], v[146:149], v[154:157], v[58:61]
	v_mfma_f32_16x16x32_bf16 v[54:57], v[138:141], v[162:165], v[54:57]
	v_mfma_f32_16x16x32_bf16 v[50:53], v[146:149], v[162:165], v[50:53]
	v_mfma_f32_16x16x32_bf16 v[46:49], v[138:141], v[170:173], v[46:49]
	v_mfma_f32_16x16x32_bf16 v[42:45], v[146:149], v[170:173], v[42:45]
	v_mfma_f32_16x16x32_bf16 v[38:41], v[138:141], v[188:191], v[38:41]
	v_mfma_f32_16x16x32_bf16 v[34:37], v[146:149], v[188:191], v[34:37]
	s_setprio 0
	s_barrier
	s_add_u32 s8, s54, 0xc000
	s_addc_u32 s9, s55, 0
	s_add_i32 s7, s10, s48
	v_lshl_add_u64 v[134:135], s[8:9], 0, v[178:179]
	s_mov_b32 m0, s7
	s_nop 0
	global_load_lds_dwordx4 v[134:135], off
	v_lshl_add_u64 v[134:135], s[8:9], 0, v[174:175]
	s_add_i32 m0, s7, 0x2000
	s_nop 0
	global_load_lds_dwordx4 v[134:135], off
	s_waitcnt vmcnt(6)
	s_barrier
	s_setprio 1
	v_mfma_f32_16x16x32_bf16 v[30:33], v[196:199], v[150:153], v[30:33]
	v_mfma_f32_16x16x32_bf16 v[26:29], v[208:211], v[150:153], v[26:29]
	v_mfma_f32_16x16x32_bf16 v[22:25], v[196:199], v[158:161], v[22:25]
	v_mfma_f32_16x16x32_bf16 v[18:21], v[208:211], v[158:161], v[18:21]
	v_mfma_f32_16x16x32_bf16 v[14:17], v[196:199], v[166:169], v[14:17]
	v_mfma_f32_16x16x32_bf16 v[10:13], v[208:211], v[166:169], v[10:13]
	v_mfma_f32_16x16x32_bf16 v[6:9], v[196:199], v[184:187], v[6:9]
	v_mfma_f32_16x16x32_bf16 v[2:5], v[208:211], v[184:187], v[2:5]
	v_mfma_f32_16x16x32_bf16 v[30:33], v[200:203], v[154:157], v[30:33]
	v_mfma_f32_16x16x32_bf16 v[26:29], v[212:215], v[154:157], v[26:29]
	v_mfma_f32_16x16x32_bf16 v[22:25], v[200:203], v[162:165], v[22:25]
	v_mfma_f32_16x16x32_bf16 v[18:21], v[212:215], v[162:165], v[18:21]
	v_mfma_f32_16x16x32_bf16 v[14:17], v[200:203], v[170:173], v[14:17]
	v_mfma_f32_16x16x32_bf16 v[10:13], v[212:215], v[170:173], v[10:13]
	v_mfma_f32_16x16x32_bf16 v[6:9], v[200:203], v[188:191], v[6:9]
	v_mfma_f32_16x16x32_bf16 v[2:5], v[212:215], v[188:191], v[2:5]
	s_setprio 0
	s_add_i32 s6, s6, 2
	s_add_u32 s4, s4, 0x10000
	s_addc_u32 s5, s5, 0
	s_add_u32 s46, s46, 0x100
	s_addc_u32 s47, s47, 0
	v_lshl_add_u64 v[132:133], v[132:133], 0, s[56:57]
	s_cmp_gt_u32 s6, 13
	v_lshl_add_u64 v[130:131], v[130:131], 0, s[56:57]
	s_barrier
	s_cbranch_scc0 .LBB0_165
	v_lshl_or_b32 v146, s78, 8, v205
	v_ashrrev_i32_e32 v147, 31, v146
	v_lshl_add_u32 v148, s58, 8, v194
	v_lshlrev_b64 v[184:185], 1, v[146:147]
	v_ashrrev_i32_e32 v149, 31, v148
	v_lshl_add_u64 v[186:187], s[42:43], 0, v[184:185]
	v_lshlrev_b64 v[188:189], 11, v[148:149]
	v_lshl_add_u64 v[130:131], v[146:147], 2, s[64:65]
	v_lshl_add_u64 v[146:147], v[186:187], 0, v[188:189]
	global_load_dwordx4 v[142:145], v[130:131], off
	global_load_dwordx4 v[138:141], v[130:131], off offset:16
	global_load_dwordx4 v[134:137], v[130:131], off offset:512
	s_nop 0
	global_load_dwordx4 v[130:133], v[130:131], off offset:528
	s_nop 0
	global_load_dwordx4 v[196:199], v[146:147], off
	global_load_dwordx4 v[170:173], v[146:147], off offset:256
	v_or_b32_e32 v146, 16, v148
	v_ashrrev_i32_e32 v147, 31, v146
	v_lshlrev_b64 v[200:201], 11, v[146:147]
	v_lshl_add_u64 v[146:147], v[186:187], 0, v[200:201]
	global_load_dwordx4 v[166:169], v[146:147], off
	global_load_dwordx4 v[162:165], v[146:147], off offset:256
	v_or_b32_e32 v146, 32, v148
	v_ashrrev_i32_e32 v147, 31, v146
	v_lshlrev_b64 v[192:193], 11, v[146:147]
	v_lshl_add_u64 v[146:147], v[186:187], 0, v[192:193]
	global_load_dwordx4 v[158:161], v[146:147], off
	global_load_dwordx4 v[154:157], v[146:147], off offset:256
	v_or_b32_e32 v146, 48, v148
	v_ashrrev_i32_e32 v147, 31, v146
	v_lshlrev_b64 v[190:191], 11, v[146:147]
	v_lshl_add_u64 v[146:147], v[186:187], 0, v[190:191]
	global_load_dwordx4 v[150:153], v[146:147], off
	s_nop 0
	global_load_dwordx4 v[146:149], v[146:147], off offset:256
	s_mov_b64 s[0:1], 0x40000
	s_andn2_b64 vcc, exec, s[38:39]
	s_waitcnt vmcnt(0)
; __device__ __forceinline__ float sigm(float x) { return __builtin_amdgcn_rcpf(1.0f + __expf(-x)); }
; __device__ __forceinline__ u32x4 pack8(f32x4 v0, f32x4 v1) { u32x4 w; w.x = cvt_pk_bf16(v0[0], v0[1]); w.y = cvt_pk_bf16(v0[2], v0[3]); w.z = cvt_pk_bf16(v1[0], v1[1]); w.w = cvt_pk_bf16(v1[2], v1[3]); return w; }
; __device__ __forceinline__ void unpack8(u32x4 w, f32x4& v0, f32x4& v1) { v0 = (f32x4){bflo(w.x), bfhi(w.x), bflo(w.y), bfhi(w.y)}; v1 = (f32x4){bflo(w.z), bfhi(w.z), bflo(w.w), bfhi(w.w)}; }
;     __device__ __forceinline__ void operator()(AccRef acc, const Unit& u, int wr, int wc, int fr, int fq, const float (&pre)[8]) const {
;     ...
;             for (int m = 0; m < 4; ++m)
; #pragma unroll
;                 for (int bj = 0; bj < 2; ++bj) {
;                     f32x4 y0, y1v; unpack8(yv[m][bj], y0, y1v);
;                     f32x4 v0 = acc[ai][bj][m][0] + bv[bj][0], v1 = acc[ai][bj][m][1] + bv[bj][1];
; #pragma unroll
;                     for (int q = 0; q < 4; ++q) { v0[q] = y0[q] * sigm(v0[q]); v1[q] = y1v[q] * sigm(v1[q]); }
;                     gst16(O + (size_t)(row0 + ai * HALF + m * 16) * 1024 + col0 + bj * HALF, pack8(v0, v1));
;                 }
	v_pk_add_f32 v[202:203], v[124:125], v[140:141]
	v_pk_add_f32 v[208:209], v[122:123], v[138:139]
	v_lshlrev_b32_e32 v207, 16, v196
	v_and_b32_e32 v210, 0xffff0000, v196
	v_lshlrev_b32_e32 v211, 16, v197
	v_and_b32_e32 v212, 0xffff0000, v197
	v_lshlrev_b32_e32 v213, 16, v198
	v_and_b32_e32 v214, 0xffff0000, v198
	v_lshlrev_b32_e32 v215, 16, v199
	v_and_b32_e32 v216, 0xffff0000, v199
	v_pk_add_f32 v[196:197], v[128:129], v[144:145]
	v_pk_add_f32 v[198:199], v[126:127], v[142:143]
	v_mul_f32_e32 v196, 0xbfb8aa3b, v196
	v_mul_f32_e32 v198, 0xbfb8aa3b, v198
	v_exp_f32_e32 v198, v198
	v_exp_f32_e32 v196, v196
	v_mul_f32_e32 v199, 0xbfb8aa3b, v199
	v_exp_f32_e32 v199, v199
	v_add_f32_e32 v198, 1.0, v198
	v_add_f32_e32 v196, 1.0, v196
	v_rcp_f32_e32 v198, v198
	v_rcp_f32_e32 v196, v196
	v_add_f32_e32 v199, 1.0, v199
	v_rcp_f32_e32 v199, v199
	v_mul_f32_e32 v198, v198, v207
	v_mul_f32_e32 v207, 0xbfb8aa3b, v208
	v_mul_f32_e32 v208, 0xbfb8aa3b, v209
	v_mul_f32_e32 v209, v196, v211
	v_mul_f32_e32 v196, 0xbfb8aa3b, v202
	v_exp_f32_e32 v196, v196
	v_mul_f32_e32 v199, v199, v210
	v_exp_f32_e32 v207, v207
	v_exp_f32_e32 v208, v208
	v_add_f32_e32 v196, 1.0, v196
	v_rcp_f32_e32 v196, v196
	v_add_f32_e32 v207, 1.0, v207
	v_add_f32_e32 v208, 1.0, v208
	v_rcp_f32_e32 v207, v207
	v_mul_f32_e32 v210, v196, v215
	v_mul_f32_e32 v196, 0xbfb8aa3b, v197
	v_exp_f32_e32 v196, v196
	v_rcp_f32_e32 v208, v208
	v_mul_f32_e32 v207, v207, v213
	v_lshlrev_b32_e32 v213, 16, v173
	v_add_f32_e32 v196, 1.0, v196
	v_rcp_f32_e32 v196, v196
	v_mul_f32_e32 v208, v208, v214
	v_and_b32_e32 v214, 0xffff0000, v173
	v_mul_f32_e32 v211, v196, v212
	v_mul_f32_e32 v196, 0xbfb8aa3b, v203
	v_exp_f32_e32 v196, v196
	s_nop 0
	v_add_f32_e32 v196, 1.0, v196
	v_rcp_f32_e32 v196, v196
	s_nop 0
	v_mul_f32_e32 v212, v196, v216
	v_lshl_add_u64 v[196:197], s[44:45], 0, v[188:189]
	v_lshl_add_u64 v[202:203], v[196:197], 0, v[184:185]
	v_cvt_pk_bf16_f32 v196, v198, v199
	v_cvt_pk_bf16_f32 v197, v209, v211
	v_cvt_pk_bf16_f32 v198, v207, v208
	v_cvt_pk_bf16_f32 v199, v210, v212
	v_lshlrev_b32_e32 v207, 16, v170
	v_and_b32_e32 v208, 0xffff0000, v170
	v_lshlrev_b32_e32 v209, 16, v171
	v_and_b32_e32 v210, 0xffff0000, v171
	v_lshlrev_b32_e32 v211, 16, v172
	v_and_b32_e32 v212, 0xffff0000, v172
	v_pk_add_f32 v[170:171], v[96:97], v[136:137]
	v_pk_add_f32 v[172:173], v[94:95], v[134:135]
	v_mul_f32_e32 v170, 0xbfb8aa3b, v170
	v_mul_f32_e32 v172, 0xbfb8aa3b, v172
	v_exp_f32_e32 v172, v172
	v_exp_f32_e32 v170, v170
	global_store_dwordx4 v[202:203], v[196:199], off
	v_mul_f32_e32 v173, 0xbfb8aa3b, v173
	v_add_f32_e32 v172, 1.0, v172
	v_add_f32_e32 v170, 1.0, v170
	v_rcp_f32_e32 v172, v172
	v_rcp_f32_e32 v170, v170
	v_pk_add_f32 v[196:197], v[92:93], v[132:133]
	v_pk_add_f32 v[198:199], v[90:91], v[130:131]
	v_mul_f32_e32 v172, v172, v207
	v_mul_f32_e32 v207, v170, v209
	v_mul_f32_e32 v170, 0xbfb8aa3b, v196
	v_exp_f32_e32 v170, v170
	v_mul_f32_e32 v198, 0xbfb8aa3b, v198
	v_mul_f32_e32 v199, 0xbfb8aa3b, v199
	v_exp_f32_e32 v198, v198
	v_add_f32_e32 v170, 1.0, v170
	v_rcp_f32_e32 v170, v170
	v_exp_f32_e32 v173, v173
	v_exp_f32_e32 v199, v199
	v_add_f32_e32 v198, 1.0, v198
	v_mul_f32_e32 v196, v170, v213
	v_mul_f32_e32 v170, 0xbfb8aa3b, v171
	v_exp_f32_e32 v170, v170
	v_add_f32_e32 v173, 1.0, v173
	v_add_f32_e32 v199, 1.0, v199
	v_rcp_f32_e32 v198, v198
	v_add_f32_e32 v170, 1.0, v170
	v_rcp_f32_e32 v170, v170
	v_rcp_f32_e32 v173, v173
	v_rcp_f32_e32 v199, v199
	v_mul_f32_e32 v198, v198, v211
	v_mul_f32_e32 v171, v170, v210
	v_mul_f32_e32 v170, 0xbfb8aa3b, v197
	v_exp_f32_e32 v170, v170
	v_mul_f32_e32 v173, v173, v208
	v_mul_f32_e32 v199, v199, v212
	v_cvt_pk_bf16_f32 v171, v207, v171
	v_add_f32_e32 v170, 1.0, v170
	v_rcp_f32_e32 v170, v170
	v_lshlrev_b32_e32 v207, 16, v169
	v_and_b32_e32 v208, 0xffff0000, v169
	v_mul_f32_e32 v197, v170, v214
	v_cvt_pk_bf16_f32 v170, v172, v173
	v_cvt_pk_bf16_f32 v172, v198, v199
	v_cvt_pk_bf16_f32 v173, v196, v197
	global_store_dwordx4 v[202:203], v[170:173], off offset:256
	v_lshlrev_b32_e32 v196, 16, v166
	v_and_b32_e32 v197, 0xffff0000, v166
	v_lshlrev_b32_e32 v198, 16, v167
	v_and_b32_e32 v199, 0xffff0000, v167
	v_lshlrev_b32_e32 v202, 16, v168
	v_and_b32_e32 v203, 0xffff0000, v168
	v_pk_add_f32 v[166:167], v[120:121], v[144:145]
	v_pk_add_f32 v[168:169], v[118:119], v[142:143]
	v_mul_f32_e32 v166, 0xbfb8aa3b, v166
	v_mul_f32_e32 v168, 0xbfb8aa3b, v168
	v_exp_f32_e32 v168, v168
	v_exp_f32_e32 v166, v166
	v_pk_add_f32 v[170:171], v[116:117], v[140:141]
	v_mul_f32_e32 v169, 0xbfb8aa3b, v169
	v_add_f32_e32 v168, 1.0, v168
	v_add_f32_e32 v166, 1.0, v166
	v_rcp_f32_e32 v168, v168
	v_rcp_f32_e32 v166, v166
	v_exp_f32_e32 v169, v169
	v_pk_add_f32 v[172:173], v[114:115], v[138:139]
	v_mul_f32_e32 v168, v168, v196
	v_mul_f32_e32 v196, v166, v198
	v_mul_f32_e32 v166, 0xbfb8aa3b, v170
	v_exp_f32_e32 v166, v166
	v_add_f32_e32 v169, 1.0, v169
	v_rcp_f32_e32 v169, v169
	v_mul_f32_e32 v172, 0xbfb8aa3b, v172
	v_add_f32_e32 v166, 1.0, v166
	v_rcp_f32_e32 v166, v166
	v_mul_f32_e32 v169, v169, v197
	v_mul_f32_e32 v173, 0xbfb8aa3b, v173
	v_exp_f32_e32 v172, v172
	v_mul_f32_e32 v197, v166, v207
	v_mul_f32_e32 v166, 0xbfb8aa3b, v167
	v_exp_f32_e32 v166, v166
	v_exp_f32_e32 v173, v173
	v_add_f32_e32 v172, 1.0, v172
	v_rcp_f32_e32 v172, v172
	v_add_f32_e32 v166, 1.0, v166
	v_rcp_f32_e32 v166, v166
	v_add_f32_e32 v173, 1.0, v173
	v_rcp_f32_e32 v173, v173
	v_mul_f32_e32 v172, v172, v202
	v_mul_f32_e32 v198, v166, v199
	v_mul_f32_e32 v166, 0xbfb8aa3b, v171
	v_exp_f32_e32 v166, v166
	v_mul_f32_e32 v173, v173, v203
	v_add_f32_e32 v166, 1.0, v166
	v_rcp_f32_e32 v166, v166
	s_nop 0
	v_mul_f32_e32 v199, v166, v208
; __device__ __forceinline__ float sigm(float x) { return __builtin_amdgcn_rcpf(1.0f + __expf(-x)); }
; __device__ __forceinline__ u32x4 pack8(f32x4 v0, f32x4 v1) { u32x4 w; w.x = cvt_pk_bf16(v0[0], v0[1]); w.y = cvt_pk_bf16(v0[2], v0[3]); w.z = cvt_pk_bf16(v1[0], v1[1]); w.w = cvt_pk_bf16(v1[2], v1[3]); return w; }
; __device__ __forceinline__ void unpack8(u32x4 w, f32x4& v0, f32x4& v1) { v0 = (f32x4){bflo(w.x), bfhi(w.x), bflo(w.y), bfhi(w.y)}; v1 = (f32x4){bflo(w.z), bfhi(w.z), bflo(w.w), bfhi(w.w)}; }
;     __device__ __forceinline__ void operator()(AccRef acc, const Unit& u, int wr, int wc, int fr, int fq, const float (&pre)[8]) const {
;     ...
;             for (int m = 0; m < 4; ++m)
; #pragma unroll
;                 for (int bj = 0; bj < 2; ++bj) {
;                     f32x4 y0, y1v; unpack8(yv[m][bj], y0, y1v);
;                     f32x4 v0 = acc[ai][bj][m][0] + bv[bj][0], v1 = acc[ai][bj][m][1] + bv[bj][1];
; #pragma unroll
;                     for (int q = 0; q < 4; ++q) { v0[q] = y0[q] * sigm(v0[q]); v1[q] = y1v[q] * sigm(v1[q]); }
;                     gst16(O + (size_t)(row0 + ai * HALF + m * 16) * 1024 + col0 + bj * HALF, pack8(v0, v1));
;                 }
	v_lshl_add_u64 v[166:167], s[44:45], 0, v[200:201]
	v_lshl_add_u64 v[170:171], v[166:167], 0, v[184:185]
	v_cvt_pk_bf16_f32 v166, v168, v169
	v_cvt_pk_bf16_f32 v167, v196, v198
	v_cvt_pk_bf16_f32 v168, v172, v173
	v_cvt_pk_bf16_f32 v169, v197, v199
	v_lshlrev_b32_e32 v172, 16, v162
	v_and_b32_e32 v173, 0xffff0000, v162
	v_lshlrev_b32_e32 v196, 16, v163
	v_and_b32_e32 v197, 0xffff0000, v163
	v_lshlrev_b32_e32 v198, 16, v164
	v_and_b32_e32 v199, 0xffff0000, v164
	v_lshlrev_b32_e32 v200, 16, v165
	v_and_b32_e32 v201, 0xffff0000, v165
	v_pk_add_f32 v[162:163], v[88:89], v[136:137]
	v_pk_add_f32 v[164:165], v[86:87], v[134:135]
	v_mul_f32_e32 v162, 0xbfb8aa3b, v162
	v_mul_f32_e32 v164, 0xbfb8aa3b, v164
	v_exp_f32_e32 v164, v164
	v_exp_f32_e32 v162, v162
	global_store_dwordx4 v[170:171], v[166:169], off
	v_mul_f32_e32 v165, 0xbfb8aa3b, v165
	v_add_f32_e32 v164, 1.0, v164
	v_add_f32_e32 v162, 1.0, v162
	v_rcp_f32_e32 v164, v164
	v_rcp_f32_e32 v162, v162
	v_pk_add_f32 v[166:167], v[84:85], v[132:133]
	v_pk_add_f32 v[168:169], v[82:83], v[130:131]
	v_mul_f32_e32 v164, v164, v172
	v_mul_f32_e32 v172, v162, v196
	v_mul_f32_e32 v162, 0xbfb8aa3b, v166
	v_exp_f32_e32 v162, v162
	v_mul_f32_e32 v168, 0xbfb8aa3b, v168
	v_mul_f32_e32 v169, 0xbfb8aa3b, v169
	v_exp_f32_e32 v168, v168
	v_add_f32_e32 v162, 1.0, v162
	v_rcp_f32_e32 v162, v162
	v_exp_f32_e32 v165, v165
	v_exp_f32_e32 v169, v169
	v_add_f32_e32 v168, 1.0, v168
	v_mul_f32_e32 v166, v162, v200
	v_mul_f32_e32 v162, 0xbfb8aa3b, v163
	v_exp_f32_e32 v162, v162
	v_add_f32_e32 v165, 1.0, v165
	v_add_f32_e32 v169, 1.0, v169
	v_rcp_f32_e32 v168, v168
	v_add_f32_e32 v162, 1.0, v162
	v_rcp_f32_e32 v162, v162
	v_rcp_f32_e32 v165, v165
	v_rcp_f32_e32 v169, v169
	v_mul_f32_e32 v168, v168, v198
	v_mul_f32_e32 v163, v162, v197
	v_mul_f32_e32 v162, 0xbfb8aa3b, v167
	v_exp_f32_e32 v162, v162
	v_mul_f32_e32 v165, v165, v173
	v_mul_f32_e32 v169, v169, v199
	v_cvt_pk_bf16_f32 v163, v172, v163
	v_add_f32_e32 v162, 1.0, v162
	v_rcp_f32_e32 v162, v162
	v_lshlrev_b32_e32 v172, 16, v161
	v_and_b32_e32 v173, 0xffff0000, v161
	v_mul_f32_e32 v167, v162, v201
	v_cvt_pk_bf16_f32 v162, v164, v165
	v_cvt_pk_bf16_f32 v164, v168, v169
	v_cvt_pk_bf16_f32 v165, v166, v167
	global_store_dwordx4 v[170:171], v[162:165], off offset:256
	v_lshlrev_b32_e32 v166, 16, v158
	v_and_b32_e32 v167, 0xffff0000, v158
	v_lshlrev_b32_e32 v168, 16, v159
	v_and_b32_e32 v169, 0xffff0000, v159
	v_lshlrev_b32_e32 v170, 16, v160
	v_and_b32_e32 v171, 0xffff0000, v160
	v_pk_add_f32 v[158:159], v[112:113], v[144:145]
	v_pk_add_f32 v[160:161], v[110:111], v[142:143]
	v_mul_f32_e32 v158, 0xbfb8aa3b, v158
	v_mul_f32_e32 v160, 0xbfb8aa3b, v160
	v_exp_f32_e32 v160, v160
	v_exp_f32_e32 v158, v158
	v_pk_add_f32 v[162:163], v[108:109], v[140:141]
	v_mul_f32_e32 v161, 0xbfb8aa3b, v161
	v_add_f32_e32 v160, 1.0, v160
	v_add_f32_e32 v158, 1.0, v158
	v_rcp_f32_e32 v160, v160
	v_rcp_f32_e32 v158, v158
	v_exp_f32_e32 v161, v161
	v_pk_add_f32 v[164:165], v[106:107], v[138:139]
	v_mul_f32_e32 v160, v160, v166
	v_mul_f32_e32 v166, v158, v168
	v_mul_f32_e32 v158, 0xbfb8aa3b, v162
	v_exp_f32_e32 v158, v158
	v_add_f32_e32 v161, 1.0, v161
	v_rcp_f32_e32 v161, v161
	v_mul_f32_e32 v164, 0xbfb8aa3b, v164
	v_add_f32_e32 v158, 1.0, v158
	v_rcp_f32_e32 v158, v158
	v_mul_f32_e32 v161, v161, v167
	v_mul_f32_e32 v165, 0xbfb8aa3b, v165
	v_exp_f32_e32 v164, v164
	v_mul_f32_e32 v167, v158, v172
	v_mul_f32_e32 v158, 0xbfb8aa3b, v159
	v_exp_f32_e32 v158, v158
	v_exp_f32_e32 v165, v165
	v_add_f32_e32 v164, 1.0, v164
	v_rcp_f32_e32 v164, v164
	v_add_f32_e32 v158, 1.0, v158
	v_rcp_f32_e32 v158, v158
	v_add_f32_e32 v165, 1.0, v165
	v_rcp_f32_e32 v165, v165
	v_mul_f32_e32 v164, v164, v170
	v_mul_f32_e32 v168, v158, v169
	v_mul_f32_e32 v158, 0xbfb8aa3b, v163
	v_exp_f32_e32 v158, v158
	v_mul_f32_e32 v165, v165, v171
	v_lshlrev_b32_e32 v170, 16, v157
	v_and_b32_e32 v171, 0xffff0000, v157
	v_add_f32_e32 v158, 1.0, v158
	v_rcp_f32_e32 v158, v158
	s_nop 0
	v_mul_f32_e32 v169, v158, v173
	v_lshl_add_u64 v[158:159], s[44:45], 0, v[192:193]
	v_lshl_add_u64 v[162:163], v[158:159], 0, v[184:185]
	v_cvt_pk_bf16_f32 v158, v160, v161
	v_cvt_pk_bf16_f32 v159, v166, v168
	v_cvt_pk_bf16_f32 v160, v164, v165
	v_cvt_pk_bf16_f32 v161, v167, v169
	v_lshlrev_b32_e32 v164, 16, v154
	v_and_b32_e32 v165, 0xffff0000, v154
	v_lshlrev_b32_e32 v166, 16, v155
	v_and_b32_e32 v167, 0xffff0000, v155
	v_lshlrev_b32_e32 v168, 16, v156
	v_and_b32_e32 v169, 0xffff0000, v156
	v_pk_add_f32 v[154:155], v[80:81], v[136:137]
	v_pk_add_f32 v[156:157], v[78:79], v[134:135]
	v_mul_f32_e32 v154, 0xbfb8aa3b, v154
	v_mul_f32_e32 v156, 0xbfb8aa3b, v156
	v_exp_f32_e32 v156, v156
	v_exp_f32_e32 v154, v154
	global_store_dwordx4 v[162:163], v[158:161], off
	v_mul_f32_e32 v157, 0xbfb8aa3b, v157
	v_add_f32_e32 v156, 1.0, v156
	v_add_f32_e32 v154, 1.0, v154
	v_rcp_f32_e32 v156, v156
	v_rcp_f32_e32 v154, v154
	v_pk_add_f32 v[158:159], v[76:77], v[132:133]
	v_pk_add_f32 v[160:161], v[74:75], v[130:131]
	v_mul_f32_e32 v156, v156, v164
	v_mul_f32_e32 v164, v154, v166
	v_mul_f32_e32 v154, 0xbfb8aa3b, v158
	v_exp_f32_e32 v154, v154
	v_mul_f32_e32 v160, 0xbfb8aa3b, v160
	v_mul_f32_e32 v161, 0xbfb8aa3b, v161
	v_exp_f32_e32 v160, v160
	v_add_f32_e32 v154, 1.0, v154
	v_rcp_f32_e32 v154, v154
	v_exp_f32_e32 v157, v157
	v_exp_f32_e32 v161, v161
	v_add_f32_e32 v160, 1.0, v160
	v_mul_f32_e32 v158, v154, v170
	v_mul_f32_e32 v154, 0xbfb8aa3b, v155
	v_exp_f32_e32 v154, v154
	v_add_f32_e32 v157, 1.0, v157
	v_add_f32_e32 v161, 1.0, v161
	v_rcp_f32_e32 v160, v160
	v_add_f32_e32 v154, 1.0, v154
	v_rcp_f32_e32 v154, v154
	v_rcp_f32_e32 v157, v157
	v_rcp_f32_e32 v161, v161
; __device__ __forceinline__ float sigm(float x) { return __builtin_amdgcn_rcpf(1.0f + __expf(-x)); }
; __device__ __forceinline__ u32x4 pack8(f32x4 v0, f32x4 v1) { u32x4 w; w.x = cvt_pk_bf16(v0[0], v0[1]); w.y = cvt_pk_bf16(v0[2], v0[3]); w.z = cvt_pk_bf16(v1[0], v1[1]); w.w = cvt_pk_bf16(v1[2], v1[3]); return w; }
; __device__ __forceinline__ void unpack8(u32x4 w, f32x4& v0, f32x4& v1) { v0 = (f32x4){bflo(w.x), bfhi(w.x), bflo(w.y), bfhi(w.y)}; v1 = (f32x4){bflo(w.z), bfhi(w.z), bflo(w.w), bfhi(w.w)}; }
;     __device__ __forceinline__ void operator()(AccRef acc, const Unit& u, int wr, int wc, int fr, int fq, const float (&pre)[8]) const {
;     ...
;         for (int ai = 0; ai < 2; ++ai) {
;             u32x4 yv[4][2];
; #pragma unroll
;             for (int m = 0; m < 4; ++m)
; #pragma unroll
;                 for (int bj = 0; bj < 2; ++bj) yv[m][bj] = gld16(Y1 + (size_t)(row0 + ai * HALF + m * 16) * 1024 + col0 + bj * HALF);
; #pragma unroll
;             for (int m = 0; m < 4; ++m)
; #pragma unroll
;                 for (int bj = 0; bj < 2; ++bj) {
;                     f32x4 y0, y1v; unpack8(yv[m][bj], y0, y1v);
;                     f32x4 v0 = acc[ai][bj][m][0] + bv[bj][0], v1 = acc[ai][bj][m][1] + bv[bj][1];
; #pragma unroll
;                     for (int q = 0; q < 4; ++q) { v0[q] = y0[q] * sigm(v0[q]); v1[q] = y1v[q] * sigm(v1[q]); }
;                     gst16(O + (size_t)(row0 + ai * HALF + m * 16) * 1024 + col0 + bj * HALF, pack8(v0, v1));
;                 }
	v_mul_f32_e32 v160, v160, v168
	v_mul_f32_e32 v155, v154, v167
	v_mul_f32_e32 v154, 0xbfb8aa3b, v159
	v_exp_f32_e32 v154, v154
	v_mul_f32_e32 v157, v157, v165
	v_mul_f32_e32 v161, v161, v169
	v_cvt_pk_bf16_f32 v155, v164, v155
	v_add_f32_e32 v154, 1.0, v154
	v_rcp_f32_e32 v154, v154
	v_lshlrev_b32_e32 v164, 16, v153
	v_and_b32_e32 v165, 0xffff0000, v153
	v_lshl_add_u64 v[192:193], v[188:189], 0, s[0:1]
	v_mul_f32_e32 v159, v154, v171
	v_cvt_pk_bf16_f32 v154, v156, v157
	v_cvt_pk_bf16_f32 v156, v160, v161
	v_cvt_pk_bf16_f32 v157, v158, v159
	global_store_dwordx4 v[162:163], v[154:157], off offset:256
	v_lshlrev_b32_e32 v158, 16, v150
	v_and_b32_e32 v159, 0xffff0000, v150
	v_lshlrev_b32_e32 v160, 16, v151
	v_and_b32_e32 v161, 0xffff0000, v151
	v_lshlrev_b32_e32 v162, 16, v152
	v_and_b32_e32 v163, 0xffff0000, v152
	v_pk_add_f32 v[150:151], v[104:105], v[144:145]
	v_pk_add_f32 v[152:153], v[102:103], v[142:143]
	v_mul_f32_e32 v150, 0xbfb8aa3b, v150
	v_mul_f32_e32 v152, 0xbfb8aa3b, v152
	v_exp_f32_e32 v152, v152
	v_exp_f32_e32 v150, v150
	v_pk_add_f32 v[154:155], v[100:101], v[140:141]
	v_mul_f32_e32 v153, 0xbfb8aa3b, v153
	v_add_f32_e32 v152, 1.0, v152
	v_add_f32_e32 v150, 1.0, v150
	v_rcp_f32_e32 v152, v152
	v_rcp_f32_e32 v150, v150
	v_exp_f32_e32 v153, v153
	v_pk_add_f32 v[156:157], v[98:99], v[138:139]
	v_mul_f32_e32 v152, v152, v158
	v_mul_f32_e32 v158, v150, v160
	v_mul_f32_e32 v150, 0xbfb8aa3b, v154
	v_exp_f32_e32 v150, v150
	v_add_f32_e32 v153, 1.0, v153
	v_rcp_f32_e32 v153, v153
	v_mul_f32_e32 v156, 0xbfb8aa3b, v156
	v_add_f32_e32 v150, 1.0, v150
	v_rcp_f32_e32 v150, v150
	v_mul_f32_e32 v153, v153, v159
	v_mul_f32_e32 v157, 0xbfb8aa3b, v157
	v_exp_f32_e32 v156, v156
	v_mul_f32_e32 v159, v150, v164
	v_mul_f32_e32 v150, 0xbfb8aa3b, v151
	v_exp_f32_e32 v150, v150
	v_exp_f32_e32 v157, v157
	v_add_f32_e32 v156, 1.0, v156
	v_rcp_f32_e32 v156, v156
	v_add_f32_e32 v150, 1.0, v150
	v_rcp_f32_e32 v150, v150
	v_add_f32_e32 v157, 1.0, v157
	v_rcp_f32_e32 v157, v157
	v_mul_f32_e32 v156, v156, v162
	v_mul_f32_e32 v160, v150, v161
	v_mul_f32_e32 v150, 0xbfb8aa3b, v155
	v_exp_f32_e32 v150, v150
	v_mul_f32_e32 v157, v157, v163
	v_lshlrev_b32_e32 v162, 16, v149
	v_and_b32_e32 v163, 0xffff0000, v149
	v_add_f32_e32 v150, 1.0, v150
	v_rcp_f32_e32 v150, v150
	s_mov_b64 s[0:1], 0x48000
	v_mul_f32_e32 v161, v150, v165
	v_lshl_add_u64 v[150:151], s[44:45], 0, v[190:191]
	v_lshl_add_u64 v[154:155], v[150:151], 0, v[184:185]
	v_cvt_pk_bf16_f32 v150, v152, v153
	v_cvt_pk_bf16_f32 v151, v158, v160
	v_cvt_pk_bf16_f32 v152, v156, v157
	v_cvt_pk_bf16_f32 v153, v159, v161
	v_lshlrev_b32_e32 v156, 16, v146
	v_and_b32_e32 v157, 0xffff0000, v146
	v_lshlrev_b32_e32 v158, 16, v147
	v_and_b32_e32 v159, 0xffff0000, v147
	v_lshlrev_b32_e32 v160, 16, v148
	v_and_b32_e32 v161, 0xffff0000, v148
	v_pk_add_f32 v[146:147], v[72:73], v[136:137]
	v_pk_add_f32 v[148:149], v[70:71], v[134:135]
	v_mul_f32_e32 v146, 0xbfb8aa3b, v146
	v_mul_f32_e32 v148, 0xbfb8aa3b, v148
	v_exp_f32_e32 v148, v148
	v_exp_f32_e32 v146, v146
	global_store_dwordx4 v[154:155], v[150:153], off
	v_mul_f32_e32 v149, 0xbfb8aa3b, v149
	v_add_f32_e32 v148, 1.0, v148
	v_add_f32_e32 v146, 1.0, v146
	v_rcp_f32_e32 v148, v148
	v_rcp_f32_e32 v146, v146
	v_pk_add_f32 v[150:151], v[68:69], v[132:133]
	v_pk_add_f32 v[152:153], v[66:67], v[130:131]
	v_mul_f32_e32 v148, v148, v156
	v_mul_f32_e32 v156, v146, v158
	v_mul_f32_e32 v146, 0xbfb8aa3b, v150
	v_exp_f32_e32 v146, v146
	v_mul_f32_e32 v152, 0xbfb8aa3b, v152
	v_exp_f32_e32 v149, v149
	v_mul_f32_e32 v153, 0xbfb8aa3b, v153
	v_add_f32_e32 v146, 1.0, v146
	v_rcp_f32_e32 v146, v146
	v_exp_f32_e32 v152, v152
	v_exp_f32_e32 v153, v153
	v_add_f32_e32 v149, 1.0, v149
	v_mul_f32_e32 v150, v146, v162
	v_mul_f32_e32 v146, 0xbfb8aa3b, v147
	v_exp_f32_e32 v146, v146
	v_add_f32_e32 v152, 1.0, v152
	v_rcp_f32_e32 v149, v149
	v_add_f32_e32 v153, 1.0, v153
	v_add_f32_e32 v146, 1.0, v146
	v_rcp_f32_e32 v146, v146
	v_rcp_f32_e32 v152, v152
	v_rcp_f32_e32 v153, v153
	v_mul_f32_e32 v149, v149, v157
	v_mul_f32_e32 v147, v146, v159
	v_mul_f32_e32 v146, 0xbfb8aa3b, v151
	v_exp_f32_e32 v146, v146
	v_cvt_pk_bf16_f32 v147, v156, v147
	v_mul_f32_e32 v152, v152, v160
	v_mul_f32_e32 v153, v153, v161
	v_add_f32_e32 v146, 1.0, v146
	v_rcp_f32_e32 v146, v146
	v_lshl_add_u64 v[190:191], v[188:189], 0, s[0:1]
	s_mov_b64 s[0:1], 0x50000
	v_lshl_add_u64 v[172:173], v[188:189], 0, s[0:1]
	v_mul_f32_e32 v151, v146, v163
	v_cvt_pk_bf16_f32 v146, v148, v149
	v_cvt_pk_bf16_f32 v148, v152, v153
	v_cvt_pk_bf16_f32 v149, v150, v151
	global_store_dwordx4 v[154:155], v[146:149], off offset:256
	s_mov_b64 s[0:1], 0x58000
	v_lshl_add_u64 v[170:171], v[188:189], 0, s[0:1]
	v_lshl_add_u64 v[146:147], v[186:187], 0, v[192:193]
	global_load_dwordx4 v[196:199], v[146:147], off
	global_load_dwordx4 v[200:203], v[146:147], off offset:256
	v_lshl_add_u64 v[146:147], v[186:187], 0, v[190:191]
	global_load_dwordx4 v[166:169], v[146:147], off
	global_load_dwordx4 v[162:165], v[146:147], off offset:256
	v_lshl_add_u64 v[146:147], v[186:187], 0, v[172:173]
	global_load_dwordx4 v[158:161], v[146:147], off
	global_load_dwordx4 v[154:157], v[146:147], off offset:256
	v_lshl_add_u64 v[146:147], v[186:187], 0, v[170:171]
	v_pk_add_f32 v[186:187], v[64:65], v[144:145]
	v_pk_add_f32 v[188:189], v[62:63], v[142:143]
	v_mul_f32_e32 v186, 0xbfb8aa3b, v186
	v_mul_f32_e32 v188, 0xbfb8aa3b, v188
	v_exp_f32_e32 v188, v188
	v_exp_f32_e32 v186, v186
	v_mul_f32_e32 v189, 0xbfb8aa3b, v189
	v_exp_f32_e32 v189, v189
	v_add_f32_e32 v188, 1.0, v188
	v_add_f32_e32 v186, 1.0, v186
	v_rcp_f32_e32 v188, v188
	v_rcp_f32_e32 v186, v186
	v_add_f32_e32 v189, 1.0, v189
	v_rcp_f32_e32 v189, v189
	global_load_dwordx4 v[150:153], v[146:147], off
	s_nop 0
	global_load_dwordx4 v[146:149], v[146:147], off offset:256
	s_waitcnt vmcnt(0)
; __device__ __forceinline__ float sigm(float x) { return __builtin_amdgcn_rcpf(1.0f + __expf(-x)); }
; __device__ __forceinline__ u32x4 pack8(f32x4 v0, f32x4 v1) { u32x4 w; w.x = cvt_pk_bf16(v0[0], v0[1]); w.y = cvt_pk_bf16(v0[2], v0[3]); w.z = cvt_pk_bf16(v1[0], v1[1]); w.w = cvt_pk_bf16(v1[2], v1[3]); return w; }
; __device__ __forceinline__ void unpack8(u32x4 w, f32x4& v0, f32x4& v1) { v0 = (f32x4){bflo(w.x), bfhi(w.x), bflo(w.y), bfhi(w.y)}; v1 = (f32x4){bflo(w.z), bfhi(w.z), bflo(w.w), bfhi(w.w)}; }
;     __device__ __forceinline__ void operator()(AccRef acc, const Unit& u, int wr, int wc, int fr, int fq, const float (&pre)[8]) const {
;     ...
;             for (int m = 0; m < 4; ++m)
; #pragma unroll
;                 for (int bj = 0; bj < 2; ++bj) {
;                     f32x4 y0, y1v; unpack8(yv[m][bj], y0, y1v);
;                     f32x4 v0 = acc[ai][bj][m][0] + bv[bj][0], v1 = acc[ai][bj][m][1] + bv[bj][1];
; #pragma unroll
;                     for (int q = 0; q < 4; ++q) { v0[q] = y0[q] * sigm(v0[q]); v1[q] = y1v[q] * sigm(v1[q]); }
;                     gst16(O + (size_t)(row0 + ai * HALF + m * 16) * 1024 + col0 + bj * HALF, pack8(v0, v1));
;                 }
	v_lshlrev_b32_e32 v207, 16, v196
	v_and_b32_e32 v208, 0xffff0000, v196
	v_lshlrev_b32_e32 v209, 16, v197
	v_and_b32_e32 v210, 0xffff0000, v197
	v_pk_add_f32 v[196:197], v[60:61], v[140:141]
	v_mul_f32_e32 v188, v188, v207
	v_mul_f32_e32 v207, v186, v209
	v_mul_f32_e32 v186, 0xbfb8aa3b, v196
	v_exp_f32_e32 v186, v186
	v_lshlrev_b32_e32 v213, 16, v199
	v_lshlrev_b32_e32 v211, 16, v198
	v_and_b32_e32 v212, 0xffff0000, v198
	v_add_f32_e32 v186, 1.0, v186
	v_rcp_f32_e32 v186, v186
	v_and_b32_e32 v214, 0xffff0000, v199
	v_pk_add_f32 v[198:199], v[58:59], v[138:139]
	v_mul_f32_e32 v189, v189, v208
	v_mul_f32_e32 v196, v186, v213
	v_mul_f32_e32 v186, 0xbfb8aa3b, v187
	v_exp_f32_e32 v186, v186
	v_mul_f32_e32 v198, 0xbfb8aa3b, v198
	v_mul_f32_e32 v199, 0xbfb8aa3b, v199
	v_exp_f32_e32 v198, v198
	v_add_f32_e32 v186, 1.0, v186
	v_rcp_f32_e32 v186, v186
	v_exp_f32_e32 v199, v199
	v_add_f32_e32 v198, 1.0, v198
	v_rcp_f32_e32 v198, v198
	v_mul_f32_e32 v208, v186, v210
	v_mul_f32_e32 v186, 0xbfb8aa3b, v197
	v_exp_f32_e32 v186, v186
	v_add_f32_e32 v199, 1.0, v199
	v_rcp_f32_e32 v199, v199
	v_mul_f32_e32 v198, v198, v211
	v_add_f32_e32 v186, 1.0, v186
	v_rcp_f32_e32 v186, v186
	v_mul_f32_e32 v199, v199, v212
	v_lshlrev_b32_e32 v210, 16, v203
	v_lshlrev_b32_e32 v209, 16, v202
	v_mul_f32_e32 v197, v186, v214
	v_lshl_add_u64 v[186:187], s[44:45], 0, v[192:193]
	v_lshl_add_u64 v[192:193], v[186:187], 0, v[184:185]
	v_cvt_pk_bf16_f32 v186, v188, v189
	v_cvt_pk_bf16_f32 v187, v207, v208
	v_cvt_pk_bf16_f32 v188, v198, v199
	v_cvt_pk_bf16_f32 v189, v196, v197
	global_store_dwordx4 v[192:193], v[186:189], off
	v_lshlrev_b32_e32 v207, 16, v200
	v_and_b32_e32 v200, 0xffff0000, v200
	v_pk_add_f32 v[186:187], v[32:33], v[136:137]
	v_pk_add_f32 v[188:189], v[30:31], v[134:135]
	v_mul_f32_e32 v186, 0xbfb8aa3b, v186
	v_mul_f32_e32 v189, 0xbfb8aa3b, v189
	v_exp_f32_e32 v189, v189
	v_exp_f32_e32 v186, v186
	v_lshlrev_b32_e32 v208, 16, v201
	v_pk_add_f32 v[196:197], v[28:29], v[132:133]
	v_add_f32_e32 v189, 1.0, v189
	v_add_f32_e32 v186, 1.0, v186
	v_rcp_f32_e32 v189, v189
	v_rcp_f32_e32 v186, v186
	v_and_b32_e32 v201, 0xffff0000, v201
	v_pk_add_f32 v[198:199], v[26:27], v[130:131]
	v_mul_f32_e32 v189, v189, v200
	v_mul_f32_e32 v200, v186, v208
	v_mul_f32_e32 v186, 0xbfb8aa3b, v196
	v_exp_f32_e32 v186, v186
	v_mul_f32_e32 v188, 0xbfb8aa3b, v188
	v_mul_f32_e32 v198, 0xbfb8aa3b, v198
	v_mul_f32_e32 v199, 0xbfb8aa3b, v199
	v_add_f32_e32 v186, 1.0, v186
	v_rcp_f32_e32 v186, v186
	v_exp_f32_e32 v188, v188
	v_exp_f32_e32 v198, v198
	v_exp_f32_e32 v199, v199
	v_mul_f32_e32 v196, v186, v210
	v_mul_f32_e32 v186, 0xbfb8aa3b, v187
	v_exp_f32_e32 v186, v186
	v_add_f32_e32 v188, 1.0, v188
	v_add_f32_e32 v198, 1.0, v198
	v_add_f32_e32 v199, 1.0, v199
	v_add_f32_e32 v186, 1.0, v186
	v_rcp_f32_e32 v186, v186
	v_rcp_f32_e32 v188, v188
	v_rcp_f32_e32 v198, v198
	v_rcp_f32_e32 v199, v199
	v_mul_f32_e32 v187, v186, v201
	v_mul_f32_e32 v186, 0xbfb8aa3b, v197
	v_exp_f32_e32 v186, v186
	v_and_b32_e32 v202, 0xffff0000, v202
	v_and_b32_e32 v203, 0xffff0000, v203
	v_mul_f32_e32 v188, v188, v207
	v_add_f32_e32 v186, 1.0, v186
	v_rcp_f32_e32 v186, v186
	v_mul_f32_e32 v198, v198, v209
	v_mul_f32_e32 v199, v199, v202
	v_cvt_pk_bf16_f32 v187, v200, v187
	v_mul_f32_e32 v197, v186, v203
	v_cvt_pk_bf16_f32 v186, v188, v189
	v_cvt_pk_bf16_f32 v188, v198, v199
	v_cvt_pk_bf16_f32 v189, v196, v197
	global_store_dwordx4 v[192:193], v[186:189], off offset:256
	v_lshlrev_b32_e32 v192, 16, v166
	v_and_b32_e32 v193, 0xffff0000, v166
	v_lshlrev_b32_e32 v196, 16, v167
	v_and_b32_e32 v197, 0xffff0000, v167
	v_lshlrev_b32_e32 v198, 16, v168
	v_and_b32_e32 v199, 0xffff0000, v168
	v_lshlrev_b32_e32 v200, 16, v169
	v_and_b32_e32 v201, 0xffff0000, v169
	v_pk_add_f32 v[166:167], v[56:57], v[144:145]
	v_pk_add_f32 v[168:169], v[54:55], v[142:143]
	v_mul_f32_e32 v166, 0xbfb8aa3b, v166
	v_mul_f32_e32 v168, 0xbfb8aa3b, v168
	v_exp_f32_e32 v168, v168
	v_exp_f32_e32 v166, v166
	v_pk_add_f32 v[186:187], v[52:53], v[140:141]
	v_mul_f32_e32 v169, 0xbfb8aa3b, v169
	v_add_f32_e32 v168, 1.0, v168
	v_add_f32_e32 v166, 1.0, v166
	v_rcp_f32_e32 v168, v168
	v_rcp_f32_e32 v166, v166
	v_exp_f32_e32 v169, v169
	v_pk_add_f32 v[188:189], v[50:51], v[138:139]
	v_mul_f32_e32 v168, v168, v192
	v_mul_f32_e32 v192, v166, v196
	v_mul_f32_e32 v166, 0xbfb8aa3b, v186
	v_exp_f32_e32 v166, v166
	v_add_f32_e32 v169, 1.0, v169
	v_rcp_f32_e32 v169, v169
	v_mul_f32_e32 v188, 0xbfb8aa3b, v188
	v_add_f32_e32 v166, 1.0, v166
	v_rcp_f32_e32 v166, v166
	v_mul_f32_e32 v169, v169, v193
	v_mul_f32_e32 v189, 0xbfb8aa3b, v189
	v_exp_f32_e32 v188, v188
	v_mul_f32_e32 v193, v166, v200
	v_mul_f32_e32 v166, 0xbfb8aa3b, v167
	v_exp_f32_e32 v166, v166
	v_exp_f32_e32 v189, v189
	v_add_f32_e32 v188, 1.0, v188
	v_rcp_f32_e32 v188, v188
	v_add_f32_e32 v166, 1.0, v166
	v_rcp_f32_e32 v166, v166
	v_add_f32_e32 v189, 1.0, v189
	v_rcp_f32_e32 v189, v189
	v_mul_f32_e32 v188, v188, v198
	v_mul_f32_e32 v196, v166, v197
	v_mul_f32_e32 v166, 0xbfb8aa3b, v187
	v_exp_f32_e32 v166, v166
	v_mul_f32_e32 v189, v189, v199
	v_add_f32_e32 v166, 1.0, v166
	v_rcp_f32_e32 v166, v166
	s_nop 0
	v_mul_f32_e32 v197, v166, v201
	v_lshl_add_u64 v[166:167], s[44:45], 0, v[190:191]
	v_lshl_add_u64 v[186:187], v[166:167], 0, v[184:185]
	v_cvt_pk_bf16_f32 v166, v168, v169
	v_cvt_pk_bf16_f32 v167, v192, v196
	v_cvt_pk_bf16_f32 v168, v188, v189
	v_cvt_pk_bf16_f32 v169, v193, v197
	v_lshlrev_b32_e32 v188, 16, v162
	v_and_b32_e32 v189, 0xffff0000, v162
	v_lshlrev_b32_e32 v190, 16, v163
	v_and_b32_e32 v191, 0xffff0000, v163
	v_lshlrev_b32_e32 v192, 16, v164
	v_and_b32_e32 v193, 0xffff0000, v164
; __device__ __forceinline__ float sigm(float x) { return __builtin_amdgcn_rcpf(1.0f + __expf(-x)); }
; __device__ __forceinline__ u32x4 pack8(f32x4 v0, f32x4 v1) { u32x4 w; w.x = cvt_pk_bf16(v0[0], v0[1]); w.y = cvt_pk_bf16(v0[2], v0[3]); w.z = cvt_pk_bf16(v1[0], v1[1]); w.w = cvt_pk_bf16(v1[2], v1[3]); return w; }
; __device__ __forceinline__ void unpack8(u32x4 w, f32x4& v0, f32x4& v1) { v0 = (f32x4){bflo(w.x), bfhi(w.x), bflo(w.y), bfhi(w.y)}; v1 = (f32x4){bflo(w.z), bfhi(w.z), bflo(w.w), bfhi(w.w)}; }
;     __device__ __forceinline__ void operator()(AccRef acc, const Unit& u, int wr, int wc, int fr, int fq, const float (&pre)[8]) const {
;     ...
;             for (int m = 0; m < 4; ++m)
; #pragma unroll
;                 for (int bj = 0; bj < 2; ++bj) {
;                     f32x4 y0, y1v; unpack8(yv[m][bj], y0, y1v);
;                     f32x4 v0 = acc[ai][bj][m][0] + bv[bj][0], v1 = acc[ai][bj][m][1] + bv[bj][1];
; #pragma unroll
;                     for (int q = 0; q < 4; ++q) { v0[q] = y0[q] * sigm(v0[q]); v1[q] = y1v[q] * sigm(v1[q]); }
;                     gst16(O + (size_t)(row0 + ai * HALF + m * 16) * 1024 + col0 + bj * HALF, pack8(v0, v1));
;                 }
	v_lshlrev_b32_e32 v196, 16, v165
	v_and_b32_e32 v197, 0xffff0000, v165
	v_pk_add_f32 v[162:163], v[24:25], v[136:137]
	v_pk_add_f32 v[164:165], v[22:23], v[134:135]
	v_mul_f32_e32 v162, 0xbfb8aa3b, v162
	v_mul_f32_e32 v164, 0xbfb8aa3b, v164
	v_exp_f32_e32 v164, v164
	v_exp_f32_e32 v162, v162
	global_store_dwordx4 v[186:187], v[166:169], off
	v_mul_f32_e32 v165, 0xbfb8aa3b, v165
	v_add_f32_e32 v164, 1.0, v164
	v_add_f32_e32 v162, 1.0, v162
	v_rcp_f32_e32 v164, v164
	v_rcp_f32_e32 v162, v162
	v_pk_add_f32 v[166:167], v[20:21], v[132:133]
	v_pk_add_f32 v[168:169], v[18:19], v[130:131]
	v_mul_f32_e32 v164, v164, v188
	v_mul_f32_e32 v188, v162, v190
	v_mul_f32_e32 v162, 0xbfb8aa3b, v166
	v_exp_f32_e32 v162, v162
	v_mul_f32_e32 v168, 0xbfb8aa3b, v168
	v_mul_f32_e32 v169, 0xbfb8aa3b, v169
	v_exp_f32_e32 v168, v168
	v_add_f32_e32 v162, 1.0, v162
	v_rcp_f32_e32 v162, v162
	v_exp_f32_e32 v165, v165
	v_exp_f32_e32 v169, v169
	v_add_f32_e32 v168, 1.0, v168
	v_mul_f32_e32 v166, v162, v196
	v_mul_f32_e32 v162, 0xbfb8aa3b, v163
	v_exp_f32_e32 v162, v162
	v_add_f32_e32 v165, 1.0, v165
	v_add_f32_e32 v169, 1.0, v169
	v_rcp_f32_e32 v168, v168
	v_add_f32_e32 v162, 1.0, v162
	v_rcp_f32_e32 v162, v162
	v_rcp_f32_e32 v165, v165
	v_rcp_f32_e32 v169, v169
	v_mul_f32_e32 v168, v168, v192
	v_mul_f32_e32 v163, v162, v191
	v_mul_f32_e32 v162, 0xbfb8aa3b, v167
	v_exp_f32_e32 v162, v162
	v_mul_f32_e32 v165, v165, v189
	v_mul_f32_e32 v169, v169, v193
	v_cvt_pk_bf16_f32 v163, v188, v163
	v_add_f32_e32 v162, 1.0, v162
	v_rcp_f32_e32 v162, v162
	v_lshlrev_b32_e32 v188, 16, v161
	v_and_b32_e32 v189, 0xffff0000, v161
	v_mul_f32_e32 v167, v162, v197
	v_cvt_pk_bf16_f32 v162, v164, v165
	v_cvt_pk_bf16_f32 v164, v168, v169
	v_cvt_pk_bf16_f32 v165, v166, v167
	global_store_dwordx4 v[186:187], v[162:165], off offset:256
	v_lshlrev_b32_e32 v166, 16, v158
	v_and_b32_e32 v167, 0xffff0000, v158
	v_lshlrev_b32_e32 v168, 16, v159
	v_and_b32_e32 v169, 0xffff0000, v159
	v_lshlrev_b32_e32 v186, 16, v160
	v_and_b32_e32 v187, 0xffff0000, v160
	v_pk_add_f32 v[158:159], v[48:49], v[144:145]
	v_pk_add_f32 v[160:161], v[46:47], v[142:143]
	v_mul_f32_e32 v158, 0xbfb8aa3b, v158
	v_mul_f32_e32 v160, 0xbfb8aa3b, v160
	v_exp_f32_e32 v160, v160
	v_exp_f32_e32 v158, v158
	v_pk_add_f32 v[162:163], v[44:45], v[140:141]
	v_mul_f32_e32 v161, 0xbfb8aa3b, v161
	v_add_f32_e32 v160, 1.0, v160
	v_add_f32_e32 v158, 1.0, v158
	v_rcp_f32_e32 v160, v160
	v_rcp_f32_e32 v158, v158
	v_exp_f32_e32 v161, v161
	v_pk_add_f32 v[164:165], v[42:43], v[138:139]
	v_mul_f32_e32 v160, v160, v166
	v_mul_f32_e32 v166, v158, v168
	v_mul_f32_e32 v158, 0xbfb8aa3b, v162
	v_exp_f32_e32 v158, v158
	v_add_f32_e32 v161, 1.0, v161
	v_rcp_f32_e32 v161, v161
	v_mul_f32_e32 v164, 0xbfb8aa3b, v164
	v_add_f32_e32 v158, 1.0, v158
	v_rcp_f32_e32 v158, v158
	v_mul_f32_e32 v161, v161, v167
	v_mul_f32_e32 v165, 0xbfb8aa3b, v165
	v_exp_f32_e32 v164, v164
	v_mul_f32_e32 v167, v158, v188
	v_mul_f32_e32 v158, 0xbfb8aa3b, v159
	v_exp_f32_e32 v158, v158
	v_exp_f32_e32 v165, v165
	v_add_f32_e32 v164, 1.0, v164
	v_rcp_f32_e32 v164, v164
	v_add_f32_e32 v158, 1.0, v158
	v_rcp_f32_e32 v158, v158
	v_add_f32_e32 v165, 1.0, v165
	v_rcp_f32_e32 v165, v165
	v_mul_f32_e32 v164, v164, v186
	v_mul_f32_e32 v168, v158, v169
	v_mul_f32_e32 v158, 0xbfb8aa3b, v163
	v_exp_f32_e32 v158, v158
	v_mul_f32_e32 v165, v165, v187
	v_pk_add_f32 v[138:139], v[34:35], v[138:139]
	v_pk_add_f32 v[142:143], v[38:39], v[142:143]
	v_add_f32_e32 v158, 1.0, v158
	v_rcp_f32_e32 v158, v158
	v_mul_f32_e32 v138, 0xbfb8aa3b, v138
	v_exp_f32_e32 v138, v138
	v_pk_add_f32 v[144:145], v[40:41], v[144:145]
	v_mul_f32_e32 v169, v158, v189
	v_lshl_add_u64 v[158:159], s[44:45], 0, v[172:173]
	v_lshl_add_u64 v[162:163], v[158:159], 0, v[184:185]
	v_cvt_pk_bf16_f32 v158, v160, v161
	v_cvt_pk_bf16_f32 v159, v166, v168
	v_cvt_pk_bf16_f32 v160, v164, v165
	v_cvt_pk_bf16_f32 v161, v167, v169
	v_lshlrev_b32_e32 v164, 16, v154
	v_and_b32_e32 v165, 0xffff0000, v154
	v_lshlrev_b32_e32 v166, 16, v155
	v_and_b32_e32 v167, 0xffff0000, v155
	v_lshlrev_b32_e32 v168, 16, v156
	v_and_b32_e32 v169, 0xffff0000, v156
	v_lshlrev_b32_e32 v172, 16, v157
	v_and_b32_e32 v173, 0xffff0000, v157
	v_pk_add_f32 v[154:155], v[16:17], v[136:137]
	v_pk_add_f32 v[156:157], v[14:15], v[134:135]
	v_mul_f32_e32 v154, 0xbfb8aa3b, v154
	v_mul_f32_e32 v156, 0xbfb8aa3b, v156
	v_exp_f32_e32 v156, v156
	v_exp_f32_e32 v154, v154
	global_store_dwordx4 v[162:163], v[158:161], off
	v_mul_f32_e32 v157, 0xbfb8aa3b, v157
	v_add_f32_e32 v156, 1.0, v156
	v_add_f32_e32 v154, 1.0, v154
	v_rcp_f32_e32 v156, v156
	v_rcp_f32_e32 v154, v154
	v_pk_add_f32 v[158:159], v[12:13], v[132:133]
	v_pk_add_f32 v[160:161], v[10:11], v[130:131]
	v_mul_f32_e32 v156, v156, v164
	v_mul_f32_e32 v164, v154, v166
	v_mul_f32_e32 v154, 0xbfb8aa3b, v158
	v_exp_f32_e32 v154, v154
	v_mul_f32_e32 v160, 0xbfb8aa3b, v160
	v_mul_f32_e32 v161, 0xbfb8aa3b, v161
	v_exp_f32_e32 v160, v160
	v_add_f32_e32 v154, 1.0, v154
	v_rcp_f32_e32 v154, v154
	v_exp_f32_e32 v157, v157
	v_exp_f32_e32 v161, v161
	v_add_f32_e32 v160, 1.0, v160
	v_mul_f32_e32 v158, v154, v172
	v_mul_f32_e32 v154, 0xbfb8aa3b, v155
	v_exp_f32_e32 v154, v154
	v_add_f32_e32 v157, 1.0, v157
	v_add_f32_e32 v161, 1.0, v161
	v_rcp_f32_e32 v160, v160
	v_add_f32_e32 v154, 1.0, v154
	v_rcp_f32_e32 v154, v154
	v_rcp_f32_e32 v157, v157
	v_rcp_f32_e32 v161, v161
	v_add_f32_e32 v138, 1.0, v138
	v_mul_f32_e32 v155, v154, v167
	v_mul_f32_e32 v154, 0xbfb8aa3b, v159
	v_exp_f32_e32 v154, v154
	v_rcp_f32_e32 v138, v138
	v_mul_f32_e32 v160, v160, v168
	v_mul_f32_e32 v157, v157, v165
	v_add_f32_e32 v154, 1.0, v154
	v_rcp_f32_e32 v154, v154
; __device__ __forceinline__ float sigm(float x) { return __builtin_amdgcn_rcpf(1.0f + __expf(-x)); }
; __device__ __forceinline__ u32x4 pack8(f32x4 v0, f32x4 v1) { u32x4 w; w.x = cvt_pk_bf16(v0[0], v0[1]); w.y = cvt_pk_bf16(v0[2], v0[3]); w.z = cvt_pk_bf16(v1[0], v1[1]); w.w = cvt_pk_bf16(v1[2], v1[3]); return w; }
; __device__ __forceinline__ void unpack8(u32x4 w, f32x4& v0, f32x4& v1) { v0 = (f32x4){bflo(w.x), bfhi(w.x), bflo(w.y), bfhi(w.y)}; v1 = (f32x4){bflo(w.z), bfhi(w.z), bflo(w.w), bfhi(w.w)}; }
; template <class Epi, bool DYN = false>
; __device__ __forceinline__ void gemm_phase(LAS unsigned char* lds, const Gemm g, const Epi& E, int wave, unsigned* ctr = nullptr) {
;     ...
;         if (!has_next) break;
; #pragma unroll
;         for (int a = 0; a < 2; ++a)
; #pragma unroll
;             for (int b = 0; b < 2; ++b)
; #pragma unroll
;                 for (int m = 0; m < 4; ++m)
; #pragma unroll
;                     for (int n = 0; n < 2; ++n) acc[a][b][m][n] = (f32x4){0.f, 0.f, 0.f, 0.f};
;         cur = nxt; cA = nA; cB = nB; ++ui;
;     __device__ __forceinline__ void operator()(AccRef acc, const Unit& u, int wr, int wc, int fr, int fq, const float (&pre)[8]) const {
;     ...
;             for (int m = 0; m < 4; ++m)
; #pragma unroll
;                 for (int bj = 0; bj < 2; ++bj) {
;                     f32x4 y0, y1v; unpack8(yv[m][bj], y0, y1v);
;                     f32x4 v0 = acc[ai][bj][m][0] + bv[bj][0], v1 = acc[ai][bj][m][1] + bv[bj][1];
; #pragma unroll
;                     for (int q = 0; q < 4; ++q) { v0[q] = y0[q] * sigm(v0[q]); v1[q] = y1v[q] * sigm(v1[q]); }
;                     gst16(O + (size_t)(row0 + ai * HALF + m * 16) * 1024 + col0 + bj * HALF, pack8(v0, v1));
;                 }
	v_mul_f32_e32 v161, v161, v169
	v_cvt_pk_bf16_f32 v155, v164, v155
	v_pk_add_f32 v[140:141], v[36:37], v[140:141]
	v_mul_f32_e32 v159, v154, v173
	v_cvt_pk_bf16_f32 v154, v156, v157
	v_cvt_pk_bf16_f32 v156, v160, v161
	v_cvt_pk_bf16_f32 v157, v158, v159
	global_store_dwordx4 v[162:163], v[154:157], off offset:256
	v_mul_f32_e32 v142, 0xbfb8aa3b, v142
	v_exp_f32_e32 v142, v142
	v_lshlrev_b32_e32 v156, 16, v152
	v_mul_f32_e32 v156, v138, v156
	v_mul_f32_e32 v138, 0xbfb8aa3b, v143
	v_exp_f32_e32 v138, v138
	v_lshlrev_b32_e32 v154, 16, v150
	v_and_b32_e32 v150, 0xffff0000, v150
	v_and_b32_e32 v152, 0xffff0000, v152
	v_add_f32_e32 v138, 1.0, v138
	v_rcp_f32_e32 v138, v138
	v_lshlrev_b32_e32 v155, 16, v151
	v_lshlrev_b32_e32 v157, 16, v153
	v_and_b32_e32 v151, 0xffff0000, v151
	v_mul_f32_e32 v150, v138, v150
	v_mul_f32_e32 v138, 0xbfb8aa3b, v139
	v_exp_f32_e32 v138, v138
	v_pk_add_f32 v[134:135], v[6:7], v[134:135]
	v_pk_add_f32 v[132:133], v[4:5], v[132:133]
	v_pk_add_f32 v[130:131], v[2:3], v[130:131]
	v_add_f32_e32 v138, 1.0, v138
	v_rcp_f32_e32 v138, v138
	v_mul_f32_e32 v134, 0xbfb8aa3b, v134
	v_mul_f32_e32 v130, 0xbfb8aa3b, v130
	v_mul_f32_e32 v131, 0xbfb8aa3b, v131
	v_mul_f32_e32 v152, v138, v152
	v_mul_f32_e32 v138, 0xbfb8aa3b, v144
	v_exp_f32_e32 v138, v138
	v_mul_f32_e32 v132, 0xbfb8aa3b, v132
	v_exp_f32_e32 v134, v134
	v_exp_f32_e32 v130, v130
	v_add_f32_e32 v138, 1.0, v138
	v_rcp_f32_e32 v138, v138
	v_exp_f32_e32 v131, v131
	v_exp_f32_e32 v132, v132
	v_add_f32_e32 v142, 1.0, v142
	v_mul_f32_e32 v144, v138, v155
	v_mul_f32_e32 v138, 0xbfb8aa3b, v140
	v_exp_f32_e32 v138, v138
	v_rcp_f32_e32 v142, v142
	v_add_f32_e32 v134, 1.0, v134
	v_add_f32_e32 v130, 1.0, v130
	v_add_f32_e32 v138, 1.0, v138
	v_rcp_f32_e32 v138, v138
	v_add_f32_e32 v131, 1.0, v131
	v_add_f32_e32 v132, 1.0, v132
	v_and_b32_e32 v153, 0xffff0000, v153
	v_mul_f32_e32 v155, v138, v157
	v_mul_f32_e32 v138, 0xbfb8aa3b, v145
	v_exp_f32_e32 v138, v138
	v_rcp_f32_e32 v134, v134
	v_rcp_f32_e32 v130, v130
	v_rcp_f32_e32 v131, v131
	v_add_f32_e32 v138, 1.0, v138
	v_rcp_f32_e32 v138, v138
	v_rcp_f32_e32 v132, v132
	v_mul_f32_e32 v154, v142, v154
	v_and_b32_e32 v145, 0xffff0000, v148
	v_mul_f32_e32 v140, v138, v151
	v_mul_f32_e32 v138, 0xbfb8aa3b, v141
	v_exp_f32_e32 v138, v138
	v_pk_add_f32 v[136:137], v[8:9], v[136:137]
	v_mul_f32_e32 v133, 0xbfb8aa3b, v133
	v_exp_f32_e32 v133, v133
	v_add_f32_e32 v138, 1.0, v138
	v_rcp_f32_e32 v138, v138
	v_add_f32_e32 v133, 1.0, v133
	v_rcp_f32_e32 v133, v133
	v_mul_f32_e32 v141, v138, v153
	v_lshl_add_u64 v[138:139], s[44:45], 0, v[170:171]
	v_lshl_add_u64 v[142:143], v[138:139], 0, v[184:185]
	v_cvt_pk_bf16_f32 v138, v154, v150
	v_cvt_pk_bf16_f32 v139, v144, v140
	v_cvt_pk_bf16_f32 v140, v156, v152
	v_cvt_pk_bf16_f32 v141, v155, v141
	global_store_dwordx4 v[142:143], v[138:141], off
	v_lshlrev_b32_e32 v144, 16, v148
	s_nop 0
	v_lshlrev_b32_e32 v138, 16, v146
	v_and_b32_e32 v139, 0xffff0000, v146
	v_lshlrev_b32_e32 v146, 16, v149
	v_mul_f32_e32 v134, v134, v138
	v_mul_f32_e32 v138, v130, v144
	v_mul_f32_e32 v130, 0xbfb8aa3b, v135
	v_mul_f32_e32 v135, v131, v145
	v_mul_f32_e32 v131, 0xbfb8aa3b, v136
	v_mul_f32_e32 v136, v132, v146
	v_mul_f32_e32 v132, 0xbfb8aa3b, v137
	v_exp_f32_e32 v130, v130
	v_exp_f32_e32 v131, v131
	v_exp_f32_e32 v132, v132
	v_lshlrev_b32_e32 v140, 16, v147
	v_add_f32_e32 v130, 1.0, v130
	v_add_f32_e32 v131, 1.0, v131
	v_add_f32_e32 v132, 1.0, v132
	v_rcp_f32_e32 v130, v130
	v_rcp_f32_e32 v131, v131
	v_rcp_f32_e32 v132, v132
	v_and_b32_e32 v141, 0xffff0000, v147
	v_and_b32_e32 v147, 0xffff0000, v149
	v_mul_f32_e32 v130, v130, v139
	v_mul_f32_e32 v131, v131, v140
	v_mul_f32_e32 v132, v132, v141
	v_mul_f32_e32 v133, v133, v147
	v_cvt_pk_bf16_f32 v130, v134, v130
	v_cvt_pk_bf16_f32 v131, v131, v132
	v_cvt_pk_bf16_f32 v132, v138, v135
	v_cvt_pk_bf16_f32 v133, v136, v133
	global_store_dwordx4 v[142:143], v[130:133], off offset:256
	s_cbranch_vccnz .LBB0_161
	v_mov_b32_e32 v2, 0
	s_mov_b32 s78, s40
	s_mov_b32 s58, s66
	s_mov_b64 s[60:61], s[70:71]
	s_mov_b64 s[62:63], s[68:69]
	s_mov_b32 s81, s82
	v_mov_b32_e32 v3, v2
	v_mov_b64_e32 v[4:5], 0
	v_mov_b64_e32 v[6:7], 0
	v_mov_b64_e32 v[8:9], 0
	v_mov_b64_e32 v[10:11], 0
	v_mov_b64_e32 v[12:13], 0
	v_mov_b64_e32 v[14:15], 0
	v_mov_b64_e32 v[16:17], 0
	v_mov_b64_e32 v[18:19], 0
	v_mov_b64_e32 v[20:21], 0
	v_mov_b64_e32 v[22:23], 0
	v_mov_b64_e32 v[24:25], 0
	v_mov_b64_e32 v[26:27], 0
	v_mov_b64_e32 v[28:29], 0
	v_mov_b64_e32 v[30:31], 0
	v_mov_b64_e32 v[32:33], 0
	v_mov_b64_e32 v[34:35], 0
	v_mov_b64_e32 v[36:37], 0
	v_mov_b64_e32 v[38:39], 0
	v_mov_b64_e32 v[40:41], 0
	v_mov_b64_e32 v[42:43], 0
	v_mov_b64_e32 v[44:45], 0
	v_mov_b64_e32 v[46:47], 0
	v_mov_b64_e32 v[48:49], 0
	v_mov_b64_e32 v[50:51], 0
	v_mov_b64_e32 v[52:53], 0
	v_mov_b64_e32 v[54:55], 0
	v_mov_b64_e32 v[56:57], 0
	v_mov_b64_e32 v[58:59], 0
	v_mov_b64_e32 v[60:61], 0
	v_mov_b64_e32 v[62:63], 0
	v_mov_b64_e32 v[64:65], 0
	v_mov_b64_e32 v[66:67], 0
	v_mov_b64_e32 v[68:69], 0
	v_mov_b64_e32 v[70:71], 0
	v_mov_b64_e32 v[72:73], 0
	v_mov_b64_e32 v[74:75], 0
	v_mov_b64_e32 v[76:77], 0
	v_mov_b64_e32 v[78:79], 0
	v_mov_b64_e32 v[80:81], 0
	v_mov_b64_e32 v[82:83], 0
	v_mov_b64_e32 v[84:85], 0
	v_mov_b64_e32 v[86:87], 0
	v_mov_b64_e32 v[88:89], 0
	v_mov_b64_e32 v[90:91], 0
	v_mov_b64_e32 v[92:93], 0
	v_mov_b64_e32 v[94:95], 0
	v_mov_b64_e32 v[96:97], 0
	v_mov_b64_e32 v[98:99], 0
	v_mov_b64_e32 v[100:101], 0
	v_mov_b64_e32 v[102:103], 0
	v_mov_b64_e32 v[104:105], 0
	v_mov_b64_e32 v[106:107], 0
	v_mov_b64_e32 v[108:109], 0
	v_mov_b64_e32 v[110:111], 0
	v_mov_b64_e32 v[112:113], 0
	v_mov_b64_e32 v[114:115], 0
	v_mov_b64_e32 v[116:117], 0
	v_mov_b64_e32 v[118:119], 0
	v_mov_b64_e32 v[120:121], 0
	v_mov_b64_e32 v[122:123], 0
	v_mov_b64_e32 v[124:125], 0
	v_mov_b64_e32 v[126:127], 0
	v_mov_b64_e32 v[128:129], 0
	s_branch .LBB0_161

; #define PG8_STAGE(bufoff, gbase, voff) do { _Pragma("unroll") for (int _i = 0; _i < 2; ++_i) \
;         __builtin_amdgcn_global_load_lds((const unsigned*)((const char*)(gbase) + (voff)[_i]), (LAS unsigned*)(lds + (bufoff) + ldsw + _i * 8192), 16, 0, 0); } while (0)
; #define PG8_WAIT_V(n) asm volatile("s_waitcnt vmcnt(" #n ")" ::: "memory")
; #define PG8_BAR __builtin_amdgcn_s_barrier()
; template <class Epi, bool DYN = false>
; __device__ __forceinline__ void gemm_phase(LAS unsigned char* lds, const Gemm g, const Epi& E, int wave, unsigned* ctr = nullptr) {
;     ...
;     f32x4 acc[2][2][4][2];
; #pragma unroll
;     for (int a = 0; a < 2; ++a)
; #pragma unroll
;         for (int b = 0; b < 2; ++b)
; #pragma unroll
;             for (int m = 0; m < 4; ++m)
; #pragma unroll
;                 for (int n = 0; n < 2; ++n) acc[a][b][m][n] = (f32x4){0.f, 0.f, 0.f, 0.f};
;     bf16x8 At[4][2], B0[2][2], B1[2][2];
;     const char* cA = (const char*)(g.A + (size_t)cur.b * g.sA) + (size_t)cur.pm * tstepA; const char* cB = (const char*)(g.Bt + (size_t)cur.b * g.sB) + (size_t)cur.pn * tstepB;
;     float pre[8];
;     E.prefetch(pre, cur, wr, fr);
;     PG8_STAGE(PG8_SB(0, 0), cB, voffB); PG8_STAGE(PG8_SA(0, 0), cA, voffA); PG8_STAGE(PG8_SB(0, 1), cB + hstepB, voffB); PG8_STAGE(PG8_SA(0, 1), cA + hstepA, voffA);
;     if (wr == 1) PG8_BAR;
;     PG8_WAIT_V(4); PG8_BAR;
;     PG8_STAGE(PG8_SB(1, 0), cB + kstepB, voffB); PG8_STAGE(PG8_SA(1, 0), cA + kstepA, voffA); PG8_STAGE(PG8_SB(1, 1), cB + hstepB + kstepB, voffB);
;     PG8_WAIT_V(6); PG8_BAR;
;     for (;;) {
;         bool has_next = DYN ? false : S.next(ui + 1, nxt);
;         const char* nA = has_next ? (const char*)(g.A + (size_t)nxt.b * g.sA) + (size_t)nxt.pm * tstepA : cA; const char* nB = has_next ? (const char*)(g.Bt + (size_t)nxt.b * g.sB) + (size_t)nxt.pn * tstepB : cB;
.LBB0_182:
	s_lshl_b64 s[0:1], s[58:59], 18
	s_add_u32 s2, s18, s0
	v_cmp_lt_i64_e32 vcc, s[44:45], v[248:249]
	s_addc_u32 s3, s19, s1
	s_and_b64 s[0:1], vcc, exec
	s_cselect_b32 s45, s3, s61
	s_cselect_b32 s44, s2, s60
	s_add_u32 s0, s60, 0x100
	s_addc_u32 s1, s61, 0
	s_add_u32 s60, s62, 0x20080
	v_mov_b32_e32 v2, 0
	s_addc_u32 s61, s63, 0
	s_mov_b32 s2, -2
	v_mov_b32_e32 v3, v2
	v_mov_b64_e32 v[4:5], 0
	v_mov_b64_e32 v[6:7], 0
	v_mov_b64_e32 v[8:9], 0
	v_mov_b64_e32 v[18:19], 0
	v_mov_b64_e32 v[20:21], 0
	v_mov_b64_e32 v[22:23], 0
	v_mov_b64_e32 v[24:25], 0
	v_mov_b64_e32 v[34:35], 0
	v_mov_b64_e32 v[36:37], 0
	v_mov_b64_e32 v[38:39], 0
	v_mov_b64_e32 v[40:41], 0
	v_mov_b64_e32 v[50:51], 0
	v_mov_b64_e32 v[52:53], 0
	v_mov_b64_e32 v[54:55], 0
	v_mov_b64_e32 v[56:57], 0
	v_mov_b64_e32 v[10:11], 0
	v_mov_b64_e32 v[12:13], 0
	v_mov_b64_e32 v[14:15], 0
	v_mov_b64_e32 v[16:17], 0
	v_mov_b64_e32 v[26:27], 0
	v_mov_b64_e32 v[28:29], 0
	v_mov_b64_e32 v[30:31], 0
	v_mov_b64_e32 v[32:33], 0
	v_mov_b64_e32 v[42:43], 0
	v_mov_b64_e32 v[44:45], 0
	v_mov_b64_e32 v[46:47], 0
	v_mov_b64_e32 v[48:49], 0
	v_mov_b64_e32 v[58:59], 0
	v_mov_b64_e32 v[60:61], 0
	v_mov_b64_e32 v[62:63], 0
	v_mov_b64_e32 v[64:65], 0
	v_mov_b64_e32 v[66:67], 0
	v_mov_b64_e32 v[68:69], 0
	v_mov_b64_e32 v[70:71], 0
	v_mov_b64_e32 v[72:73], 0
	v_mov_b64_e32 v[82:83], 0
	v_mov_b64_e32 v[84:85], 0
	v_mov_b64_e32 v[86:87], 0
	v_mov_b64_e32 v[88:89], 0
	v_mov_b64_e32 v[98:99], 0
	v_mov_b64_e32 v[100:101], 0
	v_mov_b64_e32 v[102:103], 0
	v_mov_b64_e32 v[104:105], 0
	v_mov_b64_e32 v[114:115], 0
	v_mov_b64_e32 v[116:117], 0
	v_mov_b64_e32 v[118:119], 0
	v_mov_b64_e32 v[120:121], 0
	v_mov_b64_e32 v[74:75], 0
	v_mov_b64_e32 v[76:77], 0
	v_mov_b64_e32 v[78:79], 0
	v_mov_b64_e32 v[80:81], 0
	v_mov_b64_e32 v[90:91], 0
	v_mov_b64_e32 v[92:93], 0
	v_mov_b64_e32 v[94:95], 0
	v_mov_b64_e32 v[96:97], 0
	v_mov_b64_e32 v[106:107], 0
	v_mov_b64_e32 v[108:109], 0
	v_mov_b64_e32 v[110:111], 0
	v_mov_b64_e32 v[112:113], 0
	v_mov_b64_e32 v[122:123], 0
	v_mov_b64_e32 v[124:125], 0
	v_mov_b64_e32 v[126:127], 0
	v_mov_b64_e32 v[128:129], 0

; #define PG8_STAGE(bufoff, gbase, voff) do { _Pragma("unroll") for (int _i = 0; _i < 2; ++_i) \
;         __builtin_amdgcn_global_load_lds((const unsigned*)((const char*)(gbase) + (voff)[_i]), (LAS unsigned*)(lds + (bufoff) + ldsw + _i * 8192), 16, 0, 0); } while (0)
; #define PG8_WAIT_V(n) asm volatile("s_waitcnt vmcnt(" #n ")" ::: "memory")
; #define PG8_BAR __builtin_amdgcn_s_barrier()
; template <class Epi, bool DYN = false>
; __device__ __forceinline__ void gemm_phase(LAS unsigned char* lds, const Gemm g, const Epi& E, int wave, unsigned* ctr = nullptr) {
;     ...
;     f32x4 acc[2][2][4][2];
; #pragma unroll
;     for (int a = 0; a < 2; ++a)
; #pragma unroll
;         for (int b = 0; b < 2; ++b)
; #pragma unroll
;             for (int m = 0; m < 4; ++m)
; #pragma unroll
;                 for (int n = 0; n < 2; ++n) acc[a][b][m][n] = (f32x4){0.f, 0.f, 0.f, 0.f};
;     bf16x8 At[4][2], B0[2][2], B1[2][2];
;     const char* cA = (const char*)(g.A + (size_t)cur.b * g.sA) + (size_t)cur.pm * tstepA; const char* cB = (const char*)(g.Bt + (size_t)cur.b * g.sB) + (size_t)cur.pn * tstepB;
;     float pre[8];
;     E.prefetch(pre, cur, wr, fr);
;     PG8_STAGE(PG8_SB(0, 0), cB, voffB); PG8_STAGE(PG8_SA(0, 0), cA, voffA); PG8_STAGE(PG8_SB(0, 1), cB + hstepB, voffB); PG8_STAGE(PG8_SA(0, 1), cA + hstepA, voffA);
;     if (wr == 1) PG8_BAR;
;     PG8_WAIT_V(4); PG8_BAR;
;     PG8_STAGE(PG8_SB(1, 0), cB + kstepB, voffB); PG8_STAGE(PG8_SA(1, 0), cA + kstepA, voffA); PG8_STAGE(PG8_SB(1, 1), cB + hstepB + kstepB, voffB);
;     PG8_WAIT_V(6); PG8_BAR;
;     for (;;) {
;         bool has_next = DYN ? false : S.next(ui + 1, nxt);
;         const char* nA = has_next ? (const char*)(g.A + (size_t)nxt.b * g.sA) + (size_t)nxt.pm * tstepA : cA; const char* nB = has_next ? (const char*)(g.Bt + (size_t)nxt.b * g.sB) + (size_t)nxt.pn * tstepB : cB;
.LBB0_278:
	s_lshl_b64 s[0:1], s[44:45], 17
	s_add_u32 s8, s26, s0
	v_cmp_lt_i64_e32 vcc, s[60:61], v[248:249]
	s_addc_u32 s9, s27, s1
	s_and_b64 s[0:1], vcc, exec
	v_mov_b32_e32 v2, 0
	s_cselect_b32 s61, s9, s43
	s_cselect_b32 s60, s8, s42
	s_mov_b32 s0, 0
	s_mov_b64 s[62:63], -1
	s_mov_b64 s[64:65], 0
	v_mov_b32_e32 v3, v2
	v_mov_b64_e32 v[4:5], 0
	v_mov_b64_e32 v[6:7], 0
	v_mov_b64_e32 v[8:9], 0
	v_mov_b64_e32 v[10:11], 0
	v_mov_b64_e32 v[12:13], 0
	v_mov_b64_e32 v[14:15], 0
	v_mov_b64_e32 v[16:17], 0
	v_mov_b64_e32 v[26:27], 0
	v_mov_b64_e32 v[28:29], 0
	v_mov_b64_e32 v[30:31], 0
	v_mov_b64_e32 v[32:33], 0
	v_mov_b64_e32 v[42:43], 0
	v_mov_b64_e32 v[44:45], 0
	v_mov_b64_e32 v[46:47], 0
	v_mov_b64_e32 v[48:49], 0
	v_mov_b64_e32 v[18:19], 0
	v_mov_b64_e32 v[20:21], 0
	v_mov_b64_e32 v[22:23], 0
	v_mov_b64_e32 v[24:25], 0
	v_mov_b64_e32 v[34:35], 0
	v_mov_b64_e32 v[36:37], 0
	v_mov_b64_e32 v[38:39], 0
	v_mov_b64_e32 v[40:41], 0
	v_mov_b64_e32 v[50:51], 0
	v_mov_b64_e32 v[52:53], 0
	v_mov_b64_e32 v[54:55], 0
	v_mov_b64_e32 v[56:57], 0
	v_mov_b64_e32 v[58:59], 0
	v_mov_b64_e32 v[60:61], 0
	v_mov_b64_e32 v[62:63], 0
	v_mov_b64_e32 v[64:65], 0
	v_mov_b64_e32 v[66:67], 0
	v_mov_b64_e32 v[68:69], 0
	v_mov_b64_e32 v[70:71], 0
	v_mov_b64_e32 v[72:73], 0
	v_mov_b64_e32 v[74:75], 0
	v_mov_b64_e32 v[76:77], 0
	v_mov_b64_e32 v[78:79], 0
	v_mov_b64_e32 v[80:81], 0
	v_mov_b64_e32 v[86:87], 0
	v_mov_b64_e32 v[88:89], 0
	v_mov_b64_e32 v[94:95], 0
	v_mov_b64_e32 v[96:97], 0
	v_mov_b64_e32 v[102:103], 0
	v_mov_b64_e32 v[104:105], 0
	v_mov_b64_e32 v[110:111], 0
	v_mov_b64_e32 v[112:113], 0
	v_mov_b64_e32 v[82:83], 0
	v_mov_b64_e32 v[84:85], 0
	v_mov_b64_e32 v[90:91], 0
	v_mov_b64_e32 v[92:93], 0
	v_mov_b64_e32 v[98:99], 0
	v_mov_b64_e32 v[100:101], 0
	v_mov_b64_e32 v[106:107], 0
	v_mov_b64_e32 v[108:109], 0
	v_mov_b64_e32 v[114:115], 0
	v_mov_b64_e32 v[116:117], 0
	v_mov_b64_e32 v[118:119], 0
	v_mov_b64_e32 v[120:121], 0
	v_mov_b64_e32 v[122:123], 0
	v_mov_b64_e32 v[124:125], 0
	v_mov_b64_e32 v[126:127], 0
	v_mov_b64_e32 v[128:129], 0

; template <class Epi, bool DYN = false>
; __device__ __forceinline__ void gemm_phase(LAS unsigned char* lds, const Gemm g, const Epi& E, int wave, unsigned* ctr = nullptr) {
;     ...
;     auto rng_cnt = [&](int x) { const int q = S.nwg / NXCD, r = S.nwg % NXCD; return q + (x < r ? 1 : 0); };
;     auto rng_start = [&](int x) { const int q = S.nwg / NXCD, r = S.nwg % NXCD; return x < r ? x * (q + 1) : r * (q + 1) + (x - r) * q; };
;     auto decode = [&](int wgid, Unit& u) { const int nig = WGM * S.nN, gid = wgid / nig, fm = gid * WGM, gsz = (S.nM - fm) < WGM ? (S.nM - fm) : WGM; u.pm = fm + ((wgid % nig) % gsz); u.pn = (wgid % nig) / gsz; u.b = 0; };
;     auto issue = [&]() { if (tid == 0) ticket = (int)__hip_atomic_fetch_add(ctr + xcd * 16, 1u, __ATOMIC_RELAXED, __HIP_MEMORY_SCOPE_AGENT); };
;     auto publish = [&](int si) { if (tid == 0) { int wg = -1;
;             if (ticket < rng_cnt(xcd)) wg = rng_start(xcd) + ticket;
;             else { for (int k = 1; k < 8; ++k) { const int x2 = (xcd + k) & 7; const int t2 = (int)__hip_atomic_fetch_add(ctr + x2 * 16, 1u, __ATOMIC_RELAXED, __HIP_MEMORY_SCOPE_AGENT); if (t2 < rng_cnt(x2)) { wg = rng_start(x2) + t2; break; } } }
;             slot[si] = wg; } };
;     if (DYN) { issue(); publish(0); __syncthreads(); const int w0 = __builtin_amdgcn_readfirstlane(slot[0]); if (w0 < 0) return; decode(w0, cur); issue(); }
;     else if (!S.next(0, cur)) return;
;     f32x4 acc[2][2][4][2];
; #pragma unroll
;     for (int a = 0; a < 2; ++a)
; #pragma unroll
;         for (int b = 0; b < 2; ++b)
; #pragma unroll
;             for (int m = 0; m < 4; ++m)
; #pragma unroll
;                 for (int n = 0; n < 2; ++n) acc[a][b][m][n] = (f32x4){0.f, 0.f, 0.f, 0.f};
;     bf16x8 At[4][2], B0[2][2], B1[2][2];
;     const char* cA = (const char*)(g.A + (size_t)cur.b * g.sA) + (size_t)cur.pm * tstepA; const char* cB = (const char*)(g.Bt + (size_t)cur.b * g.sB) + (size_t)cur.pn * tstepB;
;     float pre[8];
;     E.prefetch(pre, cur, wr, fr);
;     PG8_STAGE(PG8_SB(0, 0), cB, voffB); PG8_STAGE(PG8_SA(0, 0), cA, voffA); PG8_STAGE(PG8_SB(0, 1), cB + hstepB, voffB); PG8_STAGE(PG8_SA(0, 1), cA + hstepA, voffA);
;     if (wr == 1) PG8_BAR;
;     PG8_WAIT_V(4); PG8_BAR;
;     PG8_STAGE(PG8_SB(1, 0), cB + kstepB, voffB); PG8_STAGE(PG8_SA(1, 0), cA + kstepA, voffA); PG8_STAGE(PG8_SB(1, 1), cB + hstepB + kstepB, voffB);
.LBB0_495:
	v_lshrrev_b32_e32 v8, 1, v187
	v_or_b32_e32 v193, s33, v191
	v_and_b32_e32 v10, 24, v8
	v_lshlrev_b32_e32 v8, 6, v193
	v_lshlrev_b32_e32 v9, 1, v10
	s_movk_i32 s4, 0x3c0
	v_lshlrev_b32_e32 v11, 2, v193
	v_and_or_b32 v8, v8, s4, v9
	s_lshl_b32 s1, s1, 13
	v_and_b32_e32 v11, 32, v11
	s_lshl_b32 s0, s0, 5
	v_bitop3_b32 v11, v8, s1, v11 bitop3:0xde
	s_and_b32 s4, s0, 0x60
	v_lshl_or_b32 v8, v191, 6, v9
	v_lshlrev_b32_e32 v9, 2, v191
	s_lshl_b32 s0, s4, 7
	v_and_b32_e32 v9, 32, v9
	v_bitop3_b32 v201, v8, s0, v9 bitop3:0xde
	s_add_u32 s0, s66, 0x8000
	s_addc_u32 s1, s67, 0
	s_add_i32 m0, s45, 0x18000
	v_lshl_add_u64 v[8:9], s[0:1], 0, v[0:1]
	v_mov_b32_e32 v183, v1
	s_waitcnt vmcnt(4)
	s_barrier
	global_load_lds_dwordx4 v[8:9], off
	s_add_i32 m0, s45, 0x1a000
	v_lshl_add_u64 v[8:9], s[0:1], 0, v[182:183]
	s_add_u32 s0, s74, 0x8000
	v_mov_b32_e32 v179, v1
	s_addc_u32 s1, s75, 0
	s_add_i32 s86, s45, 0x8000
	v_mov_b32_e32 v181, v1
	global_load_lds_dwordx4 v[8:9], off
	v_lshl_add_u64 v[8:9], s[0:1], 0, v[178:179]
	s_mov_b32 m0, s86
	s_add_i32 s87, s45, 0xa000
	global_load_lds_dwordx4 v[8:9], off
	v_lshl_add_u64 v[8:9], s[0:1], 0, v[180:181]
	s_add_u32 s0, s66, 0xc000
	s_mov_b32 m0, s87
	s_addc_u32 s1, s67, 0
	s_add_i32 s88, s45, 0x1c000
	global_load_lds_dwordx4 v[8:9], off
	v_lshl_add_u64 v[8:9], s[0:1], 0, v[0:1]
	s_mov_b32 m0, s88
	s_add_i32 s89, s45, 0x1e000
	global_load_lds_dwordx4 v[8:9], off
	v_lshl_add_u64 v[8:9], s[0:1], 0, v[182:183]
	s_mov_b32 m0, s89
	s_add_i32 s0, s3, 1
	global_load_lds_dwordx4 v[8:9], off
	s_and_b32 s80, s0, 7
	s_lshl_b32 s0, s80, 6
	v_readlane_b32 s8, v254, 47
	s_add_u32 s5, s8, s0
	v_readlane_b32 s9, v254, 48
	s_addc_u32 s6, s9, 0
	s_lshl_b64 s[0:1], s[40:41], 2
	s_add_u32 s50, s5, s0
	s_addc_u32 s51, s6, s1
	s_add_i32 s5, s3, 2
	s_and_b32 s82, s5, 7
	s_lshl_b32 s5, s82, 6
	s_add_u32 s5, s8, s5
	s_addc_u32 s6, s9, 0
	s_add_u32 s54, s5, s0
	s_addc_u32 s55, s6, s1
	s_add_i32 s5, s3, 3
	s_and_b32 s17, s5, 7
	s_lshl_b32 s5, s17, 6
	s_add_u32 s5, s8, s5
	s_addc_u32 s6, s9, 0
	s_add_u32 s58, s5, s0
	s_addc_u32 s59, s6, s1
	s_xor_b32 s5, s2, 4
	s_lshl_b32 s6, s5, 6
	s_add_u32 s6, s8, s6
	s_addc_u32 s7, s9, 0
	s_add_u32 s90, s6, s0
	s_addc_u32 s91, s7, s1
	s_mul_i32 s23, s5, 0x288
	s_add_i32 s5, s3, 5
	s_and_b32 s5, s5, 7
	s_lshl_b32 s6, s5, 6
	s_add_u32 s6, s8, s6
	s_addc_u32 s7, s9, 0
	s_add_u32 s6, s6, s0
	s_addc_u32 s7, s7, s1
	v_writelane_b32 v255, s6, 0
	s_mulk_i32 s5, 0x288
	v_lshlrev_b32_e32 v8, 10, v5
	v_writelane_b32 v255, s7, 1
	v_writelane_b32 v255, s5, 2
	s_add_i32 s5, s3, 6
	s_and_b32 s5, s5, 7
	s_lshl_b32 s6, s5, 6
	s_add_u32 s6, s8, s6
	s_addc_u32 s7, s9, 0
	s_add_u32 s6, s6, s0
	s_addc_u32 s7, s7, s1
	v_writelane_b32 v255, s6, 4
	s_add_i32 s3, s3, -1
	s_mulk_i32 s5, 0x288
	v_writelane_b32 v255, s7, 5
	s_and_b32 s3, s3, 7
	v_writelane_b32 v255, s5, 6
	s_lshl_b32 s5, s3, 6
	s_add_u32 s5, s8, s5
	s_addc_u32 s6, s9, 0
	s_add_u32 s18, s5, s0
	s_addc_u32 s19, s6, s1
	v_writelane_b32 v255, s18, 8
	s_mulk_i32 s3, 0x288
	v_and_b32_e32 v8, 0xfffff800, v8
	v_writelane_b32 v255, s19, 9
	v_writelane_b32 v255, s3, 10
	s_mul_i32 s3, s2, 0x288
	s_lshl_b32 s2, s2, 6
	v_lshl_add_u32 v6, v6, 7, v8
	v_and_b32_e32 v5, 1, v5
	s_add_u32 s2, s8, s2
	v_lshl_or_b32 v5, v5, 6, v6
	v_writelane_b32 v254, s3, 49
	s_addc_u32 s3, s9, 0
	v_lshl_add_u32 v204, v7, 1, v5
	v_lshlrev_b32_e32 v5, 10, v2
	s_add_u32 s0, s2, s0
	v_and_b32_e32 v5, 0xfffff800, v5
	s_waitcnt vmcnt(6)
	s_addc_u32 s1, s3, s1
	v_lshl_add_u32 v3, v3, 7, v5
	v_and_b32_e32 v2, 1, v2
	v_writelane_b32 v255, s0, 12
	v_lshl_or_b32 v2, v2, 6, v3
	v_mov_b32_e32 v98, 0
	s_mulk_i32 s80, 0x288
	s_mulk_i32 s82, 0x288
	s_mulk_i32 s17, 0x288
	v_or_b32_e32 v203, s4, v10
	v_writelane_b32 v255, s1, 13
	v_mov_b32_e32 v205, v1
	v_lshl_add_u32 v206, v4, 1, v2
	v_mov_b32_e32 v207, v1
	s_mov_b32 s18, 0
	v_add_u32_e32 v212, 0, v11
	v_mov_b32_e32 v99, v98
	v_mov_b64_e32 v[100:101], 0
	v_mov_b64_e32 v[102:103], 0
	v_mov_b64_e32 v[104:105], 0
	v_mov_b64_e32 v[106:107], 0
	v_mov_b64_e32 v[108:109], 0
	v_mov_b64_e32 v[110:111], 0
	v_mov_b64_e32 v[112:113], 0
	v_mov_b64_e32 v[114:115], 0
	v_mov_b64_e32 v[116:117], 0
	v_mov_b64_e32 v[118:119], 0
	v_mov_b64_e32 v[120:121], 0
	v_mov_b64_e32 v[122:123], 0
	v_mov_b64_e32 v[124:125], 0
	v_mov_b64_e32 v[126:127], 0
	v_mov_b64_e32 v[128:129], 0
	v_mov_b64_e32 v[34:35], 0
	v_mov_b64_e32 v[36:37], 0
	v_mov_b64_e32 v[38:39], 0
	v_mov_b64_e32 v[40:41], 0
	v_mov_b64_e32 v[42:43], 0
	v_mov_b64_e32 v[44:45], 0
	v_mov_b64_e32 v[46:47], 0
	v_mov_b64_e32 v[48:49], 0
	v_mov_b64_e32 v[50:51], 0
	v_mov_b64_e32 v[52:53], 0
	v_mov_b64_e32 v[54:55], 0
	v_mov_b64_e32 v[56:57], 0
	v_mov_b64_e32 v[58:59], 0
	v_mov_b64_e32 v[60:61], 0
	v_mov_b64_e32 v[62:63], 0
	v_mov_b64_e32 v[64:65], 0
	v_mov_b64_e32 v[66:67], 0
	v_mov_b64_e32 v[68:69], 0
	v_mov_b64_e32 v[70:71], 0
	v_mov_b64_e32 v[72:73], 0
	v_mov_b64_e32 v[74:75], 0
	v_mov_b64_e32 v[76:77], 0
	v_mov_b64_e32 v[78:79], 0
	v_mov_b64_e32 v[80:81], 0
	v_mov_b64_e32 v[82:83], 0
	v_mov_b64_e32 v[84:85], 0
	v_mov_b64_e32 v[86:87], 0
	v_mov_b64_e32 v[88:89], 0
	v_mov_b64_e32 v[90:91], 0
	v_mov_b64_e32 v[92:93], 0
	v_mov_b64_e32 v[94:95], 0
	v_mov_b64_e32 v[96:97], 0
	v_mov_b64_e32 v[6:7], 0
	v_mov_b64_e32 v[8:9], 0
	v_mov_b64_e32 v[10:11], 0
	v_mov_b64_e32 v[12:13], 0
	v_mov_b64_e32 v[14:15], 0
	v_mov_b64_e32 v[16:17], 0
	v_mov_b64_e32 v[18:19], 0
	v_mov_b64_e32 v[20:21], 0
	v_mov_b64_e32 v[22:23], 0
	v_mov_b64_e32 v[24:25], 0
	v_mov_b64_e32 v[26:27], 0
	v_mov_b64_e32 v[28:29], 0
	v_mov_b64_e32 v[30:31], 0
	v_mov_b64_e32 v[32:33], 0
	v_mov_b64_e32 v[2:3], 0
	v_mov_b64_e32 v[4:5], 0
	s_mov_b64 s[76:77], s[74:75]
	s_barrier
	s_branch .LBB0_497
; template <class Epi, bool DYN = false>
; __device__ __forceinline__ void gemm_phase(LAS unsigned char* lds, const Gemm g, const Epi& E, int wave, unsigned* ctr = nullptr) {
;     ...
;         if (!has_next) break;
; #pragma unroll
;         for (int a = 0; a < 2; ++a)
; #pragma unroll
;             for (int b = 0; b < 2; ++b)
; #pragma unroll
;                 for (int m = 0; m < 4; ++m)
; #pragma unroll
;                     for (int n = 0; n < 2; ++n) acc[a][b][m][n] = (f32x4){0.f, 0.f, 0.f, 0.f};
;         cur = nxt; cA = nA; cB = nB; ++ui;
;         if (DYN) issue();
;         E.prefetch(pre, cur, wr, fr);
;     __device__ __forceinline__ void prefetch(float (&pre)[8], const Unit& u, int wr, int fr) const {
; #pragma unroll
;         for (int i = 0; i < 8; ++i) pre[i] = rs[u.pm * BM + wr * 64 + fr + (i >> 2) * HALF + (i & 3) * 16]; }
.LBB0_496:
	s_or_b64 exec, exec, s[0:1]
	v_lshl_add_u32 v2, s48, 8, v193
	v_readlane_b32 s0, v254, 41
	v_ashrrev_i32_e32 v3, 31, v2
	v_readlane_b32 s1, v254, 42
	v_mov_b32_e32 v5, 0
	s_add_i32 s18, s18, 1
	v_lshl_add_u64 v[2:3], v[2:3], 2, s[0:1]
	flat_load_dword v184, v[2:3]
	flat_load_dword v186, v[2:3] offset:64
	flat_load_dword v188, v[2:3] offset:128
	flat_load_dword v190, v[2:3] offset:192
	flat_load_dword v192, v[2:3] offset:512
	flat_load_dword v194, v[2:3] offset:576
	flat_load_dword v200, v[2:3] offset:640
	flat_load_dword v202, v[2:3] offset:704
	v_mov_b32_e32 v4, v5
	v_mov_b64_e32 v[2:3], 0
	v_mov_b64_e32 v[32:33], 0
	v_mov_b64_e32 v[30:31], 0
	v_mov_b64_e32 v[28:29], 0
	v_mov_b64_e32 v[26:27], 0
	v_mov_b64_e32 v[24:25], 0
	v_mov_b64_e32 v[22:23], 0
	v_mov_b64_e32 v[20:21], 0
	v_mov_b64_e32 v[18:19], 0
	v_mov_b64_e32 v[16:17], 0
	v_mov_b64_e32 v[14:15], 0
	v_mov_b64_e32 v[12:13], 0
	v_mov_b64_e32 v[10:11], 0
	v_mov_b64_e32 v[8:9], 0
	v_mov_b64_e32 v[6:7], 0
	v_mov_b64_e32 v[96:97], 0
	v_mov_b64_e32 v[94:95], 0
	v_mov_b64_e32 v[92:93], 0
	v_mov_b64_e32 v[90:91], 0
	v_mov_b64_e32 v[88:89], 0
	v_mov_b64_e32 v[86:87], 0
	v_mov_b64_e32 v[84:85], 0
	v_mov_b64_e32 v[82:83], 0
	v_mov_b64_e32 v[80:81], 0
	v_mov_b64_e32 v[78:79], 0
	v_mov_b64_e32 v[76:77], 0
	v_mov_b64_e32 v[74:75], 0
	v_mov_b64_e32 v[72:73], 0
	v_mov_b64_e32 v[70:71], 0
	v_mov_b64_e32 v[68:69], 0
	v_mov_b64_e32 v[66:67], 0
	v_mov_b64_e32 v[64:65], 0
	v_mov_b64_e32 v[62:63], 0
	v_mov_b64_e32 v[60:61], 0
	v_mov_b64_e32 v[58:59], 0
	v_mov_b64_e32 v[56:57], 0
	v_mov_b64_e32 v[54:55], 0
	v_mov_b64_e32 v[52:53], 0
	v_mov_b64_e32 v[50:51], 0
	v_mov_b64_e32 v[48:49], 0
	v_mov_b64_e32 v[46:47], 0
	v_mov_b64_e32 v[44:45], 0
	v_mov_b64_e32 v[42:43], 0
	v_mov_b64_e32 v[40:41], 0
	v_mov_b64_e32 v[38:39], 0
	v_mov_b64_e32 v[36:37], 0
	v_mov_b64_e32 v[34:35], 0
	v_mov_b64_e32 v[128:129], 0
	v_mov_b64_e32 v[126:127], 0
	v_mov_b64_e32 v[124:125], 0
	v_mov_b64_e32 v[122:123], 0
	v_mov_b64_e32 v[120:121], 0
	v_mov_b64_e32 v[118:119], 0
	v_mov_b64_e32 v[116:117], 0
	v_mov_b64_e32 v[114:115], 0
	v_mov_b64_e32 v[112:113], 0
	v_mov_b64_e32 v[110:111], 0
	v_mov_b64_e32 v[108:109], 0
	v_mov_b64_e32 v[106:107], 0
	v_mov_b64_e32 v[104:105], 0
	v_mov_b64_e32 v[102:103], 0
	v_mov_b64_e32 v[100:101], 0
	v_mov_b64_e32 v[98:99], 0
	s_mov_b32 s44, s72
	s_mov_b32 s22, s48
	s_andn2_b64 vcc, exec, s[68:69]
	s_mov_b64 s[74:75], s[76:77]
	s_cbranch_vccz .LBB0_744

; template <class Epi, bool DYN = false>
; __device__ __forceinline__ void gemm_phase(LAS unsigned char* lds, const Gemm g, const Epi& E, int wave, unsigned* ctr = nullptr) {
;     ...
;     auto rng_cnt = [&](int x) { const int q = S.nwg / NXCD, r = S.nwg % NXCD; return q + (x < r ? 1 : 0); };
;     auto rng_start = [&](int x) { const int q = S.nwg / NXCD, r = S.nwg % NXCD; return x < r ? x * (q + 1) : r * (q + 1) + (x - r) * q; };
;     auto decode = [&](int wgid, Unit& u) { const int nig = WGM * S.nN, gid = wgid / nig, fm = gid * WGM, gsz = (S.nM - fm) < WGM ? (S.nM - fm) : WGM; u.pm = fm + ((wgid % nig) % gsz); u.pn = (wgid % nig) / gsz; u.b = 0; };
;     auto issue = [&]() { if (tid == 0) ticket = (int)__hip_atomic_fetch_add(ctr + xcd * 16, 1u, __ATOMIC_RELAXED, __HIP_MEMORY_SCOPE_AGENT); };
;     auto publish = [&](int si) { if (tid == 0) { int wg = -1;
;             if (ticket < rng_cnt(xcd)) wg = rng_start(xcd) + ticket;
;             else { for (int k = 1; k < 8; ++k) { const int x2 = (xcd + k) & 7; const int t2 = (int)__hip_atomic_fetch_add(ctr + x2 * 16, 1u, __ATOMIC_RELAXED, __HIP_MEMORY_SCOPE_AGENT); if (t2 < rng_cnt(x2)) { wg = rng_start(x2) + t2; break; } } }
;             slot[si] = wg; } };
;     if (DYN) { issue(); publish(0); __syncthreads(); const int w0 = __builtin_amdgcn_readfirstlane(slot[0]); if (w0 < 0) return; decode(w0, cur); issue(); }
;     else if (!S.next(0, cur)) return;
;     f32x4 acc[2][2][4][2];
; #pragma unroll
;     for (int a = 0; a < 2; ++a)
; #pragma unroll
;         for (int b = 0; b < 2; ++b)
; #pragma unroll
;             for (int m = 0; m < 4; ++m)
; #pragma unroll
;                 for (int n = 0; n < 2; ++n) acc[a][b][m][n] = (f32x4){0.f, 0.f, 0.f, 0.f};
;     bf16x8 At[4][2], B0[2][2], B1[2][2];
;     const char* cA = (const char*)(g.A + (size_t)cur.b * g.sA) + (size_t)cur.pm * tstepA; const char* cB = (const char*)(g.Bt + (size_t)cur.b * g.sB) + (size_t)cur.pn * tstepB;
;     float pre[8];
;     E.prefetch(pre, cur, wr, fr);
;     PG8_STAGE(PG8_SB(0, 0), cB, voffB); PG8_STAGE(PG8_SA(0, 0), cA, voffA); PG8_STAGE(PG8_SB(0, 1), cB + hstepB, voffB); PG8_STAGE(PG8_SA(0, 1), cA + hstepA, voffA);
;     if (wr == 1) PG8_BAR;
;     PG8_WAIT_V(4); PG8_BAR;
;     PG8_STAGE(PG8_SB(1, 0), cB + kstepB, voffB); PG8_STAGE(PG8_SA(1, 0), cA + kstepA, voffA); PG8_STAGE(PG8_SB(1, 1), cB + hstepB + kstepB, voffB);
.LBB0_837:
	v_lshrrev_b32_e32 v9, 1, v192
	v_and_b32_e32 v10, 24, v9
	v_and_b32_e32 v8, 15, v192
	v_lshlrev_b32_e32 v9, 1, v10
	s_lshl_b32 s0, s0, 5
	v_lshl_or_b32 v194, s1, 6, v8
	v_lshl_or_b32 v8, v8, 6, v9
	v_lshlrev_b32_e32 v9, 2, v192
	s_and_b32 s10, s0, 0x60
	s_lshl_b32 s1, s1, 13
	v_and_b32_e32 v9, 32, v9
	s_lshl_b32 s0, s10, 7
	v_bitop3_b32 v200, v8, s0, v9 bitop3:0xde
	s_add_u32 s0, s26, 0x8000
	v_bitop3_b32 v11, v8, s1, v9 bitop3:0xde
	s_addc_u32 s1, s27, 0
	s_add_i32 m0, s33, 0x18000
	v_lshl_add_u64 v[8:9], s[0:1], 0, v[0:1]
	v_mov_b32_e32 v183, v1
	s_waitcnt vmcnt(4)
	s_barrier
	global_load_lds_dwordx4 v[8:9], off
	s_add_i32 m0, s33, 0x1a000
	v_lshl_add_u64 v[8:9], s[0:1], 0, v[182:183]
	s_add_u32 s0, s62, 0x8000
	v_mov_b32_e32 v179, v1
	s_addc_u32 s1, s63, 0
	s_add_i32 s88, s33, 0x8000
	v_mov_b32_e32 v181, v1
	global_load_lds_dwordx4 v[8:9], off
	v_lshl_add_u64 v[8:9], s[0:1], 0, v[178:179]
	s_mov_b32 m0, s88
	s_add_i32 s89, s33, 0xa000
	global_load_lds_dwordx4 v[8:9], off
	v_lshl_add_u64 v[8:9], s[0:1], 0, v[180:181]
	s_add_u32 s0, s26, 0xc000
	s_mov_b32 m0, s89
	s_addc_u32 s1, s27, 0
	s_add_i32 s90, s33, 0x1c000
	global_load_lds_dwordx4 v[8:9], off
	v_lshl_add_u64 v[8:9], s[0:1], 0, v[0:1]
	s_mov_b32 m0, s90
	s_add_i32 s95, s33, 0x1e000
	global_load_lds_dwordx4 v[8:9], off
	v_lshl_add_u64 v[8:9], s[0:1], 0, v[182:183]
	s_mov_b32 m0, s95
	s_add_i32 s0, s9, 1
	global_load_lds_dwordx4 v[8:9], off
	s_and_b32 s3, s0, 7
	s_lshl_b32 s0, s3, 6
	s_add_u32 s40, s4, s0
	s_addc_u32 s41, s7, 0
	s_add_i32 s0, s9, 2
	s_and_b32 s2, s0, 7
	s_lshl_b32 s0, s2, 6
	s_add_u32 s42, s4, s0
	s_addc_u32 s43, s7, 0
	s_add_i32 s0, s9, 3
	s_and_b32 s22, s0, 7
	s_lshl_b32 s0, s22, 6
	s_add_u32 s44, s4, s0
	s_addc_u32 s45, s7, 0
	s_xor_b32 s23, s8, 4
	s_lshl_b32 s0, s23, 6
	s_add_u32 s50, s4, s0
	s_addc_u32 s51, s7, 0
	s_add_i32 s0, s9, 5
	s_and_b32 s60, s0, 7
	s_lshl_b32 s0, s60, 6
	s_add_u32 s54, s4, s0
	s_addc_u32 s55, s7, 0
	s_add_i32 s0, s9, 6
	s_and_b32 s0, s0, 7
	s_lshl_b32 s1, s0, 6
	s_add_u32 s58, s4, s1
	s_addc_u32 s59, s7, 0
	s_mulk_i32 s0, 0x60
	s_add_i32 s9, s9, -1
	v_writelane_b32 v254, s0, 52
	s_and_b32 s0, s9, 7
	v_lshlrev_b32_e32 v8, 10, v5
	s_lshl_b32 s1, s0, 6
	v_and_b32_e32 v8, 0xfffff800, v8
	s_add_u32 s18, s4, s1
	v_lshl_add_u32 v6, v6, 7, v8
	v_and_b32_e32 v5, 1, v5
	s_addc_u32 s19, s7, 0
	v_lshl_or_b32 v5, v5, 6, v6
	v_writelane_b32 v254, s18, 54
	v_lshl_add_u32 v184, v7, 1, v5
	v_lshlrev_b32_e32 v5, 10, v2
	v_writelane_b32 v254, s19, 55
	s_mulk_i32 s0, 0x60
	v_and_b32_e32 v5, 0xfffff800, v5
	s_waitcnt vmcnt(6)
	v_writelane_b32 v254, s0, 56
	s_lshl_b32 s0, s8, 6
	v_lshl_add_u32 v3, v3, 7, v5
	v_and_b32_e32 v2, 1, v2
	s_add_u32 s64, s4, s0
	v_lshl_or_b32 v2, v2, 6, v3
	v_mov_b32_e32 v30, 0
	s_mulk_i32 s3, 0x60
	s_mulk_i32 s2, 0x60
	s_mulk_i32 s22, 0x60
	s_mulk_i32 s23, 0x60
	s_mulk_i32 s60, 0x60
	s_mul_i32 s61, s8, 0x60
	s_addc_u32 s65, s7, 0
	v_or_b32_e32 v201, s10, v10
	v_mov_b32_e32 v185, v1
	v_lshl_add_u32 v186, v4, 1, v2
	v_mov_b32_e32 v187, v1
	s_mov_b32 s4, 0
	v_add_u32_e32 v202, 0, v11
	v_mov_b32_e32 v31, v30
	v_mov_b64_e32 v[32:33], 0
	v_mov_b64_e32 v[46:47], 0
	v_mov_b64_e32 v[48:49], 0
	v_mov_b64_e32 v[54:55], 0
	v_mov_b64_e32 v[56:57], 0
	v_mov_b64_e32 v[62:63], 0
	v_mov_b64_e32 v[64:65], 0
	v_mov_b64_e32 v[70:71], 0
	v_mov_b64_e32 v[72:73], 0
	v_mov_b64_e32 v[78:79], 0
	v_mov_b64_e32 v[80:81], 0
	v_mov_b64_e32 v[86:87], 0
	v_mov_b64_e32 v[88:89], 0
	v_mov_b64_e32 v[98:99], 0
	v_mov_b64_e32 v[100:101], 0
	v_mov_b64_e32 v[2:3], 0
	v_mov_b64_e32 v[4:5], 0
	v_mov_b64_e32 v[6:7], 0
	v_mov_b64_e32 v[8:9], 0
	v_mov_b64_e32 v[10:11], 0
	v_mov_b64_e32 v[12:13], 0
	v_mov_b64_e32 v[14:15], 0
	v_mov_b64_e32 v[16:17], 0
	v_mov_b64_e32 v[18:19], 0
	v_mov_b64_e32 v[20:21], 0
	v_mov_b64_e32 v[22:23], 0
	v_mov_b64_e32 v[24:25], 0
	v_mov_b64_e32 v[26:27], 0
	v_mov_b64_e32 v[28:29], 0
	v_mov_b64_e32 v[34:35], 0
	v_mov_b64_e32 v[36:37], 0
	v_mov_b64_e32 v[38:39], 0
	v_mov_b64_e32 v[40:41], 0
	v_mov_b64_e32 v[42:43], 0
	v_mov_b64_e32 v[44:45], 0
	v_mov_b64_e32 v[50:51], 0
	v_mov_b64_e32 v[52:53], 0
	v_mov_b64_e32 v[58:59], 0
	v_mov_b64_e32 v[60:61], 0
	v_mov_b64_e32 v[66:67], 0
	v_mov_b64_e32 v[68:69], 0
	v_mov_b64_e32 v[74:75], 0
	v_mov_b64_e32 v[76:77], 0
	v_mov_b64_e32 v[82:83], 0
	v_mov_b64_e32 v[84:85], 0
	v_mov_b64_e32 v[90:91], 0
	v_mov_b64_e32 v[92:93], 0
	v_mov_b64_e32 v[94:95], 0
	v_mov_b64_e32 v[96:97], 0
	v_mov_b64_e32 v[102:103], 0
	v_mov_b64_e32 v[104:105], 0
	v_mov_b64_e32 v[106:107], 0
	v_mov_b64_e32 v[108:109], 0
	v_mov_b64_e32 v[110:111], 0
	v_mov_b64_e32 v[112:113], 0
	v_mov_b64_e32 v[114:115], 0
	v_mov_b64_e32 v[116:117], 0
	v_mov_b64_e32 v[118:119], 0
	v_mov_b64_e32 v[120:121], 0
	v_mov_b64_e32 v[122:123], 0
	v_mov_b64_e32 v[124:125], 0
	v_mov_b64_e32 v[126:127], 0
	v_mov_b64_e32 v[128:129], 0
	s_barrier
	s_branch .LBB0_839
.LBB0_838:
	s_or_b64 exec, exec, s[0:1]
	v_mov_b32_e32 v30, 0
	s_add_i32 s4, s4, 1
	s_mov_b32 s6, s19
	s_mov_b32 s5, s18
	v_mov_b32_e32 v31, v30
	v_mov_b64_e32 v[32:33], 0
	v_mov_b64_e32 v[46:47], 0
	v_mov_b64_e32 v[48:49], 0
	v_mov_b64_e32 v[54:55], 0
	v_mov_b64_e32 v[56:57], 0
	v_mov_b64_e32 v[62:63], 0
	v_mov_b64_e32 v[64:65], 0
	v_mov_b64_e32 v[70:71], 0
	v_mov_b64_e32 v[72:73], 0
	v_mov_b64_e32 v[78:79], 0
	v_mov_b64_e32 v[80:81], 0
	v_mov_b64_e32 v[86:87], 0
	v_mov_b64_e32 v[88:89], 0
	v_mov_b64_e32 v[98:99], 0
	v_mov_b64_e32 v[100:101], 0
	v_mov_b64_e32 v[2:3], 0
	v_mov_b64_e32 v[4:5], 0
	v_mov_b64_e32 v[6:7], 0
	v_mov_b64_e32 v[8:9], 0
	v_mov_b64_e32 v[10:11], 0
	v_mov_b64_e32 v[12:13], 0
	v_mov_b64_e32 v[14:15], 0
	v_mov_b64_e32 v[16:17], 0
	v_mov_b64_e32 v[18:19], 0
	v_mov_b64_e32 v[20:21], 0
	v_mov_b64_e32 v[22:23], 0
	v_mov_b64_e32 v[24:25], 0
	v_mov_b64_e32 v[26:27], 0
	v_mov_b64_e32 v[28:29], 0
	v_mov_b64_e32 v[34:35], 0
	v_mov_b64_e32 v[36:37], 0
	v_mov_b64_e32 v[38:39], 0
	v_mov_b64_e32 v[40:41], 0
	v_mov_b64_e32 v[42:43], 0
	v_mov_b64_e32 v[44:45], 0
	v_mov_b64_e32 v[50:51], 0
	v_mov_b64_e32 v[52:53], 0
	v_mov_b64_e32 v[58:59], 0
	v_mov_b64_e32 v[60:61], 0
	v_mov_b64_e32 v[66:67], 0
	v_mov_b64_e32 v[68:69], 0
	v_mov_b64_e32 v[74:75], 0
	v_mov_b64_e32 v[76:77], 0
	v_mov_b64_e32 v[82:83], 0
	v_mov_b64_e32 v[84:85], 0
	v_mov_b64_e32 v[90:91], 0
	v_mov_b64_e32 v[92:93], 0
	v_mov_b64_e32 v[94:95], 0
	v_mov_b64_e32 v[96:97], 0
	v_mov_b64_e32 v[102:103], 0
	v_mov_b64_e32 v[104:105], 0
	v_mov_b64_e32 v[106:107], 0
	v_mov_b64_e32 v[108:109], 0
	v_mov_b64_e32 v[110:111], 0
	v_mov_b64_e32 v[112:113], 0
	v_mov_b64_e32 v[114:115], 0
	v_mov_b64_e32 v[116:117], 0
	v_mov_b64_e32 v[118:119], 0
	v_mov_b64_e32 v[120:121], 0
	v_mov_b64_e32 v[122:123], 0
	v_mov_b64_e32 v[124:125], 0
	v_mov_b64_e32 v[126:127], 0
	v_mov_b64_e32 v[128:129], 0
	s_mov_b64 s[62:63], s[46:47]
	s_andn2_b64 vcc, exec, s[38:39]
	s_cbranch_vccz .LBB0_865

; template <class Epi, bool DYN = false>
; __device__ __forceinline__ void gemm_phase(LAS unsigned char* lds, const Gemm g, const Epi& E, int wave, unsigned* ctr = nullptr) {
;     ...
;     auto rng_cnt = [&](int x) { const int q = S.nwg / NXCD, r = S.nwg % NXCD; return q + (x < r ? 1 : 0); };
;     auto rng_start = [&](int x) { const int q = S.nwg / NXCD, r = S.nwg % NXCD; return x < r ? x * (q + 1) : r * (q + 1) + (x - r) * q; };
;     auto decode = [&](int wgid, Unit& u) { const int nig = WGM * S.nN, gid = wgid / nig, fm = gid * WGM, gsz = (S.nM - fm) < WGM ? (S.nM - fm) : WGM; u.pm = fm + ((wgid % nig) % gsz); u.pn = (wgid % nig) / gsz; u.b = 0; };
;     auto issue = [&]() { if (tid == 0) ticket = (int)__hip_atomic_fetch_add(ctr + xcd * 16, 1u, __ATOMIC_RELAXED, __HIP_MEMORY_SCOPE_AGENT); };
;     auto publish = [&](int si) { if (tid == 0) { int wg = -1;
;             if (ticket < rng_cnt(xcd)) wg = rng_start(xcd) + ticket;
;             else { for (int k = 1; k < 8; ++k) { const int x2 = (xcd + k) & 7; const int t2 = (int)__hip_atomic_fetch_add(ctr + x2 * 16, 1u, __ATOMIC_RELAXED, __HIP_MEMORY_SCOPE_AGENT); if (t2 < rng_cnt(x2)) { wg = rng_start(x2) + t2; break; } } }
;             slot[si] = wg; } };
;     if (DYN) { issue(); publish(0); __syncthreads(); const int w0 = __builtin_amdgcn_readfirstlane(slot[0]); if (w0 < 0) return; decode(w0, cur); issue(); }
;     else if (!S.next(0, cur)) return;
;     f32x4 acc[2][2][4][2];
; #pragma unroll
;     for (int a = 0; a < 2; ++a)
; #pragma unroll
;         for (int b = 0; b < 2; ++b)
; #pragma unroll
;             for (int m = 0; m < 4; ++m)
; #pragma unroll
;                 for (int n = 0; n < 2; ++n) acc[a][b][m][n] = (f32x4){0.f, 0.f, 0.f, 0.f};
;     bf16x8 At[4][2], B0[2][2], B1[2][2];
;     const char* cA = (const char*)(g.A + (size_t)cur.b * g.sA) + (size_t)cur.pm * tstepA; const char* cB = (const char*)(g.Bt + (size_t)cur.b * g.sB) + (size_t)cur.pn * tstepB;
;     float pre[8];
;     E.prefetch(pre, cur, wr, fr);
;     PG8_STAGE(PG8_SB(0, 0), cB, voffB); PG8_STAGE(PG8_SA(0, 0), cA, voffA); PG8_STAGE(PG8_SB(0, 1), cB + hstepB, voffB); PG8_STAGE(PG8_SA(0, 1), cA + hstepA, voffA);
;     if (wr == 1) PG8_BAR;
;     PG8_WAIT_V(4); PG8_BAR;
;     PG8_STAGE(PG8_SB(1, 0), cB + kstepB, voffB); PG8_STAGE(PG8_SA(1, 0), cA + kstepA, voffA); PG8_STAGE(PG8_SB(1, 1), cB + hstepB + kstepB, voffB);
.LBB0_909:
	v_lshrrev_b32_e32 v7, 1, v202
	v_or_b32_e32 v213, s18, v204
	v_and_b32_e32 v7, 24, v7
	v_lshlrev_b32_e32 v8, 6, v213
	v_lshlrev_b32_e32 v9, 1, v7
	v_lshlrev_b32_e32 v10, 2, v213
	v_and_or_b32 v8, v8, s2, v9
	s_lshl_b32 s1, s1, 13
	v_and_b32_e32 v10, 32, v10
	s_lshl_b32 s8, s0, 5
	v_bitop3_b32 v10, v8, s1, v10 bitop3:0xde
	s_and_b32 s60, s8, 0x60
	v_lshl_or_b32 v8, v204, 6, v9
	v_lshlrev_b32_e32 v9, 2, v204
	s_lshl_b32 s0, s60, 7
	v_and_b32_e32 v9, 32, v9
	v_bitop3_b32 v214, v8, s0, v9 bitop3:0xde
	s_add_u32 s0, s64, 0x8000
	v_mov_b32_e32 v181, v1
	s_addc_u32 s1, s65, 0
	s_add_i32 m0, s19, 0x18000
	v_lshl_add_u64 v[8:9], s[0:1], 0, v[180:181]
	v_mov_b32_e32 v185, v1
	s_waitcnt vmcnt(4)
	s_barrier
	global_load_lds_dwordx4 v[8:9], off
	s_add_i32 m0, s19, 0x1a000
	v_lshl_add_u64 v[8:9], s[0:1], 0, v[184:185]
	s_add_u32 s0, s68, 0x8000
	v_mov_b32_e32 v179, v1
	s_addc_u32 s1, s69, 0
	s_add_i32 s61, s19, 0x8000
	v_mov_b32_e32 v183, v1
	global_load_lds_dwordx4 v[8:9], off
	v_lshl_add_u64 v[8:9], s[0:1], 0, v[178:179]
	s_mov_b32 m0, s61
	s_add_i32 s58, s19, 0xa000
	global_load_lds_dwordx4 v[8:9], off
	v_lshl_add_u64 v[8:9], s[0:1], 0, v[182:183]
	s_add_u32 s0, s64, 0xc000
	s_mov_b32 m0, s58
	s_addc_u32 s1, s65, 0
	s_add_i32 s59, s19, 0x1c000
	global_load_lds_dwordx4 v[8:9], off
	v_lshl_add_u64 v[8:9], s[0:1], 0, v[180:181]
	s_mov_b32 m0, s59
	s_add_i32 s62, s19, 0x1e000
	global_load_lds_dwordx4 v[8:9], off
	v_lshl_add_u64 v[8:9], s[0:1], 0, v[184:185]
	s_mov_b32 m0, s62
	s_add_i32 s0, s7, 1
	global_load_lds_dwordx4 v[8:9], off
	s_and_b32 s63, s0, 7
	s_lshl_b32 s0, s63, 6
	s_add_u32 s40, s4, s0
	s_addc_u32 s41, s5, 0
	s_add_i32 s0, s7, 2
	s_and_b32 s2, s0, 7
	s_lshl_b32 s0, s2, 6
	s_add_u32 s42, s4, s0
	s_addc_u32 s43, s5, 0
	s_add_i32 s0, s7, 3
	s_and_b32 s3, s0, 7
	s_lshl_b32 s0, s3, 6
	s_add_u32 s44, s4, s0
	s_addc_u32 s45, s5, 0
	s_xor_b32 s95, s6, 4
	s_lshl_b32 s0, s95, 6
	s_add_u32 s50, s4, s0
	s_addc_u32 s51, s5, 0
	s_add_i32 s0, s7, 5
	s_and_b32 s28, s0, 7
	s_lshl_b32 s0, s28, 6
	s_add_u32 s54, s4, s0
	s_addc_u32 s55, s5, 0
	s_add_i32 s0, s7, 6
	s_and_b32 s0, s0, 7
	s_lshl_b32 s1, s0, 6
	s_add_u32 s38, s4, s1
	s_addc_u32 s39, s5, 0
	v_writelane_b32 v254, s38, 54
	s_mulk_i32 s0, 0x210
	s_add_i32 s7, s7, -1
	v_writelane_b32 v254, s39, 55
	v_writelane_b32 v254, s0, 39
	s_and_b32 s0, s7, 7
	v_and_or_b32 v8, s8, 32, v7
	v_lshlrev_b32_e32 v7, 10, v4
	s_lshl_b32 s1, s0, 6
	v_and_b32_e32 v7, 0xfffff800, v7
	s_add_u32 s38, s4, s1
	v_lshl_add_u32 v5, v5, 7, v7
	v_and_b32_e32 v4, 1, v4
	s_addc_u32 s39, s5, 0
	v_lshl_or_b32 v4, v4, 6, v5
	v_writelane_b32 v254, s38, 56
	v_lshl_add_u32 v186, v6, 1, v4
	v_lshlrev_b32_e32 v4, 10, v0
	v_writelane_b32 v254, s39, 57
	s_mulk_i32 s0, 0x210
	v_and_b32_e32 v4, 0xfffff800, v4
	s_waitcnt vmcnt(6)
	v_writelane_b32 v254, s0, 43
	s_lshl_b32 s0, s6, 6
	v_lshl_add_u32 v2, v2, 7, v4
	v_and_b32_e32 v0, 1, v0
	s_add_u32 s92, s4, s0
	v_lshl_or_b32 v0, v0, 6, v2
	v_mov_b32_e32 v98, 0
	s_mulk_i32 s63, 0x210
	s_mulk_i32 s2, 0x210
	s_mulk_i32 s3, 0x210
	s_mulk_i32 s95, 0x210
	s_mulk_i32 s28, 0x210
	s_mul_i32 s90, s6, 0x210
	s_addc_u32 s93, s5, 0
	v_mov_b32_e32 v187, v1
	v_lshl_add_u32 v188, v3, 1, v0
	v_mov_b32_e32 v189, v1
	s_mov_b32 s33, 0
	v_add_u32_e32 v215, 0, v10
	v_lshlrev_b32_e32 v190, 1, v8
	v_mov_b32_e32 v99, v98
	v_mov_b64_e32 v[100:101], 0
	v_mov_b64_e32 v[102:103], 0
	v_mov_b64_e32 v[104:105], 0
	v_mov_b64_e32 v[106:107], 0
	v_mov_b64_e32 v[108:109], 0
	v_mov_b64_e32 v[110:111], 0
	v_mov_b64_e32 v[112:113], 0
	v_mov_b64_e32 v[114:115], 0
	v_mov_b64_e32 v[116:117], 0
	v_mov_b64_e32 v[118:119], 0
	v_mov_b64_e32 v[120:121], 0
	v_mov_b64_e32 v[122:123], 0
	v_mov_b64_e32 v[124:125], 0
	v_mov_b64_e32 v[126:127], 0
	v_mov_b64_e32 v[128:129], 0
	v_mov_b64_e32 v[34:35], 0
	v_mov_b64_e32 v[36:37], 0
	v_mov_b64_e32 v[38:39], 0
	v_mov_b64_e32 v[40:41], 0
	v_mov_b64_e32 v[42:43], 0
	v_mov_b64_e32 v[44:45], 0
	v_mov_b64_e32 v[46:47], 0
	v_mov_b64_e32 v[48:49], 0
	v_mov_b64_e32 v[50:51], 0
	v_mov_b64_e32 v[52:53], 0
	v_mov_b64_e32 v[54:55], 0
	v_mov_b64_e32 v[56:57], 0
	v_mov_b64_e32 v[58:59], 0
	v_mov_b64_e32 v[60:61], 0
	v_mov_b64_e32 v[62:63], 0
	v_mov_b64_e32 v[64:65], 0
	v_mov_b64_e32 v[66:67], 0
	v_mov_b64_e32 v[68:69], 0
	v_mov_b64_e32 v[70:71], 0
	v_mov_b64_e32 v[72:73], 0
	v_mov_b64_e32 v[74:75], 0
	v_mov_b64_e32 v[76:77], 0
	v_mov_b64_e32 v[78:79], 0
	v_mov_b64_e32 v[80:81], 0
	v_mov_b64_e32 v[82:83], 0
	v_mov_b64_e32 v[84:85], 0
	v_mov_b64_e32 v[86:87], 0
	v_mov_b64_e32 v[88:89], 0
	v_mov_b64_e32 v[90:91], 0
	v_mov_b64_e32 v[92:93], 0
	v_mov_b64_e32 v[94:95], 0
	v_mov_b64_e32 v[96:97], 0
	v_mov_b64_e32 v[6:7], 0
	v_mov_b64_e32 v[8:9], 0
	v_mov_b64_e32 v[10:11], 0
	v_mov_b64_e32 v[12:13], 0
	v_mov_b64_e32 v[14:15], 0
	v_mov_b64_e32 v[16:17], 0
	v_mov_b64_e32 v[18:19], 0
	v_mov_b64_e32 v[20:21], 0
	v_mov_b64_e32 v[22:23], 0
	v_mov_b64_e32 v[24:25], 0
	v_mov_b64_e32 v[26:27], 0
	v_mov_b64_e32 v[28:29], 0
	v_mov_b64_e32 v[30:31], 0
	v_mov_b64_e32 v[32:33], 0
	v_mov_b64_e32 v[2:3], 0
	v_mov_b64_e32 v[4:5], 0
	s_mov_b64 s[70:71], s[68:69]
	s_barrier
	s_branch .LBB0_911
; template <class Epi, bool DYN = false>
; __device__ __forceinline__ void gemm_phase(LAS unsigned char* lds, const Gemm g, const Epi& E, int wave, unsigned* ctr = nullptr) {
;     ...
;         if (!has_next) break;
; #pragma unroll
;         for (int a = 0; a < 2; ++a)
; #pragma unroll
;             for (int b = 0; b < 2; ++b)
; #pragma unroll
;                 for (int m = 0; m < 4; ++m)
; #pragma unroll
;                     for (int n = 0; n < 2; ++n) acc[a][b][m][n] = (f32x4){0.f, 0.f, 0.f, 0.f};
;         cur = nxt; cA = nA; cB = nB; ++ui;
;         if (DYN) issue();
;         E.prefetch(pre, cur, wr, fr);
;     __device__ __forceinline__ void prefetch(float (&pre)[8], const Unit& u, int wr, int fr) const {
; #pragma unroll
;         for (int i = 0; i < 8; ++i) pre[i] = rs[u.pm * BM + wr * 64 + fr + (i >> 2) * HALF + (i & 3) * 16]; }
.LBB0_910:
	s_or_b64 exec, exec, s[0:1]
	v_lshl_add_u32 v2, s48, 8, v213
	v_readlane_b32 s0, v254, 41
	v_ashrrev_i32_e32 v3, 31, v2
	v_readlane_b32 s1, v254, 42
	v_mov_b32_e32 v5, 0
	s_add_i32 s33, s33, 1
	v_lshl_add_u64 v[2:3], v[2:3], 2, s[0:1]
	flat_load_dword v205, v[2:3]
	flat_load_dword v206, v[2:3] offset:64
	flat_load_dword v207, v[2:3] offset:128
	flat_load_dword v208, v[2:3] offset:192
	flat_load_dword v209, v[2:3] offset:512
	flat_load_dword v210, v[2:3] offset:576
	flat_load_dword v211, v[2:3] offset:640
	flat_load_dword v212, v[2:3] offset:704
	v_mov_b32_e32 v4, v5
	v_mov_b64_e32 v[2:3], 0
	v_mov_b64_e32 v[32:33], 0
	v_mov_b64_e32 v[30:31], 0
	v_mov_b64_e32 v[28:29], 0
	v_mov_b64_e32 v[26:27], 0
	v_mov_b64_e32 v[24:25], 0
	v_mov_b64_e32 v[22:23], 0
	v_mov_b64_e32 v[20:21], 0
	v_mov_b64_e32 v[18:19], 0
	v_mov_b64_e32 v[16:17], 0
	v_mov_b64_e32 v[14:15], 0
	v_mov_b64_e32 v[12:13], 0
	v_mov_b64_e32 v[10:11], 0
	v_mov_b64_e32 v[8:9], 0
	v_mov_b64_e32 v[6:7], 0
	v_mov_b64_e32 v[96:97], 0
	v_mov_b64_e32 v[94:95], 0
	v_mov_b64_e32 v[92:93], 0
	v_mov_b64_e32 v[90:91], 0
	v_mov_b64_e32 v[88:89], 0
	v_mov_b64_e32 v[86:87], 0
	v_mov_b64_e32 v[84:85], 0
	v_mov_b64_e32 v[82:83], 0
	v_mov_b64_e32 v[80:81], 0
	v_mov_b64_e32 v[78:79], 0
	v_mov_b64_e32 v[76:77], 0
	v_mov_b64_e32 v[74:75], 0
	v_mov_b64_e32 v[72:73], 0
	v_mov_b64_e32 v[70:71], 0
	v_mov_b64_e32 v[68:69], 0
	v_mov_b64_e32 v[66:67], 0
	v_mov_b64_e32 v[64:65], 0
	v_mov_b64_e32 v[62:63], 0
	v_mov_b64_e32 v[60:61], 0
	v_mov_b64_e32 v[58:59], 0
	v_mov_b64_e32 v[56:57], 0
	v_mov_b64_e32 v[54:55], 0
	v_mov_b64_e32 v[52:53], 0
	v_mov_b64_e32 v[50:51], 0
	v_mov_b64_e32 v[48:49], 0
	v_mov_b64_e32 v[46:47], 0
	v_mov_b64_e32 v[44:45], 0
	v_mov_b64_e32 v[42:43], 0
	v_mov_b64_e32 v[40:41], 0
	v_mov_b64_e32 v[38:39], 0
	v_mov_b64_e32 v[36:37], 0
	v_mov_b64_e32 v[34:35], 0
	v_mov_b64_e32 v[128:129], 0
	v_mov_b64_e32 v[126:127], 0
	v_mov_b64_e32 v[124:125], 0
	v_mov_b64_e32 v[122:123], 0
	v_mov_b64_e32 v[120:121], 0
	v_mov_b64_e32 v[118:119], 0
	v_mov_b64_e32 v[116:117], 0
	v_mov_b64_e32 v[114:115], 0
	v_mov_b64_e32 v[112:113], 0
	v_mov_b64_e32 v[110:111], 0
	v_mov_b64_e32 v[108:109], 0
	v_mov_b64_e32 v[106:107], 0
	v_mov_b64_e32 v[104:105], 0
	v_mov_b64_e32 v[102:103], 0
	v_mov_b64_e32 v[100:101], 0
	v_mov_b64_e32 v[98:99], 0
	s_mov_b32 s22, s66
	s_mov_b32 s26, s48
	s_andn2_b64 vcc, exec, s[38:39]
	s_mov_b64 s[68:69], s[70:71]
	s_cbranch_vccz .LBB0_937
